# 8-phase GEMM loops: removed the full vmcnt(0) drains before fragment reads (counted vmcnt(6)/(4)/(2) of the template now effective); out-proj residual epilogue with 8 row loads in flight
# speedup vs baseline: 1.0579x; 1.0579x over previous
.LBB0_288:
	v_or_b32_e32 v160, 0x10000, v156
	v_or_b32_e32 v162, 0x10000, v158
	v_or_b32_e32 v161, 0x10000, v157
	ds_read_b128 v[170:173], v160
	ds_read_b128 v[174:177], v161
	v_or_b32_e32 v163, 0x10000, v159
	ds_read_b128 v[178:181], v162
	ds_read_b128 v[182:185], v163
	s_add_u32 s34, s19, s16
	s_addc_u32 s35, s30, s17
	s_add_u32 s34, s34, 0x80
	v_add_u32_e32 v164, 0xc000, v137
	s_addc_u32 s35, s35, 0
	v_readfirstlane_b32 s36, v164
	ds_read_b128 v[186:189], v139
	ds_read_b128 v[190:193], v139 offset:1024
	ds_read_b128 v[194:197], v142
	ds_read_b128 v[198:201], v142 offset:1024
	ds_read_b128 v[202:205], v141
	ds_read_b128 v[206:209], v141 offset:1024
	ds_read_b128 v[224:227], v140
	ds_read_b128 v[228:231], v140 offset:1024
	s_mov_b32 m0, s36
	v_lshl_add_u64 v[166:167], s[34:35], 0, v[132:133]
	v_add_u32_e32 v165, 0xe000, v137
	global_load_lds_dwordx4 v[166:167], off
	v_lshl_add_u64 v[166:167], s[34:35], 0, v[130:131]
	v_readfirstlane_b32 s34, v165
	s_mov_b32 m0, s34
	s_nop 0
	global_load_lds_dwordx4 v[166:167], off
	s_waitcnt lgkmcnt(8)
	s_barrier
	s_waitcnt lgkmcnt(0)
	s_setprio 1
	s_waitcnt lgkmcnt(0)
	v_mfma_f32_16x16x32_bf16 v[126:129], v[186:189], v[170:173], v[126:129]
	v_mfma_f32_16x16x32_bf16 v[122:125], v[186:189], v[178:181], v[122:125]
	v_mfma_f32_16x16x32_bf16 v[118:121], v[194:197], v[170:173], v[118:121]
	v_mfma_f32_16x16x32_bf16 v[114:117], v[194:197], v[178:181], v[114:117]
	v_mfma_f32_16x16x32_bf16 v[110:113], v[202:205], v[170:173], v[110:113]
	v_mfma_f32_16x16x32_bf16 v[106:109], v[202:205], v[178:181], v[106:109]
	v_mfma_f32_16x16x32_bf16 v[102:105], v[224:227], v[170:173], v[102:105]
	v_mfma_f32_16x16x32_bf16 v[98:101], v[224:227], v[178:181], v[98:101]
	v_mfma_f32_16x16x32_bf16 v[126:129], v[190:193], v[174:177], v[126:129]
	v_mfma_f32_16x16x32_bf16 v[122:125], v[190:193], v[182:185], v[122:125]
	v_mfma_f32_16x16x32_bf16 v[118:121], v[198:201], v[174:177], v[118:121]
	v_mfma_f32_16x16x32_bf16 v[114:117], v[198:201], v[182:185], v[114:117]
	v_mfma_f32_16x16x32_bf16 v[110:113], v[206:209], v[174:177], v[110:113]
	v_mfma_f32_16x16x32_bf16 v[106:109], v[206:209], v[182:185], v[106:109]
	v_mfma_f32_16x16x32_bf16 v[102:105], v[228:231], v[174:177], v[102:105]
	v_mfma_f32_16x16x32_bf16 v[98:101], v[228:231], v[182:185], v[98:101]
	s_setprio 0
	s_barrier
	s_add_u32 s36, s0, s16
	s_addc_u32 s37, s1, s17
	s_add_u32 s34, s36, 0x100
	v_or_b32_e32 v166, 0x14000, v156
	v_or_b32_e32 v168, 0x14000, v158
	s_addc_u32 s35, s37, 0
	v_readfirstlane_b32 s38, v143
	v_or_b32_e32 v167, 0x14000, v157
	ds_read_b128 v[232:235], v166
	ds_read_b128 v[236:239], v167
	v_or_b32_e32 v169, 0x14000, v159
	ds_read_b128 v[240:243], v168
	ds_read_b128 v[244:247], v169
	s_mov_b32 m0, s38
	v_lshl_add_u64 v[212:213], s[34:35], 0, v[132:133]
	global_load_lds_dwordx4 v[212:213], off
	v_lshl_add_u64 v[212:213], s[34:35], 0, v[130:131]
	v_readfirstlane_b32 s34, v144
	s_mov_b32 m0, s34
	s_nop 0
	global_load_lds_dwordx4 v[212:213], off
	s_barrier
	s_waitcnt lgkmcnt(0)
	s_setprio 1
	s_waitcnt lgkmcnt(0)
	v_mfma_f32_16x16x32_bf16 v[94:97], v[186:189], v[232:235], v[94:97]
	v_mfma_f32_16x16x32_bf16 v[90:93], v[186:189], v[240:243], v[90:93]
	v_mfma_f32_16x16x32_bf16 v[86:89], v[194:197], v[232:235], v[86:89]
	v_mfma_f32_16x16x32_bf16 v[82:85], v[194:197], v[240:243], v[82:85]
	v_mfma_f32_16x16x32_bf16 v[78:81], v[202:205], v[232:235], v[78:81]
	v_mfma_f32_16x16x32_bf16 v[74:77], v[202:205], v[240:243], v[74:77]
	v_mfma_f32_16x16x32_bf16 v[70:73], v[224:227], v[232:235], v[70:73]
	v_mfma_f32_16x16x32_bf16 v[66:69], v[224:227], v[240:243], v[66:69]
	v_mfma_f32_16x16x32_bf16 v[94:97], v[190:193], v[236:239], v[94:97]
	v_mfma_f32_16x16x32_bf16 v[90:93], v[190:193], v[244:247], v[90:93]
	v_mfma_f32_16x16x32_bf16 v[86:89], v[198:201], v[236:239], v[86:89]
	v_mfma_f32_16x16x32_bf16 v[82:85], v[198:201], v[244:247], v[82:85]
	v_mfma_f32_16x16x32_bf16 v[78:81], v[206:209], v[236:239], v[78:81]
	v_mfma_f32_16x16x32_bf16 v[74:77], v[206:209], v[244:247], v[74:77]
	v_mfma_f32_16x16x32_bf16 v[70:73], v[228:231], v[236:239], v[70:73]
	v_mfma_f32_16x16x32_bf16 v[66:69], v[228:231], v[244:247], v[66:69]
	s_setprio 0
	s_add_u32 s38, s10, s16
	s_addc_u32 s39, s11, s17
	s_add_u32 s34, s38, 0x100
	s_addc_u32 s35, s39, 0
	v_readfirstlane_b32 s40, v137
	s_barrier
	ds_read_b128 v[186:189], v139 offset:16384
	ds_read_b128 v[190:193], v139 offset:17408
	ds_read_b128 v[194:197], v142 offset:16384
	ds_read_b128 v[198:201], v142 offset:17408
	ds_read_b128 v[202:205], v141 offset:16384
	ds_read_b128 v[206:209], v141 offset:17408
	ds_read_b128 v[224:227], v140 offset:16384
	ds_read_b128 v[228:231], v140 offset:17408
	s_mov_b32 m0, s40
	v_lshl_add_u64 v[212:213], s[34:35], 0, v[132:133]
	global_load_lds_dwordx4 v[212:213], off
	v_lshl_add_u64 v[212:213], s[34:35], 0, v[130:131]
	v_readfirstlane_b32 s34, v138
	s_mov_b32 m0, s34
	s_nop 0
	global_load_lds_dwordx4 v[212:213], off
	s_barrier
	s_waitcnt lgkmcnt(0)
	s_setprio 1
	s_waitcnt lgkmcnt(0)
	v_mfma_f32_16x16x32_bf16 v[62:65], v[186:189], v[170:173], v[62:65]
	v_mfma_f32_16x16x32_bf16 v[58:61], v[186:189], v[178:181], v[58:61]
	v_mfma_f32_16x16x32_bf16 v[54:57], v[194:197], v[170:173], v[54:57]
	v_mfma_f32_16x16x32_bf16 v[50:53], v[194:197], v[178:181], v[50:53]
	v_mfma_f32_16x16x32_bf16 v[46:49], v[202:205], v[170:173], v[46:49]
	v_mfma_f32_16x16x32_bf16 v[42:45], v[202:205], v[178:181], v[42:45]
	v_mfma_f32_16x16x32_bf16 v[38:41], v[224:227], v[170:173], v[38:41]
	v_mfma_f32_16x16x32_bf16 v[34:37], v[224:227], v[178:181], v[34:37]
	v_mfma_f32_16x16x32_bf16 v[62:65], v[190:193], v[174:177], v[62:65]
	v_mfma_f32_16x16x32_bf16 v[58:61], v[190:193], v[182:185], v[58:61]
	v_mfma_f32_16x16x32_bf16 v[54:57], v[198:201], v[174:177], v[54:57]
	v_mfma_f32_16x16x32_bf16 v[50:53], v[198:201], v[182:185], v[50:53]
	v_mfma_f32_16x16x32_bf16 v[46:49], v[206:209], v[174:177], v[46:49]
	v_mfma_f32_16x16x32_bf16 v[42:45], v[206:209], v[182:185], v[42:45]
	v_mfma_f32_16x16x32_bf16 v[38:41], v[228:231], v[174:177], v[38:41]
	v_mfma_f32_16x16x32_bf16 v[34:37], v[228:231], v[182:185], v[34:37]
	s_setprio 0
	s_barrier
	s_add_u32 s40, s12, s16
	s_addc_u32 s41, s13, s17
	s_add_u32 s34, s40, 0x100
	s_addc_u32 s35, s41, 0
	v_readfirstlane_b32 s42, v146
	s_mov_b32 m0, s42
	v_lshl_add_u64 v[170:171], s[34:35], 0, v[132:133]
	global_load_lds_dwordx4 v[170:171], off
	v_lshl_add_u64 v[170:171], s[34:35], 0, v[130:131]
	v_readfirstlane_b32 s34, v147
	s_mov_b32 m0, s34
	s_nop 0
	global_load_lds_dwordx4 v[170:171], off
	s_waitcnt vmcnt(6)
	s_barrier
	s_setprio 1
	v_mfma_f32_16x16x32_bf16 v[30:33], v[186:189], v[232:235], v[30:33]
	v_mfma_f32_16x16x32_bf16 v[26:29], v[186:189], v[240:243], v[26:29]
	v_mfma_f32_16x16x32_bf16 v[22:25], v[194:197], v[232:235], v[22:25]
	v_mfma_f32_16x16x32_bf16 v[18:21], v[194:197], v[240:243], v[18:21]
	v_mfma_f32_16x16x32_bf16 v[14:17], v[202:205], v[232:235], v[14:17]
	v_mfma_f32_16x16x32_bf16 v[10:13], v[202:205], v[240:243], v[10:13]
	v_mfma_f32_16x16x32_bf16 v[6:9], v[224:227], v[232:235], v[6:9]
	v_mfma_f32_16x16x32_bf16 v[2:5], v[224:227], v[240:243], v[2:5]
	v_mfma_f32_16x16x32_bf16 v[30:33], v[190:193], v[236:239], v[30:33]
	v_mfma_f32_16x16x32_bf16 v[26:29], v[190:193], v[244:247], v[26:29]
	v_mfma_f32_16x16x32_bf16 v[22:25], v[198:201], v[236:239], v[22:25]
	v_mfma_f32_16x16x32_bf16 v[18:21], v[198:201], v[244:247], v[18:21]
	v_mfma_f32_16x16x32_bf16 v[14:17], v[206:209], v[236:239], v[14:17]
	v_mfma_f32_16x16x32_bf16 v[10:13], v[206:209], v[244:247], v[10:13]
	v_mfma_f32_16x16x32_bf16 v[6:9], v[228:231], v[236:239], v[6:9]
	v_mfma_f32_16x16x32_bf16 v[2:5], v[228:231], v[244:247], v[2:5]
	s_setprio 0
	v_or_b32_e32 v170, 0x18000, v156
	v_or_b32_e32 v172, 0x18000, v158
	s_barrier
	v_or_b32_e32 v171, 0x18000, v157
	ds_read_b128 v[178:181], v170
	ds_read_b128 v[182:185], v171
	v_or_b32_e32 v173, 0x18000, v159
	ds_read_b128 v[186:189], v172
	ds_read_b128 v[190:193], v173
	s_add_u32 s34, s7, s16
	s_addc_u32 s35, s18, s17
	v_readfirstlane_b32 s42, v148
	ds_read_b128 v[194:197], v139 offset:32768
	ds_read_b128 v[198:201], v139 offset:33792
	ds_read_b128 v[202:205], v142 offset:32768
	ds_read_b128 v[206:209], v142 offset:33792
	ds_read_b128 v[224:227], v141 offset:32768
	ds_read_b128 v[228:231], v141 offset:33792
	ds_read_b128 v[232:235], v140 offset:32768
	ds_read_b128 v[236:239], v140 offset:33792
	s_mov_b32 m0, s42
	v_lshl_add_u64 v[174:175], s[34:35], 0, v[132:133]
	global_load_lds_dwordx4 v[174:175], off
	v_lshl_add_u64 v[174:175], s[34:35], 0, v[130:131]
	v_readfirstlane_b32 s34, v149
	s_mov_b32 m0, s34
	s_nop 0
	global_load_lds_dwordx4 v[174:175], off
	s_waitcnt lgkmcnt(8)
	s_barrier
	s_waitcnt lgkmcnt(0)
	s_setprio 1
	s_waitcnt lgkmcnt(0)
	v_mfma_f32_16x16x32_bf16 v[126:129], v[194:197], v[178:181], v[126:129]
	v_mfma_f32_16x16x32_bf16 v[122:125], v[194:197], v[186:189], v[122:125]
	v_mfma_f32_16x16x32_bf16 v[118:121], v[202:205], v[178:181], v[118:121]
	v_mfma_f32_16x16x32_bf16 v[114:117], v[202:205], v[186:189], v[114:117]
	v_mfma_f32_16x16x32_bf16 v[110:113], v[224:227], v[178:181], v[110:113]
	v_mfma_f32_16x16x32_bf16 v[106:109], v[224:227], v[186:189], v[106:109]
	v_mfma_f32_16x16x32_bf16 v[102:105], v[232:235], v[178:181], v[102:105]
	v_mfma_f32_16x16x32_bf16 v[98:101], v[232:235], v[186:189], v[98:101]
	v_mfma_f32_16x16x32_bf16 v[126:129], v[198:201], v[182:185], v[126:129]
	v_mfma_f32_16x16x32_bf16 v[122:125], v[198:201], v[190:193], v[122:125]
	v_mfma_f32_16x16x32_bf16 v[118:121], v[206:209], v[182:185], v[118:121]
	v_mfma_f32_16x16x32_bf16 v[114:117], v[206:209], v[190:193], v[114:117]
	v_mfma_f32_16x16x32_bf16 v[110:113], v[228:231], v[182:185], v[110:113]
	v_mfma_f32_16x16x32_bf16 v[106:109], v[228:231], v[190:193], v[106:109]
	v_mfma_f32_16x16x32_bf16 v[102:105], v[236:239], v[182:185], v[102:105]
	v_mfma_f32_16x16x32_bf16 v[98:101], v[236:239], v[190:193], v[98:101]
	s_setprio 0
	s_barrier
	s_add_u32 s34, s36, 0x180
	v_or_b32_e32 v174, 0x1c000, v156
	v_or_b32_e32 v176, 0x1c000, v158
	s_addc_u32 s35, s37, 0
	v_readfirstlane_b32 s36, v150
	v_or_b32_e32 v175, 0x1c000, v157
	ds_read_b128 v[240:243], v174
	ds_read_b128 v[244:247], v175
	v_or_b32_e32 v177, 0x1c000, v159
	ds_read_b128 v[248:251], v176
	ds_read_b128 v[212:215], v177
	s_mov_b32 m0, s36
	v_lshl_add_u64 v[216:217], s[34:35], 0, v[132:133]
	global_load_lds_dwordx4 v[216:217], off
	v_lshl_add_u64 v[216:217], s[34:35], 0, v[130:131]
	v_readfirstlane_b32 s34, v151
	s_mov_b32 m0, s34
	s_nop 0
	global_load_lds_dwordx4 v[216:217], off
	s_barrier
	s_waitcnt lgkmcnt(0)
	s_setprio 1
	s_waitcnt lgkmcnt(0)
	v_mfma_f32_16x16x32_bf16 v[94:97], v[194:197], v[240:243], v[94:97]
	v_mfma_f32_16x16x32_bf16 v[90:93], v[194:197], v[248:251], v[90:93]
	v_mfma_f32_16x16x32_bf16 v[86:89], v[202:205], v[240:243], v[86:89]
	v_mfma_f32_16x16x32_bf16 v[82:85], v[202:205], v[248:251], v[82:85]
	v_mfma_f32_16x16x32_bf16 v[78:81], v[224:227], v[240:243], v[78:81]
	v_mfma_f32_16x16x32_bf16 v[74:77], v[224:227], v[248:251], v[74:77]
	v_mfma_f32_16x16x32_bf16 v[70:73], v[232:235], v[240:243], v[70:73]
	v_mfma_f32_16x16x32_bf16 v[66:69], v[232:235], v[248:251], v[66:69]
	v_mfma_f32_16x16x32_bf16 v[94:97], v[198:201], v[244:247], v[94:97]
	v_mfma_f32_16x16x32_bf16 v[90:93], v[198:201], v[212:215], v[90:93]
	v_mfma_f32_16x16x32_bf16 v[86:89], v[206:209], v[244:247], v[86:89]
	v_mfma_f32_16x16x32_bf16 v[82:85], v[206:209], v[212:215], v[82:85]
	v_mfma_f32_16x16x32_bf16 v[78:81], v[228:231], v[244:247], v[78:81]
	v_mfma_f32_16x16x32_bf16 v[74:77], v[228:231], v[212:215], v[74:77]
	v_mfma_f32_16x16x32_bf16 v[70:73], v[236:239], v[244:247], v[70:73]
	v_mfma_f32_16x16x32_bf16 v[66:69], v[236:239], v[212:215], v[66:69]
	s_setprio 0
	s_add_u32 s34, s38, 0x180
	s_addc_u32 s35, s39, 0
	v_readfirstlane_b32 s36, v152
	s_barrier
	ds_read_b128 v[194:197], v139 offset:49152
	ds_read_b128 v[198:201], v139 offset:50176
	ds_read_b128 v[202:205], v142 offset:49152
	ds_read_b128 v[206:209], v142 offset:50176
	ds_read_b128 v[224:227], v141 offset:49152
	ds_read_b128 v[228:231], v141 offset:50176
	ds_read_b128 v[232:235], v140 offset:49152
	ds_read_b128 v[236:239], v140 offset:50176
	s_mov_b32 m0, s36
	v_lshl_add_u64 v[216:217], s[34:35], 0, v[132:133]
	global_load_lds_dwordx4 v[216:217], off
	v_lshl_add_u64 v[216:217], s[34:35], 0, v[130:131]
	v_readfirstlane_b32 s34, v153
	s_mov_b32 m0, s34
	s_nop 0
	global_load_lds_dwordx4 v[216:217], off
	s_barrier
	s_waitcnt lgkmcnt(0)
	s_setprio 1
	s_waitcnt lgkmcnt(0)
	v_mfma_f32_16x16x32_bf16 v[62:65], v[194:197], v[178:181], v[62:65]
	v_mfma_f32_16x16x32_bf16 v[58:61], v[194:197], v[186:189], v[58:61]
	v_mfma_f32_16x16x32_bf16 v[54:57], v[202:205], v[178:181], v[54:57]
	v_mfma_f32_16x16x32_bf16 v[50:53], v[202:205], v[186:189], v[50:53]
	v_mfma_f32_16x16x32_bf16 v[46:49], v[224:227], v[178:181], v[46:49]
	v_mfma_f32_16x16x32_bf16 v[42:45], v[224:227], v[186:189], v[42:45]
	v_mfma_f32_16x16x32_bf16 v[38:41], v[232:235], v[178:181], v[38:41]
	v_mfma_f32_16x16x32_bf16 v[34:37], v[232:235], v[186:189], v[34:37]
	v_mfma_f32_16x16x32_bf16 v[62:65], v[198:201], v[182:185], v[62:65]
	v_mfma_f32_16x16x32_bf16 v[58:61], v[198:201], v[190:193], v[58:61]
	v_mfma_f32_16x16x32_bf16 v[54:57], v[206:209], v[182:185], v[54:57]
	v_mfma_f32_16x16x32_bf16 v[50:53], v[206:209], v[190:193], v[50:53]
	v_mfma_f32_16x16x32_bf16 v[46:49], v[228:231], v[182:185], v[46:49]
	v_mfma_f32_16x16x32_bf16 v[42:45], v[228:231], v[190:193], v[42:45]
	v_mfma_f32_16x16x32_bf16 v[38:41], v[236:239], v[182:185], v[38:41]
	v_mfma_f32_16x16x32_bf16 v[34:37], v[236:239], v[190:193], v[34:37]
	s_setprio 0
	s_barrier
	s_add_u32 s34, s40, 0x180
	s_addc_u32 s35, s41, 0
	v_readfirstlane_b32 s36, v154
	s_mov_b32 m0, s36
	v_lshl_add_u64 v[178:179], s[34:35], 0, v[132:133]
	global_load_lds_dwordx4 v[178:179], off
	v_lshl_add_u64 v[178:179], s[34:35], 0, v[130:131]
	v_readfirstlane_b32 s34, v155
	s_mov_b32 m0, s34
	s_nop 0
	global_load_lds_dwordx4 v[178:179], off
	s_waitcnt vmcnt(6)
	s_barrier
	s_setprio 1
	v_mfma_f32_16x16x32_bf16 v[30:33], v[194:197], v[240:243], v[30:33]
	v_mfma_f32_16x16x32_bf16 v[26:29], v[194:197], v[248:251], v[26:29]
	v_mfma_f32_16x16x32_bf16 v[22:25], v[202:205], v[240:243], v[22:25]
	v_mfma_f32_16x16x32_bf16 v[18:21], v[202:205], v[248:251], v[18:21]
	v_mfma_f32_16x16x32_bf16 v[14:17], v[224:227], v[240:243], v[14:17]
	v_mfma_f32_16x16x32_bf16 v[10:13], v[224:227], v[248:251], v[10:13]
	v_mfma_f32_16x16x32_bf16 v[6:9], v[232:235], v[240:243], v[6:9]
	v_mfma_f32_16x16x32_bf16 v[2:5], v[232:235], v[248:251], v[2:5]
	v_mfma_f32_16x16x32_bf16 v[30:33], v[198:201], v[244:247], v[30:33]
	v_mfma_f32_16x16x32_bf16 v[26:29], v[198:201], v[212:215], v[26:29]
	v_mfma_f32_16x16x32_bf16 v[22:25], v[206:209], v[244:247], v[22:25]
	v_mfma_f32_16x16x32_bf16 v[18:21], v[206:209], v[212:215], v[18:21]
	v_mfma_f32_16x16x32_bf16 v[14:17], v[228:231], v[244:247], v[14:17]
	v_mfma_f32_16x16x32_bf16 v[10:13], v[228:231], v[212:215], v[10:13]
	v_mfma_f32_16x16x32_bf16 v[6:9], v[236:239], v[244:247], v[6:9]
	v_mfma_f32_16x16x32_bf16 v[2:5], v[236:239], v[212:215], v[2:5]
	s_setprio 0
	s_add_i32 s31, s31, 2
	s_add_u32 s16, s16, 0x100
	s_addc_u32 s17, s17, 0
	s_cmp_lt_u32 s31, 12
	s_barrier
	s_cbranch_scc1 .LBB0_288
	s_add_u32 s0, s14, 0x780
	s_addc_u32 s1, s15, 0
	ds_read_b128 v[146:149], v160
	ds_read_b128 v[150:153], v161
	ds_read_b128 v[154:157], v162
	ds_read_b128 v[158:161], v163
	ds_read_b128 v[178:181], v139
	ds_read_b128 v[182:185], v139 offset:1024
	ds_read_b128 v[186:189], v142
	ds_read_b128 v[190:193], v142 offset:1024
	ds_read_b128 v[194:197], v141
	ds_read_b128 v[198:201], v141 offset:1024
	ds_read_b128 v[202:205], v140
	ds_read_b128 v[206:209], v140 offset:1024
	v_readfirstlane_b32 s7, v164
	v_lshl_add_u64 v[132:133], s[0:1], 0, v[132:133]
	s_mov_b32 m0, s7
	v_lshl_add_u64 v[130:131], s[0:1], 0, v[130:131]
	v_readfirstlane_b32 s0, v165
	global_load_lds_dwordx4 v[132:133], off
	s_mov_b32 m0, s0
	s_nop 0
	global_load_lds_dwordx4 v[130:131], off
	s_barrier
	s_waitcnt lgkmcnt(0)
	s_setprio 1
	s_waitcnt lgkmcnt(0)
	v_mfma_f32_16x16x32_bf16 v[126:129], v[178:181], v[146:149], v[126:129]
	v_mfma_f32_16x16x32_bf16 v[122:125], v[178:181], v[154:157], v[122:125]
	v_mfma_f32_16x16x32_bf16 v[110:113], v[194:197], v[146:149], v[110:113]
	v_mfma_f32_16x16x32_bf16 v[106:109], v[194:197], v[154:157], v[106:109]
	v_mfma_f32_16x16x32_bf16 v[126:129], v[182:185], v[150:153], v[126:129]
	v_mfma_f32_16x16x32_bf16 v[122:125], v[182:185], v[158:161], v[122:125]
	v_mfma_f32_16x16x32_bf16 v[118:121], v[186:189], v[146:149], v[118:121]
	v_mfma_f32_16x16x32_bf16 v[114:117], v[186:189], v[154:157], v[114:117]
	v_mfma_f32_16x16x32_bf16 v[110:113], v[198:201], v[150:153], v[110:113]
	v_mfma_f32_16x16x32_bf16 v[106:109], v[198:201], v[158:161], v[106:109]
	v_mfma_f32_16x16x32_bf16 v[102:105], v[202:205], v[146:149], v[102:105]
	v_mfma_f32_16x16x32_bf16 v[98:101], v[202:205], v[154:157], v[98:101]
	v_mfma_f32_16x16x32_bf16 v[130:133], v[190:193], v[150:153], v[118:121]
	v_mfma_f32_16x16x32_bf16 v[162:165], v[190:193], v[158:161], v[114:117]
	v_mfma_f32_16x16x32_bf16 v[212:215], v[206:209], v[150:153], v[102:105]
	v_mfma_f32_16x16x32_bf16 v[224:227], v[206:209], v[158:161], v[98:101]
	s_setprio 0
	s_barrier
	s_nop 0
	ds_read_b128 v[98:101], v166
	ds_read_b128 v[102:105], v167
	ds_read_b128 v[114:117], v168
	ds_read_b128 v[118:121], v169
	s_barrier
	s_waitcnt lgkmcnt(0)
	s_setprio 1
	s_waitcnt lgkmcnt(3)
	v_mfma_f32_16x16x32_bf16 v[94:97], v[178:181], v[98:101], v[94:97]
	s_waitcnt lgkmcnt(1)
	v_mfma_f32_16x16x32_bf16 v[90:93], v[178:181], v[114:117], v[90:93]
	v_mfma_f32_16x16x32_bf16 v[78:81], v[194:197], v[98:101], v[78:81]
	v_mfma_f32_16x16x32_bf16 v[74:77], v[194:197], v[114:117], v[74:77]
	v_mfma_f32_16x16x32_bf16 v[94:97], v[182:185], v[102:105], v[94:97]
	s_waitcnt lgkmcnt(0)
	v_mfma_f32_16x16x32_bf16 v[90:93], v[182:185], v[118:121], v[90:93]
	v_mfma_f32_16x16x32_bf16 v[86:89], v[186:189], v[98:101], v[86:89]
	v_mfma_f32_16x16x32_bf16 v[82:85], v[186:189], v[114:117], v[82:85]
	v_mfma_f32_16x16x32_bf16 v[78:81], v[198:201], v[102:105], v[78:81]
	v_mfma_f32_16x16x32_bf16 v[74:77], v[198:201], v[118:121], v[74:77]
	v_mfma_f32_16x16x32_bf16 v[70:73], v[202:205], v[98:101], v[70:73]
	v_mfma_f32_16x16x32_bf16 v[66:69], v[202:205], v[114:117], v[66:69]
	v_mfma_f32_16x16x32_bf16 v[166:169], v[190:193], v[102:105], v[86:89]
	v_mfma_f32_16x16x32_bf16 v[178:181], v[190:193], v[118:121], v[82:85]
	v_mfma_f32_16x16x32_bf16 v[182:185], v[206:209], v[102:105], v[70:73]
	v_mfma_f32_16x16x32_bf16 v[186:189], v[206:209], v[118:121], v[66:69]
	s_setprio 0
	s_barrier
	s_nop 1
	ds_read_b128 v[66:69], v139 offset:16384
	ds_read_b128 v[70:73], v139 offset:17408
	ds_read_b128 v[82:85], v142 offset:16384
	ds_read_b128 v[86:89], v142 offset:17408
	ds_read_b128 v[190:193], v141 offset:16384
	ds_read_b128 v[194:197], v141 offset:17408
	ds_read_b128 v[198:201], v140 offset:16384
	ds_read_b128 v[202:205], v140 offset:17408
	s_waitcnt vmcnt(4)
	s_barrier
	s_waitcnt lgkmcnt(0)
	s_setprio 1
	s_waitcnt lgkmcnt(7)
	v_mfma_f32_16x16x32_bf16 v[62:65], v[66:69], v[146:149], v[62:65]
	v_mfma_f32_16x16x32_bf16 v[58:61], v[66:69], v[154:157], v[58:61]
	s_waitcnt lgkmcnt(3)
	v_mfma_f32_16x16x32_bf16 v[46:49], v[190:193], v[146:149], v[46:49]
	v_mfma_f32_16x16x32_bf16 v[42:45], v[190:193], v[154:157], v[42:45]
	v_mfma_f32_16x16x32_bf16 v[62:65], v[70:73], v[150:153], v[62:65]
	v_mfma_f32_16x16x32_bf16 v[58:61], v[70:73], v[158:161], v[58:61]
	v_mfma_f32_16x16x32_bf16 v[54:57], v[82:85], v[146:149], v[54:57]
	v_mfma_f32_16x16x32_bf16 v[50:53], v[82:85], v[154:157], v[50:53]
	s_waitcnt lgkmcnt(2)
	v_mfma_f32_16x16x32_bf16 v[46:49], v[194:197], v[150:153], v[46:49]
	v_mfma_f32_16x16x32_bf16 v[42:45], v[194:197], v[158:161], v[42:45]
	s_waitcnt lgkmcnt(1)
	v_mfma_f32_16x16x32_bf16 v[38:41], v[198:201], v[146:149], v[38:41]
	v_mfma_f32_16x16x32_bf16 v[34:37], v[198:201], v[154:157], v[34:37]
	v_mfma_f32_16x16x32_bf16 v[206:209], v[86:89], v[150:153], v[54:57]
	v_mfma_f32_16x16x32_bf16 v[228:231], v[86:89], v[158:161], v[50:53]
	s_waitcnt lgkmcnt(0)
	v_mfma_f32_16x16x32_bf16 v[146:149], v[202:205], v[150:153], v[38:41]
	v_mfma_f32_16x16x32_bf16 v[150:153], v[202:205], v[158:161], v[34:37]
	s_setprio 0
	s_setprio 1
	v_mfma_f32_16x16x32_bf16 v[30:33], v[66:69], v[98:101], v[30:33]
	v_mfma_f32_16x16x32_bf16 v[26:29], v[66:69], v[114:117], v[26:29]
	v_mfma_f32_16x16x32_bf16 v[14:17], v[190:193], v[98:101], v[14:17]
	v_mfma_f32_16x16x32_bf16 v[10:13], v[190:193], v[114:117], v[10:13]
	v_mfma_f32_16x16x32_bf16 v[30:33], v[70:73], v[102:105], v[30:33]
	v_mfma_f32_16x16x32_bf16 v[26:29], v[70:73], v[118:121], v[26:29]
	v_mfma_f32_16x16x32_bf16 v[22:25], v[82:85], v[98:101], v[22:25]
	v_mfma_f32_16x16x32_bf16 v[18:21], v[82:85], v[114:117], v[18:21]
	v_mfma_f32_16x16x32_bf16 v[14:17], v[194:197], v[102:105], v[14:17]
	v_mfma_f32_16x16x32_bf16 v[10:13], v[194:197], v[118:121], v[10:13]
	v_mfma_f32_16x16x32_bf16 v[6:9], v[198:201], v[98:101], v[6:9]
	v_mfma_f32_16x16x32_bf16 v[2:5], v[198:201], v[114:117], v[2:5]
	v_mfma_f32_16x16x32_bf16 v[154:157], v[86:89], v[102:105], v[22:25]
	v_mfma_f32_16x16x32_bf16 v[158:161], v[86:89], v[118:121], v[18:21]
	v_mfma_f32_16x16x32_bf16 v[190:193], v[202:205], v[102:105], v[6:9]
	v_mfma_f32_16x16x32_bf16 v[194:197], v[202:205], v[118:121], v[2:5]
	s_setprio 0
	s_barrier
	s_nop 1
	ds_read_b128 v[2:5], v170
	ds_read_b128 v[6:9], v171
	ds_read_b128 v[198:201], v172
	ds_read_b128 v[170:173], v173
	ds_read_b128 v[18:21], v139 offset:32768
	ds_read_b128 v[22:25], v139 offset:33792
	ds_read_b128 v[34:37], v142 offset:32768
	ds_read_b128 v[38:41], v142 offset:33792
	ds_read_b128 v[50:53], v141 offset:32768
	ds_read_b128 v[54:57], v141 offset:33792
	ds_read_b128 v[202:205], v140 offset:32768
	ds_read_b128 v[232:235], v140 offset:33792
	s_waitcnt vmcnt(2)
	s_barrier
	s_waitcnt lgkmcnt(0)
	s_setprio 1
	s_waitcnt lgkmcnt(7)
	v_mfma_f32_16x16x32_bf16 v[66:69], v[18:21], v[2:5], v[126:129]
	s_waitcnt lgkmcnt(6)
	v_mfma_f32_16x16x32_bf16 v[114:117], v[22:25], v[6:9], v[66:69]
	v_mfma_f32_16x16x32_bf16 v[66:69], v[18:21], v[198:201], v[122:125]
	v_mfma_f32_16x16x32_bf16 v[118:121], v[22:25], v[170:173], v[66:69]
	s_waitcnt lgkmcnt(5)
	v_mfma_f32_16x16x32_bf16 v[66:69], v[34:37], v[2:5], v[130:133]
	s_waitcnt lgkmcnt(4)
	v_mfma_f32_16x16x32_bf16 v[98:101], v[38:41], v[6:9], v[66:69]
	v_mfma_f32_16x16x32_bf16 v[66:69], v[34:37], v[198:201], v[162:165]
	v_mfma_f32_16x16x32_bf16 v[102:105], v[38:41], v[170:173], v[66:69]
	s_waitcnt lgkmcnt(3)
	v_mfma_f32_16x16x32_bf16 v[66:69], v[50:53], v[2:5], v[110:113]
	s_waitcnt lgkmcnt(2)
	v_mfma_f32_16x16x32_bf16 v[82:85], v[54:57], v[6:9], v[66:69]
	v_mfma_f32_16x16x32_bf16 v[66:69], v[50:53], v[198:201], v[106:109]
	v_mfma_f32_16x16x32_bf16 v[86:89], v[54:57], v[170:173], v[66:69]
	s_waitcnt lgkmcnt(1)
	v_mfma_f32_16x16x32_bf16 v[66:69], v[202:205], v[2:5], v[212:215]
	v_mfma_f32_16x16x32_bf16 v[70:73], v[202:205], v[198:201], v[224:227]
	s_waitcnt lgkmcnt(0)
	v_mfma_f32_16x16x32_bf16 v[66:69], v[232:235], v[6:9], v[66:69]
	v_mfma_f32_16x16x32_bf16 v[70:73], v[232:235], v[170:173], v[70:73]
	s_setprio 0
	s_barrier
	ds_read_b128 v[130:133], v174
	ds_read_b128 v[162:165], v175
	ds_read_b128 v[212:215], v176
	ds_read_b128 v[174:177], v177
	s_waitcnt vmcnt(0)
	s_barrier
	s_waitcnt lgkmcnt(0)
	s_setprio 1
	s_waitcnt lgkmcnt(3)
	v_mfma_f32_16x16x32_bf16 v[94:97], v[18:21], v[130:133], v[94:97]
	s_waitcnt lgkmcnt(1)
	v_mfma_f32_16x16x32_bf16 v[18:21], v[18:21], v[212:215], v[90:93]
	s_waitcnt lgkmcnt(0)
	v_mfma_f32_16x16x32_bf16 v[122:125], v[22:25], v[174:177], v[18:21]
	v_mfma_f32_16x16x32_bf16 v[18:21], v[34:37], v[130:133], v[166:169]
	v_mfma_f32_16x16x32_bf16 v[110:113], v[38:41], v[162:165], v[18:21]
	v_mfma_f32_16x16x32_bf16 v[18:21], v[34:37], v[212:215], v[178:181]
	v_mfma_f32_16x16x32_bf16 v[106:109], v[38:41], v[174:177], v[18:21]
	v_mfma_f32_16x16x32_bf16 v[18:21], v[50:53], v[130:133], v[78:81]
	v_mfma_f32_16x16x32_bf16 v[126:129], v[22:25], v[162:165], v[94:97]
	v_mfma_f32_16x16x32_bf16 v[94:97], v[54:57], v[162:165], v[18:21]
	v_mfma_f32_16x16x32_bf16 v[18:21], v[50:53], v[212:215], v[74:77]
	v_mfma_f32_16x16x32_bf16 v[90:93], v[54:57], v[174:177], v[18:21]
	v_mfma_f32_16x16x32_bf16 v[18:21], v[202:205], v[130:133], v[182:185]
	v_mfma_f32_16x16x32_bf16 v[78:81], v[232:235], v[162:165], v[18:21]
	v_mfma_f32_16x16x32_bf16 v[18:21], v[202:205], v[212:215], v[186:189]
	v_mfma_f32_16x16x32_bf16 v[74:77], v[232:235], v[174:177], v[18:21]
	s_setprio 0
	s_barrier
	ds_read_b128 v[166:169], v139 offset:49152
	ds_read_b128 v[178:181], v139 offset:50176
	ds_read_b128 v[182:185], v142 offset:49152
	ds_read_b128 v[186:189], v142 offset:50176
	ds_read_b128 v[202:205], v141 offset:49152
	ds_read_b128 v[224:227], v141 offset:50176
	ds_read_b128 v[232:235], v140 offset:49152
	ds_read_b128 v[138:141], v140 offset:50176
	s_barrier
	s_waitcnt lgkmcnt(0)
	s_setprio 1
	s_waitcnt lgkmcnt(7)
	v_mfma_f32_16x16x32_bf16 v[18:21], v[166:169], v[2:5], v[62:65]
	s_waitcnt lgkmcnt(6)
	v_mfma_f32_16x16x32_bf16 v[50:53], v[178:181], v[6:9], v[18:21]
	v_mfma_f32_16x16x32_bf16 v[18:21], v[166:169], v[198:201], v[58:61]
	v_mfma_f32_16x16x32_bf16 v[54:57], v[178:181], v[170:173], v[18:21]
	s_waitcnt lgkmcnt(5)
	v_mfma_f32_16x16x32_bf16 v[18:21], v[182:185], v[2:5], v[206:209]
	s_waitcnt lgkmcnt(4)
	v_mfma_f32_16x16x32_bf16 v[34:37], v[186:189], v[6:9], v[18:21]
	v_mfma_f32_16x16x32_bf16 v[18:21], v[182:185], v[198:201], v[228:231]
	v_mfma_f32_16x16x32_bf16 v[38:41], v[186:189], v[170:173], v[18:21]
	s_waitcnt lgkmcnt(3)
	v_mfma_f32_16x16x32_bf16 v[18:21], v[202:205], v[2:5], v[46:49]
	s_waitcnt lgkmcnt(1)
	v_mfma_f32_16x16x32_bf16 v[2:5], v[232:235], v[2:5], v[146:149]
	v_mfma_f32_16x16x32_bf16 v[18:21], v[224:227], v[6:9], v[18:21]
	v_mfma_f32_16x16x32_bf16 v[22:25], v[202:205], v[198:201], v[42:45]
	s_waitcnt lgkmcnt(0)
	v_mfma_f32_16x16x32_bf16 v[2:5], v[138:141], v[6:9], v[2:5]
	v_mfma_f32_16x16x32_bf16 v[6:9], v[232:235], v[198:201], v[150:153]
	v_mfma_f32_16x16x32_bf16 v[22:25], v[224:227], v[170:173], v[22:25]
	v_mfma_f32_16x16x32_bf16 v[6:9], v[138:141], v[170:173], v[6:9]
	s_setprio 0
	s_setprio 1
	v_mfma_f32_16x16x32_bf16 v[26:29], v[166:169], v[212:215], v[26:29]
	v_mfma_f32_16x16x32_bf16 v[58:61], v[178:181], v[174:177], v[26:29]
	v_mfma_f32_16x16x32_bf16 v[26:29], v[182:185], v[130:133], v[154:157]
	v_mfma_f32_16x16x32_bf16 v[46:49], v[186:189], v[162:165], v[26:29]
	v_mfma_f32_16x16x32_bf16 v[26:29], v[182:185], v[212:215], v[158:161]
	v_mfma_f32_16x16x32_bf16 v[10:13], v[202:205], v[212:215], v[10:13]
	v_mfma_f32_16x16x32_bf16 v[30:33], v[166:169], v[130:133], v[30:33]
	v_mfma_f32_16x16x32_bf16 v[42:45], v[186:189], v[174:177], v[26:29]
	v_mfma_f32_16x16x32_bf16 v[14:17], v[202:205], v[130:133], v[14:17]
	v_mfma_f32_16x16x32_bf16 v[26:29], v[224:227], v[174:177], v[10:13]
	v_mfma_f32_16x16x32_bf16 v[10:13], v[232:235], v[130:133], v[190:193]
	v_mfma_f32_16x16x32_bf16 v[62:65], v[178:181], v[162:165], v[30:33]
	v_mfma_f32_16x16x32_bf16 v[30:33], v[224:227], v[162:165], v[14:17]
	v_mfma_f32_16x16x32_bf16 v[14:17], v[138:141], v[162:165], v[10:13]
	v_mfma_f32_16x16x32_bf16 v[10:13], v[232:235], v[212:215], v[194:197]
	v_mfma_f32_16x16x32_bf16 v[10:13], v[138:141], v[174:177], v[10:13]
	s_setprio 0
	s_movk_i32 s0, 0x100
	v_cmp_gt_u32_e32 vcc, s0, v134
	s_barrier
	s_and_saveexec_b64 s[0:1], vcc
	s_cbranch_execz .LBB0_291
	s_barrier

.LBB0_709:
	v_or_b32_e32 v160, 0x10000, v156
	v_or_b32_e32 v162, 0x10000, v158
	v_or_b32_e32 v161, 0x10000, v157
	ds_read_b128 v[170:173], v160
	ds_read_b128 v[174:177], v161
	v_or_b32_e32 v163, 0x10000, v159
	ds_read_b128 v[178:181], v162
	ds_read_b128 v[182:185], v163
	s_add_u32 s25, s17, s14
	s_addc_u32 s27, s23, s15
	s_add_u32 s26, s25, 0x80
	v_add_u32_e32 v164, 0xc000, v138
	s_addc_u32 s27, s27, 0
	v_readfirstlane_b32 s25, v164
	v_add_u32_e32 v165, 0xe000, v138
	ds_read_b128 v[186:189], v140
	ds_read_b128 v[190:193], v140 offset:1024
	ds_read_b128 v[194:197], v143
	ds_read_b128 v[198:201], v143 offset:1024
	ds_read_b128 v[202:205], v142
	ds_read_b128 v[206:209], v142 offset:1024
	ds_read_b128 v[212:215], v141
	ds_read_b128 v[224:227], v141 offset:1024
	s_mov_b32 m0, s25
	v_lshl_add_u64 v[166:167], s[26:27], 0, v[132:133]
	v_readfirstlane_b32 s25, v165
	global_load_lds_dwordx4 v[166:167], off
	v_lshl_add_u64 v[166:167], s[26:27], 0, v[130:131]
	s_mov_b32 m0, s25
	s_nop 0
	global_load_lds_dwordx4 v[166:167], off
	s_waitcnt lgkmcnt(8)
	s_barrier
	s_waitcnt lgkmcnt(0)
	s_setprio 1
	s_waitcnt lgkmcnt(0)
	v_mfma_f32_16x16x32_bf16 v[126:129], v[186:189], v[170:173], v[126:129]
	v_mfma_f32_16x16x32_bf16 v[122:125], v[186:189], v[178:181], v[122:125]
	v_mfma_f32_16x16x32_bf16 v[118:121], v[194:197], v[170:173], v[118:121]
	v_mfma_f32_16x16x32_bf16 v[114:117], v[194:197], v[178:181], v[114:117]
	v_mfma_f32_16x16x32_bf16 v[110:113], v[202:205], v[170:173], v[110:113]
	v_mfma_f32_16x16x32_bf16 v[106:109], v[202:205], v[178:181], v[106:109]
	v_mfma_f32_16x16x32_bf16 v[102:105], v[212:215], v[170:173], v[102:105]
	v_mfma_f32_16x16x32_bf16 v[98:101], v[212:215], v[178:181], v[98:101]
	v_mfma_f32_16x16x32_bf16 v[126:129], v[190:193], v[174:177], v[126:129]
	v_mfma_f32_16x16x32_bf16 v[122:125], v[190:193], v[182:185], v[122:125]
	v_mfma_f32_16x16x32_bf16 v[118:121], v[198:201], v[174:177], v[118:121]
	v_mfma_f32_16x16x32_bf16 v[114:117], v[198:201], v[182:185], v[114:117]
	v_mfma_f32_16x16x32_bf16 v[110:113], v[206:209], v[174:177], v[110:113]
	v_mfma_f32_16x16x32_bf16 v[106:109], v[206:209], v[182:185], v[106:109]
	v_mfma_f32_16x16x32_bf16 v[102:105], v[224:227], v[174:177], v[102:105]
	v_mfma_f32_16x16x32_bf16 v[98:101], v[224:227], v[182:185], v[98:101]
	s_setprio 0
	s_barrier
	s_add_u32 s25, s6, s14
	s_addc_u32 s28, s7, s15
	s_add_u32 s26, s25, 0x100
	v_or_b32_e32 v166, 0x14000, v156
	v_or_b32_e32 v168, 0x14000, v158
	s_addc_u32 s27, s28, 0
	v_readfirstlane_b32 s29, v144
	v_or_b32_e32 v167, 0x14000, v157
	ds_read_b128 v[228:231], v166
	ds_read_b128 v[232:235], v167
	v_or_b32_e32 v169, 0x14000, v159
	ds_read_b128 v[236:239], v168
	ds_read_b128 v[240:243], v169
	s_mov_b32 m0, s29
	v_lshl_add_u64 v[216:217], s[26:27], 0, v[132:133]
	global_load_lds_dwordx4 v[216:217], off
	v_lshl_add_u64 v[216:217], s[26:27], 0, v[130:131]
	v_readfirstlane_b32 s26, v145
	s_mov_b32 m0, s26
	s_nop 0
	global_load_lds_dwordx4 v[216:217], off
	s_barrier
	s_waitcnt lgkmcnt(0)
	s_setprio 1
	s_waitcnt lgkmcnt(0)
	v_mfma_f32_16x16x32_bf16 v[94:97], v[186:189], v[228:231], v[94:97]
	v_mfma_f32_16x16x32_bf16 v[90:93], v[186:189], v[236:239], v[90:93]
	v_mfma_f32_16x16x32_bf16 v[86:89], v[194:197], v[228:231], v[86:89]
	v_mfma_f32_16x16x32_bf16 v[82:85], v[194:197], v[236:239], v[82:85]
	v_mfma_f32_16x16x32_bf16 v[78:81], v[202:205], v[228:231], v[78:81]
	v_mfma_f32_16x16x32_bf16 v[74:77], v[202:205], v[236:239], v[74:77]
	v_mfma_f32_16x16x32_bf16 v[70:73], v[212:215], v[228:231], v[70:73]
	v_mfma_f32_16x16x32_bf16 v[66:69], v[212:215], v[236:239], v[66:69]
	v_mfma_f32_16x16x32_bf16 v[94:97], v[190:193], v[232:235], v[94:97]
	v_mfma_f32_16x16x32_bf16 v[90:93], v[190:193], v[240:243], v[90:93]
	v_mfma_f32_16x16x32_bf16 v[86:89], v[198:201], v[232:235], v[86:89]
	v_mfma_f32_16x16x32_bf16 v[82:85], v[198:201], v[240:243], v[82:85]
	v_mfma_f32_16x16x32_bf16 v[78:81], v[206:209], v[232:235], v[78:81]
	v_mfma_f32_16x16x32_bf16 v[74:77], v[206:209], v[240:243], v[74:77]
	v_mfma_f32_16x16x32_bf16 v[70:73], v[224:227], v[232:235], v[70:73]
	v_mfma_f32_16x16x32_bf16 v[66:69], v[224:227], v[240:243], v[66:69]
	s_setprio 0
	s_add_u32 s29, s8, s14
	s_addc_u32 s30, s9, s15
	s_add_u32 s26, s29, 0x100
	s_addc_u32 s27, s30, 0
	v_readfirstlane_b32 s31, v138
	s_barrier
	ds_read_b128 v[186:189], v140 offset:16384
	ds_read_b128 v[190:193], v140 offset:17408
	ds_read_b128 v[194:197], v143 offset:16384
	ds_read_b128 v[198:201], v143 offset:17408
	ds_read_b128 v[202:205], v142 offset:16384
	ds_read_b128 v[206:209], v142 offset:17408
	ds_read_b128 v[212:215], v141 offset:16384
	ds_read_b128 v[224:227], v141 offset:17408
	s_mov_b32 m0, s31
	v_lshl_add_u64 v[216:217], s[26:27], 0, v[132:133]
	global_load_lds_dwordx4 v[216:217], off
	v_lshl_add_u64 v[216:217], s[26:27], 0, v[130:131]
	v_readfirstlane_b32 s26, v139
	s_mov_b32 m0, s26
	s_nop 0
	global_load_lds_dwordx4 v[216:217], off
	s_barrier
	s_waitcnt lgkmcnt(0)
	s_setprio 1
	s_waitcnt lgkmcnt(0)
	v_mfma_f32_16x16x32_bf16 v[62:65], v[186:189], v[170:173], v[62:65]
	v_mfma_f32_16x16x32_bf16 v[58:61], v[186:189], v[178:181], v[58:61]
	v_mfma_f32_16x16x32_bf16 v[54:57], v[194:197], v[170:173], v[54:57]
	v_mfma_f32_16x16x32_bf16 v[50:53], v[194:197], v[178:181], v[50:53]
	v_mfma_f32_16x16x32_bf16 v[46:49], v[202:205], v[170:173], v[46:49]
	v_mfma_f32_16x16x32_bf16 v[42:45], v[202:205], v[178:181], v[42:45]
	v_mfma_f32_16x16x32_bf16 v[38:41], v[212:215], v[170:173], v[38:41]
	v_mfma_f32_16x16x32_bf16 v[34:37], v[212:215], v[178:181], v[34:37]
	v_mfma_f32_16x16x32_bf16 v[62:65], v[190:193], v[174:177], v[62:65]
	v_mfma_f32_16x16x32_bf16 v[58:61], v[190:193], v[182:185], v[58:61]
	v_mfma_f32_16x16x32_bf16 v[54:57], v[198:201], v[174:177], v[54:57]
	v_mfma_f32_16x16x32_bf16 v[50:53], v[198:201], v[182:185], v[50:53]
	v_mfma_f32_16x16x32_bf16 v[46:49], v[206:209], v[174:177], v[46:49]
	v_mfma_f32_16x16x32_bf16 v[42:45], v[206:209], v[182:185], v[42:45]
	v_mfma_f32_16x16x32_bf16 v[38:41], v[224:227], v[174:177], v[38:41]
	v_mfma_f32_16x16x32_bf16 v[34:37], v[224:227], v[182:185], v[34:37]
	s_setprio 0
	s_barrier
	s_add_u32 s31, s10, s14
	s_addc_u32 s34, s11, s15
	s_add_u32 s26, s31, 0x100
	s_addc_u32 s27, s34, 0
	v_readfirstlane_b32 s35, v146
	s_mov_b32 m0, s35
	v_lshl_add_u64 v[170:171], s[26:27], 0, v[132:133]
	global_load_lds_dwordx4 v[170:171], off
	v_lshl_add_u64 v[170:171], s[26:27], 0, v[130:131]
	v_readfirstlane_b32 s26, v147
	s_mov_b32 m0, s26
	s_nop 0
	global_load_lds_dwordx4 v[170:171], off
	s_waitcnt vmcnt(6)
	s_barrier
	s_setprio 1
	v_mfma_f32_16x16x32_bf16 v[30:33], v[186:189], v[228:231], v[30:33]
	v_mfma_f32_16x16x32_bf16 v[26:29], v[186:189], v[236:239], v[26:29]
	v_mfma_f32_16x16x32_bf16 v[22:25], v[194:197], v[228:231], v[22:25]
	v_mfma_f32_16x16x32_bf16 v[18:21], v[194:197], v[236:239], v[18:21]
	v_mfma_f32_16x16x32_bf16 v[14:17], v[202:205], v[228:231], v[14:17]
	v_mfma_f32_16x16x32_bf16 v[10:13], v[202:205], v[236:239], v[10:13]
	v_mfma_f32_16x16x32_bf16 v[6:9], v[212:215], v[228:231], v[6:9]
	v_mfma_f32_16x16x32_bf16 v[2:5], v[212:215], v[236:239], v[2:5]
	v_mfma_f32_16x16x32_bf16 v[30:33], v[190:193], v[232:235], v[30:33]
	v_mfma_f32_16x16x32_bf16 v[26:29], v[190:193], v[240:243], v[26:29]
	v_mfma_f32_16x16x32_bf16 v[22:25], v[198:201], v[232:235], v[22:25]
	v_mfma_f32_16x16x32_bf16 v[18:21], v[198:201], v[240:243], v[18:21]
	v_mfma_f32_16x16x32_bf16 v[14:17], v[206:209], v[232:235], v[14:17]
	v_mfma_f32_16x16x32_bf16 v[10:13], v[206:209], v[240:243], v[10:13]
	v_mfma_f32_16x16x32_bf16 v[6:9], v[224:227], v[232:235], v[6:9]
	v_mfma_f32_16x16x32_bf16 v[2:5], v[224:227], v[240:243], v[2:5]
	s_setprio 0
	v_or_b32_e32 v170, 0x18000, v156
	v_or_b32_e32 v172, 0x18000, v158
	s_barrier
	v_or_b32_e32 v171, 0x18000, v157
	ds_read_b128 v[178:181], v170
	ds_read_b128 v[182:185], v171
	v_or_b32_e32 v173, 0x18000, v159
	ds_read_b128 v[186:189], v172
	ds_read_b128 v[190:193], v173
	s_add_u32 s26, s1, s14
	s_addc_u32 s27, s16, s15
	v_readfirstlane_b32 s35, v148
	ds_read_b128 v[194:197], v140 offset:32768
	ds_read_b128 v[198:201], v140 offset:33792
	ds_read_b128 v[202:205], v143 offset:32768
	ds_read_b128 v[206:209], v143 offset:33792
	ds_read_b128 v[212:215], v142 offset:32768
	ds_read_b128 v[224:227], v142 offset:33792
	ds_read_b128 v[228:231], v141 offset:32768
	ds_read_b128 v[232:235], v141 offset:33792
	s_mov_b32 m0, s35
	v_lshl_add_u64 v[174:175], s[26:27], 0, v[132:133]
	global_load_lds_dwordx4 v[174:175], off
	v_lshl_add_u64 v[174:175], s[26:27], 0, v[130:131]
	v_readfirstlane_b32 s26, v149
	s_mov_b32 m0, s26
	s_nop 0
	global_load_lds_dwordx4 v[174:175], off
	s_waitcnt lgkmcnt(8)
	s_barrier
	s_waitcnt lgkmcnt(0)
	s_setprio 1
	s_waitcnt lgkmcnt(0)
	v_mfma_f32_16x16x32_bf16 v[126:129], v[194:197], v[178:181], v[126:129]
	v_mfma_f32_16x16x32_bf16 v[122:125], v[194:197], v[186:189], v[122:125]
	v_mfma_f32_16x16x32_bf16 v[118:121], v[202:205], v[178:181], v[118:121]
	v_mfma_f32_16x16x32_bf16 v[114:117], v[202:205], v[186:189], v[114:117]
	v_mfma_f32_16x16x32_bf16 v[110:113], v[212:215], v[178:181], v[110:113]
	v_mfma_f32_16x16x32_bf16 v[106:109], v[212:215], v[186:189], v[106:109]
	v_mfma_f32_16x16x32_bf16 v[102:105], v[228:231], v[178:181], v[102:105]
	v_mfma_f32_16x16x32_bf16 v[98:101], v[228:231], v[186:189], v[98:101]
	v_mfma_f32_16x16x32_bf16 v[126:129], v[198:201], v[182:185], v[126:129]
	v_mfma_f32_16x16x32_bf16 v[122:125], v[198:201], v[190:193], v[122:125]
	v_mfma_f32_16x16x32_bf16 v[118:121], v[206:209], v[182:185], v[118:121]
	v_mfma_f32_16x16x32_bf16 v[114:117], v[206:209], v[190:193], v[114:117]
	v_mfma_f32_16x16x32_bf16 v[110:113], v[224:227], v[182:185], v[110:113]
	v_mfma_f32_16x16x32_bf16 v[106:109], v[224:227], v[190:193], v[106:109]
	v_mfma_f32_16x16x32_bf16 v[102:105], v[232:235], v[182:185], v[102:105]
	v_mfma_f32_16x16x32_bf16 v[98:101], v[232:235], v[190:193], v[98:101]
	s_setprio 0
	s_barrier
	s_add_u32 s26, s25, 0x180
	v_or_b32_e32 v174, 0x1c000, v156
	v_or_b32_e32 v176, 0x1c000, v158
	s_addc_u32 s27, s28, 0
	v_readfirstlane_b32 s25, v150
	v_or_b32_e32 v175, 0x1c000, v157
	ds_read_b128 v[236:239], v174
	ds_read_b128 v[240:243], v175
	v_or_b32_e32 v177, 0x1c000, v159
	ds_read_b128 v[244:247], v176
	ds_read_b128 v[248:251], v177
	s_mov_b32 m0, s25
	v_lshl_add_u64 v[216:217], s[26:27], 0, v[132:133]
	v_readfirstlane_b32 s25, v151
	global_load_lds_dwordx4 v[216:217], off
	v_lshl_add_u64 v[216:217], s[26:27], 0, v[130:131]
	s_mov_b32 m0, s25
	s_nop 0
	global_load_lds_dwordx4 v[216:217], off
	s_barrier
	s_waitcnt lgkmcnt(0)
	s_setprio 1
	s_waitcnt lgkmcnt(0)
	v_mfma_f32_16x16x32_bf16 v[94:97], v[194:197], v[236:239], v[94:97]
	v_mfma_f32_16x16x32_bf16 v[90:93], v[194:197], v[244:247], v[90:93]
	v_mfma_f32_16x16x32_bf16 v[86:89], v[202:205], v[236:239], v[86:89]
	v_mfma_f32_16x16x32_bf16 v[82:85], v[202:205], v[244:247], v[82:85]
	v_mfma_f32_16x16x32_bf16 v[78:81], v[212:215], v[236:239], v[78:81]
	v_mfma_f32_16x16x32_bf16 v[74:77], v[212:215], v[244:247], v[74:77]
	v_mfma_f32_16x16x32_bf16 v[70:73], v[228:231], v[236:239], v[70:73]
	v_mfma_f32_16x16x32_bf16 v[66:69], v[228:231], v[244:247], v[66:69]
	v_mfma_f32_16x16x32_bf16 v[94:97], v[198:201], v[240:243], v[94:97]
	v_mfma_f32_16x16x32_bf16 v[90:93], v[198:201], v[248:251], v[90:93]
	v_mfma_f32_16x16x32_bf16 v[86:89], v[206:209], v[240:243], v[86:89]
	v_mfma_f32_16x16x32_bf16 v[82:85], v[206:209], v[248:251], v[82:85]
	v_mfma_f32_16x16x32_bf16 v[78:81], v[224:227], v[240:243], v[78:81]
	v_mfma_f32_16x16x32_bf16 v[74:77], v[224:227], v[248:251], v[74:77]
	v_mfma_f32_16x16x32_bf16 v[70:73], v[232:235], v[240:243], v[70:73]
	v_mfma_f32_16x16x32_bf16 v[66:69], v[232:235], v[248:251], v[66:69]
	s_setprio 0
	s_add_u32 s26, s29, 0x180
	s_addc_u32 s27, s30, 0
	v_readfirstlane_b32 s25, v152
	s_barrier
	ds_read_b128 v[194:197], v140 offset:49152
	ds_read_b128 v[198:201], v140 offset:50176
	ds_read_b128 v[202:205], v143 offset:49152
	ds_read_b128 v[206:209], v143 offset:50176
	ds_read_b128 v[212:215], v142 offset:49152
	ds_read_b128 v[224:227], v142 offset:50176
	ds_read_b128 v[228:231], v141 offset:49152
	ds_read_b128 v[232:235], v141 offset:50176
	s_mov_b32 m0, s25
	v_lshl_add_u64 v[216:217], s[26:27], 0, v[132:133]
	v_readfirstlane_b32 s25, v153
	global_load_lds_dwordx4 v[216:217], off
	v_lshl_add_u64 v[216:217], s[26:27], 0, v[130:131]
	s_mov_b32 m0, s25
	s_nop 0
	global_load_lds_dwordx4 v[216:217], off
	s_barrier
	s_waitcnt lgkmcnt(0)
	s_setprio 1
	s_waitcnt lgkmcnt(0)
	v_mfma_f32_16x16x32_bf16 v[62:65], v[194:197], v[178:181], v[62:65]
	v_mfma_f32_16x16x32_bf16 v[58:61], v[194:197], v[186:189], v[58:61]
	v_mfma_f32_16x16x32_bf16 v[54:57], v[202:205], v[178:181], v[54:57]
	v_mfma_f32_16x16x32_bf16 v[50:53], v[202:205], v[186:189], v[50:53]
	v_mfma_f32_16x16x32_bf16 v[46:49], v[212:215], v[178:181], v[46:49]
	v_mfma_f32_16x16x32_bf16 v[42:45], v[212:215], v[186:189], v[42:45]
	v_mfma_f32_16x16x32_bf16 v[38:41], v[228:231], v[178:181], v[38:41]
	v_mfma_f32_16x16x32_bf16 v[34:37], v[228:231], v[186:189], v[34:37]
	v_mfma_f32_16x16x32_bf16 v[62:65], v[198:201], v[182:185], v[62:65]
	v_mfma_f32_16x16x32_bf16 v[58:61], v[198:201], v[190:193], v[58:61]
	v_mfma_f32_16x16x32_bf16 v[54:57], v[206:209], v[182:185], v[54:57]
	v_mfma_f32_16x16x32_bf16 v[50:53], v[206:209], v[190:193], v[50:53]
	v_mfma_f32_16x16x32_bf16 v[46:49], v[224:227], v[182:185], v[46:49]
	v_mfma_f32_16x16x32_bf16 v[42:45], v[224:227], v[190:193], v[42:45]
	v_mfma_f32_16x16x32_bf16 v[38:41], v[232:235], v[182:185], v[38:41]
	v_mfma_f32_16x16x32_bf16 v[34:37], v[232:235], v[190:193], v[34:37]
	s_setprio 0
	s_barrier
	s_add_u32 s26, s31, 0x180
	s_addc_u32 s27, s34, 0
	v_readfirstlane_b32 s25, v154
	s_mov_b32 m0, s25
	v_lshl_add_u64 v[178:179], s[26:27], 0, v[132:133]
	v_readfirstlane_b32 s25, v155
	global_load_lds_dwordx4 v[178:179], off
	v_lshl_add_u64 v[178:179], s[26:27], 0, v[130:131]
	s_mov_b32 m0, s25
	s_nop 0
	global_load_lds_dwordx4 v[178:179], off
	s_waitcnt vmcnt(6)
	s_barrier
	s_setprio 1
	v_mfma_f32_16x16x32_bf16 v[30:33], v[194:197], v[236:239], v[30:33]
	v_mfma_f32_16x16x32_bf16 v[26:29], v[194:197], v[244:247], v[26:29]
	v_mfma_f32_16x16x32_bf16 v[22:25], v[202:205], v[236:239], v[22:25]
	v_mfma_f32_16x16x32_bf16 v[18:21], v[202:205], v[244:247], v[18:21]
	v_mfma_f32_16x16x32_bf16 v[14:17], v[212:215], v[236:239], v[14:17]
	v_mfma_f32_16x16x32_bf16 v[10:13], v[212:215], v[244:247], v[10:13]
	v_mfma_f32_16x16x32_bf16 v[6:9], v[228:231], v[236:239], v[6:9]
	v_mfma_f32_16x16x32_bf16 v[2:5], v[228:231], v[244:247], v[2:5]
	v_mfma_f32_16x16x32_bf16 v[30:33], v[198:201], v[240:243], v[30:33]
	v_mfma_f32_16x16x32_bf16 v[26:29], v[198:201], v[248:251], v[26:29]
	v_mfma_f32_16x16x32_bf16 v[22:25], v[206:209], v[240:243], v[22:25]
	v_mfma_f32_16x16x32_bf16 v[18:21], v[206:209], v[248:251], v[18:21]
	v_mfma_f32_16x16x32_bf16 v[14:17], v[224:227], v[240:243], v[14:17]
	v_mfma_f32_16x16x32_bf16 v[10:13], v[224:227], v[248:251], v[10:13]
	v_mfma_f32_16x16x32_bf16 v[6:9], v[232:235], v[240:243], v[6:9]
	v_mfma_f32_16x16x32_bf16 v[2:5], v[232:235], v[248:251], v[2:5]
	s_setprio 0
	s_add_i32 s24, s24, 2
	s_add_u32 s14, s14, 0x100
	s_addc_u32 s15, s15, 0
	s_cmp_lt_u32 s24, 28
	s_barrier
	s_cbranch_scc1 .LBB0_709
	s_add_u32 s6, s12, 0xf80
	s_addc_u32 s7, s13, 0
	v_readfirstlane_b32 s1, v164
	ds_read_b128 v[144:147], v160
	ds_read_b128 v[148:151], v161
	ds_read_b128 v[152:155], v162
	ds_read_b128 v[156:159], v163
	ds_read_b128 v[160:163], v140
	ds_read_b128 v[178:181], v140 offset:1024
	ds_read_b128 v[182:185], v143
	ds_read_b128 v[186:189], v143 offset:1024
	ds_read_b128 v[190:193], v142
	ds_read_b128 v[194:197], v142 offset:1024
	ds_read_b128 v[198:201], v141
	ds_read_b128 v[202:205], v141 offset:1024
	s_mov_b32 m0, s1
	v_lshl_add_u64 v[132:133], s[6:7], 0, v[132:133]
	v_readfirstlane_b32 s1, v165
	global_load_lds_dwordx4 v[132:133], off
	v_lshl_add_u64 v[130:131], s[6:7], 0, v[130:131]
	s_mov_b32 m0, s1
	s_nop 0
	global_load_lds_dwordx4 v[130:131], off
	s_barrier
	s_waitcnt lgkmcnt(0)
	s_setprio 1
	s_waitcnt lgkmcnt(0)
	v_mfma_f32_16x16x32_bf16 v[126:129], v[160:163], v[144:147], v[126:129]
	v_mfma_f32_16x16x32_bf16 v[122:125], v[160:163], v[152:155], v[122:125]
	v_mfma_f32_16x16x32_bf16 v[118:121], v[182:185], v[144:147], v[118:121]
	v_mfma_f32_16x16x32_bf16 v[114:117], v[182:185], v[152:155], v[114:117]
	v_mfma_f32_16x16x32_bf16 v[110:113], v[190:193], v[144:147], v[110:113]
	v_mfma_f32_16x16x32_bf16 v[106:109], v[190:193], v[152:155], v[106:109]
	v_mfma_f32_16x16x32_bf16 v[98:101], v[198:201], v[152:155], v[98:101]
	v_mfma_f32_16x16x32_bf16 v[126:129], v[178:181], v[148:151], v[126:129]
	v_mfma_f32_16x16x32_bf16 v[122:125], v[178:181], v[156:159], v[122:125]
	v_mfma_f32_16x16x32_bf16 v[118:121], v[186:189], v[148:151], v[118:121]
	v_mfma_f32_16x16x32_bf16 v[114:117], v[186:189], v[156:159], v[114:117]
	v_mfma_f32_16x16x32_bf16 v[110:113], v[194:197], v[148:151], v[110:113]
	v_mfma_f32_16x16x32_bf16 v[106:109], v[194:197], v[156:159], v[106:109]
	v_mfma_f32_16x16x32_bf16 v[102:105], v[198:201], v[144:147], v[102:105]
	v_mfma_f32_16x16x32_bf16 v[98:101], v[202:205], v[156:159], v[98:101]
	v_mfma_f32_16x16x32_bf16 v[130:133], v[202:205], v[148:151], v[102:105]
	s_setprio 0
	s_barrier
	s_nop 2
	ds_read_b128 v[102:105], v166
	ds_read_b128 v[164:167], v167
	ds_read_b128 v[206:209], v168
	ds_read_b128 v[212:215], v169
	s_barrier
	s_waitcnt lgkmcnt(0)
	s_setprio 1
	s_waitcnt lgkmcnt(1)
	v_mfma_f32_16x16x32_bf16 v[90:93], v[160:163], v[206:209], v[90:93]
	v_mfma_f32_16x16x32_bf16 v[94:97], v[160:163], v[102:105], v[94:97]
	s_waitcnt lgkmcnt(0)
	v_mfma_f32_16x16x32_bf16 v[90:93], v[178:181], v[212:215], v[90:93]
	v_mfma_f32_16x16x32_bf16 v[86:89], v[182:185], v[102:105], v[86:89]
	v_mfma_f32_16x16x32_bf16 v[82:85], v[182:185], v[206:209], v[82:85]
	v_mfma_f32_16x16x32_bf16 v[78:81], v[190:193], v[102:105], v[78:81]
	v_mfma_f32_16x16x32_bf16 v[74:77], v[190:193], v[206:209], v[74:77]
	v_mfma_f32_16x16x32_bf16 v[70:73], v[198:201], v[102:105], v[70:73]
	v_mfma_f32_16x16x32_bf16 v[66:69], v[198:201], v[206:209], v[66:69]
	v_mfma_f32_16x16x32_bf16 v[224:227], v[178:181], v[164:167], v[94:97]
	v_mfma_f32_16x16x32_bf16 v[160:163], v[186:189], v[164:167], v[86:89]
	v_mfma_f32_16x16x32_bf16 v[178:181], v[186:189], v[212:215], v[82:85]
	v_mfma_f32_16x16x32_bf16 v[182:185], v[194:197], v[164:167], v[78:81]
	v_mfma_f32_16x16x32_bf16 v[186:189], v[194:197], v[212:215], v[74:77]
	v_mfma_f32_16x16x32_bf16 v[190:193], v[202:205], v[164:167], v[70:73]
	v_mfma_f32_16x16x32_bf16 v[194:197], v[202:205], v[212:215], v[66:69]
	s_setprio 0
	s_barrier
	s_nop 0
	ds_read_b128 v[66:69], v140 offset:16384
	ds_read_b128 v[70:73], v140 offset:17408
	ds_read_b128 v[74:77], v143 offset:16384
	ds_read_b128 v[78:81], v143 offset:17408
	ds_read_b128 v[82:85], v142 offset:16384
	ds_read_b128 v[86:89], v142 offset:17408
	ds_read_b128 v[94:97], v141 offset:16384
	ds_read_b128 v[198:201], v141 offset:17408
	s_waitcnt vmcnt(4)
	s_barrier
	s_waitcnt lgkmcnt(0)
	s_setprio 1
	s_waitcnt lgkmcnt(7)
	v_mfma_f32_16x16x32_bf16 v[62:65], v[66:69], v[144:147], v[62:65]
	v_mfma_f32_16x16x32_bf16 v[58:61], v[66:69], v[152:155], v[58:61]
	s_waitcnt lgkmcnt(5)
	v_mfma_f32_16x16x32_bf16 v[54:57], v[74:77], v[144:147], v[54:57]
	v_mfma_f32_16x16x32_bf16 v[50:53], v[74:77], v[152:155], v[50:53]
	s_waitcnt lgkmcnt(3)
	v_mfma_f32_16x16x32_bf16 v[46:49], v[82:85], v[144:147], v[46:49]
	v_mfma_f32_16x16x32_bf16 v[42:45], v[82:85], v[152:155], v[42:45]
	s_waitcnt lgkmcnt(1)
	v_mfma_f32_16x16x32_bf16 v[38:41], v[94:97], v[144:147], v[38:41]
	v_mfma_f32_16x16x32_bf16 v[34:37], v[94:97], v[152:155], v[34:37]
	v_mfma_f32_16x16x32_bf16 v[62:65], v[70:73], v[148:151], v[62:65]
	v_mfma_f32_16x16x32_bf16 v[58:61], v[70:73], v[156:159], v[58:61]
	v_mfma_f32_16x16x32_bf16 v[54:57], v[78:81], v[148:151], v[54:57]
	v_mfma_f32_16x16x32_bf16 v[50:53], v[78:81], v[156:159], v[50:53]
	v_mfma_f32_16x16x32_bf16 v[46:49], v[86:89], v[148:151], v[46:49]
	v_mfma_f32_16x16x32_bf16 v[42:45], v[86:89], v[156:159], v[42:45]
	s_waitcnt lgkmcnt(0)
	v_mfma_f32_16x16x32_bf16 v[38:41], v[198:201], v[148:151], v[38:41]
	v_mfma_f32_16x16x32_bf16 v[34:37], v[198:201], v[156:159], v[34:37]
	s_setprio 0
	s_setprio 1
	v_mfma_f32_16x16x32_bf16 v[30:33], v[66:69], v[102:105], v[30:33]
	v_mfma_f32_16x16x32_bf16 v[26:29], v[66:69], v[206:209], v[26:29]
	v_mfma_f32_16x16x32_bf16 v[22:25], v[74:77], v[102:105], v[22:25]
	v_mfma_f32_16x16x32_bf16 v[18:21], v[74:77], v[206:209], v[18:21]
	v_mfma_f32_16x16x32_bf16 v[14:17], v[82:85], v[102:105], v[14:17]
	v_mfma_f32_16x16x32_bf16 v[10:13], v[82:85], v[206:209], v[10:13]
	v_mfma_f32_16x16x32_bf16 v[6:9], v[94:97], v[102:105], v[6:9]
	v_mfma_f32_16x16x32_bf16 v[2:5], v[94:97], v[206:209], v[2:5]
	v_mfma_f32_16x16x32_bf16 v[144:147], v[70:73], v[164:167], v[30:33]
	v_mfma_f32_16x16x32_bf16 v[148:151], v[70:73], v[212:215], v[26:29]
	v_mfma_f32_16x16x32_bf16 v[152:155], v[78:81], v[164:167], v[22:25]
	v_mfma_f32_16x16x32_bf16 v[156:159], v[78:81], v[212:215], v[18:21]
	v_mfma_f32_16x16x32_bf16 v[202:205], v[86:89], v[164:167], v[14:17]
	v_mfma_f32_16x16x32_bf16 v[228:231], v[86:89], v[212:215], v[10:13]
	v_mfma_f32_16x16x32_bf16 v[164:167], v[198:201], v[164:167], v[6:9]
	v_mfma_f32_16x16x32_bf16 v[198:201], v[198:201], v[212:215], v[2:5]
	s_setprio 0
	s_barrier
	s_nop 0
	ds_read_b128 v[2:5], v170
	ds_read_b128 v[6:9], v171
	ds_read_b128 v[168:171], v172
	ds_read_b128 v[206:209], v173
	ds_read_b128 v[10:13], v140 offset:32768
	ds_read_b128 v[14:17], v140 offset:33792
	ds_read_b128 v[18:21], v143 offset:32768
	ds_read_b128 v[22:25], v143 offset:33792
	ds_read_b128 v[26:29], v142 offset:32768
	ds_read_b128 v[30:33], v142 offset:33792
	ds_read_b128 v[212:215], v141 offset:32768
	ds_read_b128 v[232:235], v141 offset:33792
	s_waitcnt vmcnt(2)
	s_barrier
	s_waitcnt lgkmcnt(0)
	s_setprio 1
	s_waitcnt lgkmcnt(7)
	v_mfma_f32_16x16x32_bf16 v[66:69], v[10:13], v[2:5], v[126:129]
	s_waitcnt lgkmcnt(6)
	v_mfma_f32_16x16x32_bf16 v[94:97], v[14:17], v[6:9], v[66:69]
	v_mfma_f32_16x16x32_bf16 v[66:69], v[10:13], v[168:171], v[122:125]
	v_mfma_f32_16x16x32_bf16 v[102:105], v[14:17], v[206:209], v[66:69]
	s_waitcnt lgkmcnt(5)
	v_mfma_f32_16x16x32_bf16 v[66:69], v[18:21], v[2:5], v[118:121]
	s_waitcnt lgkmcnt(4)
	v_mfma_f32_16x16x32_bf16 v[82:85], v[22:25], v[6:9], v[66:69]
	v_mfma_f32_16x16x32_bf16 v[66:69], v[18:21], v[168:171], v[114:117]
	v_mfma_f32_16x16x32_bf16 v[86:89], v[22:25], v[206:209], v[66:69]
	s_waitcnt lgkmcnt(3)
	v_mfma_f32_16x16x32_bf16 v[66:69], v[26:29], v[2:5], v[110:113]
	s_waitcnt lgkmcnt(2)
	v_mfma_f32_16x16x32_bf16 v[74:77], v[30:33], v[6:9], v[66:69]
	v_mfma_f32_16x16x32_bf16 v[66:69], v[26:29], v[168:171], v[106:109]
	v_mfma_f32_16x16x32_bf16 v[78:81], v[30:33], v[206:209], v[66:69]
	s_waitcnt lgkmcnt(1)
	v_mfma_f32_16x16x32_bf16 v[66:69], v[212:215], v[2:5], v[130:133]
	v_mfma_f32_16x16x32_bf16 v[70:73], v[212:215], v[168:171], v[98:101]
	s_waitcnt lgkmcnt(0)
	v_mfma_f32_16x16x32_bf16 v[66:69], v[232:235], v[6:9], v[66:69]
	v_mfma_f32_16x16x32_bf16 v[70:73], v[232:235], v[206:209], v[70:73]
	s_setprio 0
	s_barrier
	ds_read_b128 v[130:133], v174
	ds_read_b128 v[172:175], v175
	ds_read_b128 v[236:239], v176
	ds_read_b128 v[240:243], v177
	s_waitcnt vmcnt(0)
	s_barrier
	s_waitcnt lgkmcnt(0)
	s_setprio 1
	s_waitcnt lgkmcnt(3)
	v_mfma_f32_16x16x32_bf16 v[98:101], v[10:13], v[130:133], v[224:227]
	s_waitcnt lgkmcnt(1)
	v_mfma_f32_16x16x32_bf16 v[10:13], v[10:13], v[236:239], v[90:93]
	s_waitcnt lgkmcnt(0)
	v_mfma_f32_16x16x32_bf16 v[126:129], v[14:17], v[240:243], v[10:13]
	v_mfma_f32_16x16x32_bf16 v[10:13], v[18:21], v[130:133], v[160:163]
	v_mfma_f32_16x16x32_bf16 v[114:117], v[22:25], v[172:175], v[10:13]
	v_mfma_f32_16x16x32_bf16 v[10:13], v[18:21], v[236:239], v[178:181]
	v_mfma_f32_16x16x32_bf16 v[118:121], v[22:25], v[240:243], v[10:13]
	v_mfma_f32_16x16x32_bf16 v[10:13], v[26:29], v[130:133], v[182:185]
	v_mfma_f32_16x16x32_bf16 v[106:109], v[30:33], v[172:175], v[10:13]
	v_mfma_f32_16x16x32_bf16 v[10:13], v[26:29], v[236:239], v[186:189]
	v_mfma_f32_16x16x32_bf16 v[110:113], v[30:33], v[240:243], v[10:13]
	v_mfma_f32_16x16x32_bf16 v[10:13], v[212:215], v[130:133], v[190:193]
	v_mfma_f32_16x16x32_bf16 v[90:93], v[232:235], v[172:175], v[10:13]
	v_mfma_f32_16x16x32_bf16 v[10:13], v[212:215], v[236:239], v[194:197]
	v_mfma_f32_16x16x32_bf16 v[122:125], v[14:17], v[172:175], v[98:101]
	v_mfma_f32_16x16x32_bf16 v[98:101], v[232:235], v[240:243], v[10:13]
	s_setprio 0
	s_barrier
	ds_read_b128 v[160:163], v140 offset:49152
	ds_read_b128 v[176:179], v140 offset:50176
	ds_read_b128 v[180:183], v143 offset:49152
	ds_read_b128 v[184:187], v143 offset:50176
	ds_read_b128 v[188:191], v142 offset:49152
	ds_read_b128 v[192:195], v142 offset:50176
	ds_read_b128 v[212:215], v141 offset:49152
	ds_read_b128 v[138:141], v141 offset:50176
	s_barrier
	s_waitcnt lgkmcnt(0)
	s_setprio 1
	s_waitcnt lgkmcnt(7)
	v_mfma_f32_16x16x32_bf16 v[10:13], v[160:163], v[2:5], v[62:65]
	s_waitcnt lgkmcnt(6)
	v_mfma_f32_16x16x32_bf16 v[26:29], v[176:179], v[6:9], v[10:13]
	v_mfma_f32_16x16x32_bf16 v[10:13], v[160:163], v[168:171], v[58:61]
	v_mfma_f32_16x16x32_bf16 v[30:33], v[176:179], v[206:209], v[10:13]
	s_waitcnt lgkmcnt(5)
	v_mfma_f32_16x16x32_bf16 v[10:13], v[180:183], v[2:5], v[54:57]
	s_waitcnt lgkmcnt(4)
	v_mfma_f32_16x16x32_bf16 v[18:21], v[184:187], v[6:9], v[10:13]
	v_mfma_f32_16x16x32_bf16 v[10:13], v[180:183], v[168:171], v[50:53]
	v_mfma_f32_16x16x32_bf16 v[22:25], v[184:187], v[206:209], v[10:13]
	s_waitcnt lgkmcnt(3)
	v_mfma_f32_16x16x32_bf16 v[10:13], v[188:191], v[2:5], v[46:49]
	s_waitcnt lgkmcnt(1)
	v_mfma_f32_16x16x32_bf16 v[2:5], v[212:215], v[2:5], v[38:41]
	v_mfma_f32_16x16x32_bf16 v[10:13], v[192:195], v[6:9], v[10:13]
	v_mfma_f32_16x16x32_bf16 v[14:17], v[188:191], v[168:171], v[42:45]
	s_waitcnt lgkmcnt(0)
	v_mfma_f32_16x16x32_bf16 v[2:5], v[138:141], v[6:9], v[2:5]
	v_mfma_f32_16x16x32_bf16 v[6:9], v[212:215], v[168:171], v[34:37]
	v_mfma_f32_16x16x32_bf16 v[14:17], v[192:195], v[206:209], v[14:17]
	v_mfma_f32_16x16x32_bf16 v[6:9], v[138:141], v[206:209], v[6:9]
	s_setprio 0
	s_setprio 1
	v_mfma_f32_16x16x32_bf16 v[34:37], v[160:163], v[130:133], v[144:147]
	v_mfma_f32_16x16x32_bf16 v[58:61], v[176:179], v[172:175], v[34:37]
	v_mfma_f32_16x16x32_bf16 v[34:37], v[160:163], v[236:239], v[148:151]
	v_mfma_f32_16x16x32_bf16 v[62:65], v[176:179], v[240:243], v[34:37]
	v_mfma_f32_16x16x32_bf16 v[34:37], v[180:183], v[130:133], v[152:155]
	v_mfma_f32_16x16x32_bf16 v[50:53], v[184:187], v[172:175], v[34:37]
	v_mfma_f32_16x16x32_bf16 v[34:37], v[180:183], v[236:239], v[156:159]
	v_mfma_f32_16x16x32_bf16 v[54:57], v[184:187], v[240:243], v[34:37]
	v_mfma_f32_16x16x32_bf16 v[34:37], v[188:191], v[130:133], v[202:205]
	v_mfma_f32_16x16x32_bf16 v[42:45], v[192:195], v[172:175], v[34:37]
	v_mfma_f32_16x16x32_bf16 v[34:37], v[188:191], v[236:239], v[228:231]
	v_mfma_f32_16x16x32_bf16 v[46:49], v[192:195], v[240:243], v[34:37]
	v_mfma_f32_16x16x32_bf16 v[34:37], v[212:215], v[130:133], v[164:167]
	v_mfma_f32_16x16x32_bf16 v[38:41], v[212:215], v[236:239], v[198:201]
	v_mfma_f32_16x16x32_bf16 v[34:37], v[138:141], v[172:175], v[34:37]
	v_mfma_f32_16x16x32_bf16 v[38:41], v[138:141], v[240:243], v[38:41]
	s_setprio 0
	s_movk_i32 s1, 0x100
	v_cmp_gt_u32_e32 vcc, s1, v1
	s_barrier
	s_and_saveexec_b64 s[6:7], vcc
	s_cbranch_execz .LBB0_712
	s_barrier
.LBB0_712:
	s_or_b64 exec, exec, s[6:7]
	v_lshlrev_b32_e32 v133, 2, v135
	v_lshl_or_b32 v131, v136, 2, v137
	v_lshl_or_b32 v134, v134, 7, v133
	v_mov_b32_e32 v1, v210
	v_mad_u64_u32 v[134:135], s[6:7], v131, s96, v[134:135]
	s_barrier
	ds_write2_b32 v134, v94, v102 offset1:16
	ds_write2_b32 v134, v122, v126 offset0:128 offset1:144
	v_add_u32_e32 v94, 0x400, v134
	ds_write2_b32 v94, v95, v103 offset0:4 offset1:20
	ds_write2_b32 v94, v123, v127 offset0:132 offset1:148
	v_add_u32_e32 v95, 0x800, v134
	ds_write2_b32 v95, v96, v104 offset0:8 offset1:24
	ds_write2_b32 v95, v124, v128 offset0:136 offset1:152
	v_add_u32_e32 v96, 0xc00, v134
	ds_write2_b32 v96, v97, v105 offset0:12 offset1:28
	ds_write2_b32 v96, v125, v129 offset0:140 offset1:156
	v_add_u32_e32 v97, 0x4000, v134
	ds_write2_b32 v97, v82, v86 offset0:64 offset1:80
	ds_write2_b32 v97, v114, v118 offset0:192 offset1:208
	v_add_u32_e32 v82, 0x4400, v134
	ds_write2_b32 v82, v83, v87 offset0:68 offset1:84
	ds_write2_b32 v82, v115, v119 offset0:196 offset1:212
	v_add_u32_e32 v83, 0x4800, v134
	ds_write2_b32 v83, v84, v88 offset0:72 offset1:88
	ds_write2_b32 v83, v116, v120 offset0:200 offset1:216
	v_add_u32_e32 v84, 0x4c00, v134
	ds_write2_b32 v84, v85, v89 offset0:76 offset1:92
	ds_write2_b32 v84, v117, v121 offset0:204 offset1:220
	v_add_u32_e32 v85, 0x8000, v134
	ds_write2_b32 v85, v74, v78 offset0:128 offset1:144
	v_add_u32_e32 v74, 0x8400, v134
	ds_write2_b32 v74, v106, v110 offset1:16
	ds_write2_b32 v74, v75, v79 offset0:132 offset1:148
	v_add_u32_e32 v75, 0x8800, v134
	ds_write2_b32 v75, v107, v111 offset0:4 offset1:20
	ds_write2_b32 v75, v76, v80 offset0:136 offset1:152
	v_add_u32_e32 v76, 0x8c00, v134
	v_add_u32_e32 v78, 0xc000, v134
	v_readlane_b32 s1, v254, 60
	v_lshlrev_b32_e32 v130, 2, v1
	ds_write2_b32 v76, v108, v112 offset0:8 offset1:24
	ds_write2_b32 v76, v77, v81 offset0:140 offset1:156
	v_add_u32_e32 v77, 0x9000, v134
	ds_write2_b32 v78, v66, v70 offset0:192 offset1:208
	v_add_u32_e32 v70, 0xc400, v134
	s_add_i32 s1, s0, s1
	s_lshl_b64 s[4:5], s[4:5], 2
	v_readlane_b32 s8, v254, 37
	v_and_b32_e32 v132, 0xfc, v130
	ds_write2_b32 v77, v109, v113 offset0:12 offset1:28
	ds_write2_b32 v70, v90, v98 offset0:64 offset1:80
	ds_write2_b32 v70, v67, v71 offset0:196 offset1:212
	v_add_u32_e32 v71, 0xc800, v134
	v_readlane_b32 s9, v254, 38
	s_add_u32 s6, s8, s4
	v_lshlrev_b32_e32 v130, 2, v132
	ds_write2_b32 v71, v91, v99 offset0:68 offset1:84
	ds_write2_b32 v71, v68, v72 offset0:200 offset1:216
	v_add_u32_e32 v72, 0xcc00, v134
	s_addc_u32 s7, s9, s5
	v_mov_b32_e32 v131, v0
	ds_write2_b32 v72, v92, v100 offset0:72 offset1:88
	ds_write2_b32 v72, v69, v73 offset0:204 offset1:220
	v_add_u32_e32 v73, 0xd000, v134
	v_lshl_add_u64 v[66:67], s[6:7], 0, v[130:131]
	s_mov_b32 s6, 0
	ds_write2_b32 v73, v93, v101 offset0:76 offset1:92
	s_waitcnt lgkmcnt(0)
	s_barrier
	v_readlane_b32 s10, v254, 39
	v_readlane_b32 s11, v254, 40
	v_readfirstlane_b32 s8, v66
	v_readfirstlane_b32 s9, v67
	v_lshrrev_b32_e32 v81, 6, v1
	v_lshlrev_b32_e32 v80, 12, v81
	v_or_b32_e32 v79, v80, v130
	v_mov_b32_e32 v80, v79
	v_mad_u32_u24 v81, v81, s96, v130
	s_nop 3
	s_lshl_b32 s6, s1, 12
	s_add_u32 s8, s8, s6
	s_addc_u32 s9, s9, 0
	s_cmp_lt_i32 s1, s85
	s_cselect_b32 s6, s48, s50
	s_cselect_b32 s7, s49, s51
	s_cselect_b32 vcc_lo, 0, s85
	s_sub_i32 vcc_lo, s1, vcc_lo
	s_lshl_b32 vcc_lo, vcc_lo, 12
	s_add_u32 s6, s6, vcc_lo
	s_addc_u32 s7, s7, 0
	s_add_u32 s6, s6, s4
	s_addc_u32 s7, s7, s5
	global_load_dwordx4 v[98:101], v79, s[6:7]
	v_add_u32_e32 v79, 0x8000, v79
	global_load_dwordx4 v[102:105], v79, s[6:7]
	v_add_u32_e32 v79, 0x8000, v79
	global_load_dwordx4 v[106:109], v79, s[6:7]
	v_add_u32_e32 v79, 0x8000, v79
	global_load_dwordx4 v[110:113], v79, s[6:7]
	v_add_u32_e32 v79, 0x8000, v79
	global_load_dwordx4 v[114:117], v79, s[6:7]
	v_add_u32_e32 v79, 0x8000, v79
	global_load_dwordx4 v[118:121], v79, s[6:7]
	v_add_u32_e32 v79, 0x8000, v79
	global_load_dwordx4 v[122:125], v79, s[6:7]
	v_add_u32_e32 v79, 0x8000, v79
	global_load_dwordx4 v[126:129], v79, s[6:7]
	v_add_u32_e32 v79, 0x8000, v79
	ds_read_b128 v[86:89], v81
	ds_read_b128 v[90:93], v81 offset:8320
	s_waitcnt vmcnt(7) lgkmcnt(1)
	v_pk_add_f32 v[86:87], v[86:87], v[98:99]
	v_pk_add_f32 v[88:89], v[88:89], v[100:101]
	global_store_dwordx4 v80, v[86:89], s[8:9]
	v_add_u32_e32 v80, 0x8000, v80
	global_load_dwordx4 v[98:101], v79, s[6:7]
	v_add_u32_e32 v79, 0x8000, v79
	ds_read_b128 v[86:89], v81 offset:16640
	s_waitcnt vmcnt(8) lgkmcnt(1)
	v_pk_add_f32 v[90:91], v[90:91], v[102:103]
	v_pk_add_f32 v[92:93], v[92:93], v[104:105]
	global_store_dwordx4 v80, v[90:93], s[8:9]
	v_add_u32_e32 v80, 0x8000, v80
	global_load_dwordx4 v[102:105], v79, s[6:7]
	v_add_u32_e32 v79, 0x8000, v79
	ds_read_b128 v[90:93], v81 offset:24960
	s_waitcnt vmcnt(9) lgkmcnt(1)
	v_pk_add_f32 v[86:87], v[86:87], v[106:107]
	v_pk_add_f32 v[88:89], v[88:89], v[108:109]
	global_store_dwordx4 v80, v[86:89], s[8:9]
	v_add_u32_e32 v80, 0x8000, v80
	global_load_dwordx4 v[106:109], v79, s[6:7]
	v_add_u32_e32 v79, 0x8000, v79
	ds_read_b128 v[86:89], v81 offset:33280
	s_waitcnt vmcnt(10) lgkmcnt(1)
	v_pk_add_f32 v[90:91], v[90:91], v[110:111]
	v_pk_add_f32 v[92:93], v[92:93], v[112:113]
	global_store_dwordx4 v80, v[90:93], s[8:9]
	v_add_u32_e32 v80, 0x8000, v80
	global_load_dwordx4 v[110:113], v79, s[6:7]
	v_add_u32_e32 v79, 0x8000, v79
	ds_read_b128 v[90:93], v81 offset:41600
	s_waitcnt vmcnt(11) lgkmcnt(1)
	v_pk_add_f32 v[86:87], v[86:87], v[114:115]
	v_pk_add_f32 v[88:89], v[88:89], v[116:117]
	global_store_dwordx4 v80, v[86:89], s[8:9]
	v_add_u32_e32 v80, 0x8000, v80
	global_load_dwordx4 v[114:117], v79, s[6:7]
	v_add_u32_e32 v79, 0x8000, v79
	ds_read_b128 v[86:89], v81 offset:49920
	s_waitcnt vmcnt(12) lgkmcnt(1)
	v_pk_add_f32 v[90:91], v[90:91], v[118:119]
	v_pk_add_f32 v[92:93], v[92:93], v[120:121]
	global_store_dwordx4 v80, v[90:93], s[8:9]
	v_add_u32_e32 v80, 0x8000, v80
	global_load_dwordx4 v[118:121], v79, s[6:7]
	v_add_u32_e32 v79, 0x8000, v79
	ds_read_b128 v[90:93], v81 offset:58240
	s_waitcnt vmcnt(13) lgkmcnt(1)
	v_pk_add_f32 v[86:87], v[86:87], v[122:123]
	v_pk_add_f32 v[88:89], v[88:89], v[124:125]
	global_store_dwordx4 v80, v[86:89], s[8:9]
	v_add_u32_e32 v80, 0x8000, v80
	global_load_dwordx4 v[122:125], v79, s[6:7]
	v_add_u32_e32 v79, 0x8000, v79
	v_add_u32_e32 v81, 0x10400, v81
	ds_read_b128 v[86:89], v81
	s_waitcnt vmcnt(14) lgkmcnt(1)
	v_pk_add_f32 v[90:91], v[90:91], v[126:127]
	v_pk_add_f32 v[92:93], v[92:93], v[128:129]
	global_store_dwordx4 v80, v[90:93], s[8:9]
	v_add_u32_e32 v80, 0x8000, v80
	global_load_dwordx4 v[126:129], v79, s[6:7]
	v_add_u32_e32 v79, 0x8000, v79
	ds_read_b128 v[90:93], v81 offset:8320
	s_waitcnt vmcnt(14) lgkmcnt(1)
	v_pk_add_f32 v[86:87], v[86:87], v[98:99]
	v_pk_add_f32 v[88:89], v[88:89], v[100:101]
	global_store_dwordx4 v80, v[86:89], s[8:9]
	v_add_u32_e32 v80, 0x8000, v80
	global_load_dwordx4 v[98:101], v79, s[6:7]
	v_add_u32_e32 v79, 0x8000, v79
	ds_read_b128 v[86:89], v81 offset:16640
	s_waitcnt vmcnt(14) lgkmcnt(1)
	v_pk_add_f32 v[90:91], v[90:91], v[102:103]
	v_pk_add_f32 v[92:93], v[92:93], v[104:105]
	global_store_dwordx4 v80, v[90:93], s[8:9]
	v_add_u32_e32 v80, 0x8000, v80
	global_load_dwordx4 v[102:105], v79, s[6:7]
	v_add_u32_e32 v79, 0x8000, v79
	ds_read_b128 v[90:93], v81 offset:24960
	s_waitcnt vmcnt(14) lgkmcnt(1)
	v_pk_add_f32 v[86:87], v[86:87], v[106:107]
	v_pk_add_f32 v[88:89], v[88:89], v[108:109]
	global_store_dwordx4 v80, v[86:89], s[8:9]
	v_add_u32_e32 v80, 0x8000, v80
	global_load_dwordx4 v[106:109], v79, s[6:7]
	v_add_u32_e32 v79, 0x8000, v79
	ds_read_b128 v[86:89], v81 offset:33280
	s_waitcnt vmcnt(14) lgkmcnt(1)
	v_pk_add_f32 v[90:91], v[90:91], v[110:111]
	v_pk_add_f32 v[92:93], v[92:93], v[112:113]
	global_store_dwordx4 v80, v[90:93], s[8:9]
	v_add_u32_e32 v80, 0x8000, v80
	global_load_dwordx4 v[110:113], v79, s[6:7]
	v_add_u32_e32 v79, 0x8000, v79
	ds_read_b128 v[90:93], v81 offset:41600
	s_waitcnt vmcnt(14) lgkmcnt(1)
	v_pk_add_f32 v[86:87], v[86:87], v[114:115]
	v_pk_add_f32 v[88:89], v[88:89], v[116:117]
	global_store_dwordx4 v80, v[86:89], s[8:9]
	v_add_u32_e32 v80, 0x8000, v80
	global_load_dwordx4 v[114:117], v79, s[6:7]
	v_add_u32_e32 v79, 0x8000, v79
	ds_read_b128 v[86:89], v81 offset:49920
	s_waitcnt vmcnt(14) lgkmcnt(1)
	v_pk_add_f32 v[90:91], v[90:91], v[118:119]
	v_pk_add_f32 v[92:93], v[92:93], v[120:121]
	global_store_dwordx4 v80, v[90:93], s[8:9]
	v_add_u32_e32 v80, 0x8000, v80
	global_load_dwordx4 v[118:121], v79, s[6:7]
	v_add_u32_e32 v79, 0x8000, v79
	ds_read_b128 v[90:93], v81 offset:58240
	s_waitcnt vmcnt(14) lgkmcnt(1)
	v_pk_add_f32 v[86:87], v[86:87], v[122:123]
	v_pk_add_f32 v[88:89], v[88:89], v[124:125]
	global_store_dwordx4 v80, v[86:89], s[8:9]
	v_add_u32_e32 v80, 0x8000, v80
	global_load_dwordx4 v[122:125], v79, s[6:7]
	v_add_u32_e32 v79, 0x8000, v79
	s_waitcnt vmcnt(14) lgkmcnt(0)
	v_pk_add_f32 v[90:91], v[90:91], v[126:127]
	v_pk_add_f32 v[92:93], v[92:93], v[128:129]
	global_store_dwordx4 v80, v[90:93], s[8:9]
	v_add_u32_e32 v80, 0x8000, v80
	global_load_dwordx4 v[126:129], v79, s[6:7]
	v_add_u32_e32 v79, 0x8000, v79
	v_readlane_b32 s1, v254, 61
	s_add_i32 s0, s1, s0
	s_mov_b32 s1, 0
	s_barrier
	ds_write2_b32 v134, v26, v30 offset1:16
	ds_write2_b32 v134, v58, v62 offset0:128 offset1:144
	ds_write2_b32 v94, v27, v31 offset0:4 offset1:20
	ds_write2_b32 v94, v59, v63 offset0:132 offset1:148
	ds_write2_b32 v95, v28, v32 offset0:8 offset1:24
	ds_write2_b32 v95, v60, v64 offset0:136 offset1:152
	ds_write2_b32 v96, v29, v33 offset0:12 offset1:28
	ds_write2_b32 v96, v61, v65 offset0:140 offset1:156
	ds_write2_b32 v97, v18, v22 offset0:64 offset1:80
	ds_write2_b32 v97, v50, v54 offset0:192 offset1:208
	ds_write2_b32 v82, v19, v23 offset0:68 offset1:84
	ds_write2_b32 v82, v51, v55 offset0:196 offset1:212
	ds_write2_b32 v83, v20, v24 offset0:72 offset1:88
	ds_write2_b32 v83, v52, v56 offset0:200 offset1:216
	ds_write2_b32 v84, v21, v25 offset0:76 offset1:92
	ds_write2_b32 v84, v53, v57 offset0:204 offset1:220
	ds_write2_b32 v85, v10, v14 offset0:128 offset1:144
	ds_write2_b32 v74, v42, v46 offset1:16
	ds_write2_b32 v74, v11, v15 offset0:132 offset1:148
	ds_write2_b32 v75, v43, v47 offset0:4 offset1:20
	ds_write2_b32 v75, v12, v16 offset0:136 offset1:152
	ds_write2_b32 v76, v44, v48 offset0:8 offset1:24
	ds_write2_b32 v76, v13, v17 offset0:140 offset1:156
	ds_write2_b32 v77, v45, v49 offset0:12 offset1:28
	ds_write2_b32 v78, v2, v6 offset0:192 offset1:208
	ds_write2_b32 v70, v34, v38 offset0:64 offset1:80
	ds_write2_b32 v70, v3, v7 offset0:196 offset1:212
	ds_write2_b32 v71, v35, v39 offset0:68 offset1:84
	ds_write2_b32 v71, v4, v8 offset0:200 offset1:216
	ds_write2_b32 v72, v36, v40 offset0:72 offset1:88
	ds_write2_b32 v72, v5, v9 offset0:204 offset1:220
	ds_write2_b32 v73, v37, v41 offset0:76 offset1:92
	s_waitcnt lgkmcnt(0)
	s_barrier
	v_add_u32_e32 v81, 0xfffefc00, v81
	ds_read_b128 v[86:89], v81
	ds_read_b128 v[90:93], v81 offset:8320
	s_waitcnt vmcnt(14) lgkmcnt(1)
	v_pk_add_f32 v[86:87], v[86:87], v[98:99]
	v_pk_add_f32 v[88:89], v[88:89], v[100:101]
	global_store_dwordx4 v80, v[86:89], s[8:9]
	v_add_u32_e32 v80, 0x8000, v80
	global_load_dwordx4 v[98:101], v79, s[6:7]
	v_add_u32_e32 v79, 0x8000, v79
	ds_read_b128 v[86:89], v81 offset:16640
	s_waitcnt vmcnt(14) lgkmcnt(1)
	v_pk_add_f32 v[90:91], v[90:91], v[102:103]
	v_pk_add_f32 v[92:93], v[92:93], v[104:105]
	global_store_dwordx4 v80, v[90:93], s[8:9]
	v_add_u32_e32 v80, 0x8000, v80
	global_load_dwordx4 v[102:105], v79, s[6:7]
	v_add_u32_e32 v79, 0x8000, v79
	ds_read_b128 v[90:93], v81 offset:24960
	s_waitcnt vmcnt(14) lgkmcnt(1)
	v_pk_add_f32 v[86:87], v[86:87], v[106:107]
	v_pk_add_f32 v[88:89], v[88:89], v[108:109]
	global_store_dwordx4 v80, v[86:89], s[8:9]
	v_add_u32_e32 v80, 0x8000, v80
	global_load_dwordx4 v[106:109], v79, s[6:7]
	v_add_u32_e32 v79, 0x8000, v79
	ds_read_b128 v[86:89], v81 offset:33280
	s_waitcnt vmcnt(14) lgkmcnt(1)
	v_pk_add_f32 v[90:91], v[90:91], v[110:111]
	v_pk_add_f32 v[92:93], v[92:93], v[112:113]
	global_store_dwordx4 v80, v[90:93], s[8:9]
	v_add_u32_e32 v80, 0x8000, v80
	global_load_dwordx4 v[110:113], v79, s[6:7]
	v_add_u32_e32 v79, 0x8000, v79
	ds_read_b128 v[90:93], v81 offset:41600
	s_waitcnt vmcnt(14) lgkmcnt(1)
	v_pk_add_f32 v[86:87], v[86:87], v[114:115]
	v_pk_add_f32 v[88:89], v[88:89], v[116:117]
	global_store_dwordx4 v80, v[86:89], s[8:9]
	v_add_u32_e32 v80, 0x8000, v80
	global_load_dwordx4 v[114:117], v79, s[6:7]
	v_add_u32_e32 v79, 0x8000, v79
	ds_read_b128 v[86:89], v81 offset:49920
	s_waitcnt vmcnt(14) lgkmcnt(1)
	v_pk_add_f32 v[90:91], v[90:91], v[118:119]
	v_pk_add_f32 v[92:93], v[92:93], v[120:121]
	global_store_dwordx4 v80, v[90:93], s[8:9]
	v_add_u32_e32 v80, 0x8000, v80
	global_load_dwordx4 v[118:121], v79, s[6:7]
	v_add_u32_e32 v79, 0x8000, v79
	ds_read_b128 v[90:93], v81 offset:58240
	s_waitcnt vmcnt(14) lgkmcnt(1)
	v_pk_add_f32 v[86:87], v[86:87], v[122:123]
	v_pk_add_f32 v[88:89], v[88:89], v[124:125]
	global_store_dwordx4 v80, v[86:89], s[8:9]
	v_add_u32_e32 v80, 0x8000, v80
	global_load_dwordx4 v[122:125], v79, s[6:7]
	v_add_u32_e32 v79, 0x8000, v79
	v_add_u32_e32 v81, 0x10400, v81
	ds_read_b128 v[86:89], v81
	s_waitcnt vmcnt(14) lgkmcnt(1)
	v_pk_add_f32 v[90:91], v[90:91], v[126:127]
	v_pk_add_f32 v[92:93], v[92:93], v[128:129]
	global_store_dwordx4 v80, v[90:93], s[8:9]
	v_add_u32_e32 v80, 0x8000, v80
	global_load_dwordx4 v[126:129], v79, s[6:7]
	v_add_u32_e32 v79, 0x8000, v79
	ds_read_b128 v[90:93], v81 offset:8320
	s_waitcnt vmcnt(14) lgkmcnt(1)
	v_pk_add_f32 v[86:87], v[86:87], v[98:99]
	v_pk_add_f32 v[88:89], v[88:89], v[100:101]
	global_store_dwordx4 v80, v[86:89], s[8:9]
	v_add_u32_e32 v80, 0x8000, v80
	s_nop 0
	ds_read_b128 v[86:89], v81 offset:16640
	s_waitcnt vmcnt(13) lgkmcnt(1)
	v_pk_add_f32 v[90:91], v[90:91], v[102:103]
	v_pk_add_f32 v[92:93], v[92:93], v[104:105]
	global_store_dwordx4 v80, v[90:93], s[8:9]
	v_add_u32_e32 v80, 0x8000, v80
	s_nop 0
	ds_read_b128 v[90:93], v81 offset:24960
	s_waitcnt vmcnt(12) lgkmcnt(1)
	v_pk_add_f32 v[86:87], v[86:87], v[106:107]
	v_pk_add_f32 v[88:89], v[88:89], v[108:109]
	global_store_dwordx4 v80, v[86:89], s[8:9]
	v_add_u32_e32 v80, 0x8000, v80
	s_nop 0
	ds_read_b128 v[86:89], v81 offset:33280
	s_waitcnt vmcnt(11) lgkmcnt(1)
	v_pk_add_f32 v[90:91], v[90:91], v[110:111]
	v_pk_add_f32 v[92:93], v[92:93], v[112:113]
	global_store_dwordx4 v80, v[90:93], s[8:9]
	v_add_u32_e32 v80, 0x8000, v80
	s_nop 0
	ds_read_b128 v[90:93], v81 offset:41600
	s_waitcnt vmcnt(10) lgkmcnt(1)
	v_pk_add_f32 v[86:87], v[86:87], v[114:115]
	v_pk_add_f32 v[88:89], v[88:89], v[116:117]
	global_store_dwordx4 v80, v[86:89], s[8:9]
	v_add_u32_e32 v80, 0x8000, v80
	s_nop 0
	ds_read_b128 v[86:89], v81 offset:49920
	s_waitcnt vmcnt(9) lgkmcnt(1)
	v_pk_add_f32 v[90:91], v[90:91], v[118:119]
	v_pk_add_f32 v[92:93], v[92:93], v[120:121]
	global_store_dwordx4 v80, v[90:93], s[8:9]
	v_add_u32_e32 v80, 0x8000, v80
	s_nop 0
	ds_read_b128 v[90:93], v81 offset:58240
	s_waitcnt vmcnt(8) lgkmcnt(1)
	v_pk_add_f32 v[86:87], v[86:87], v[122:123]
	v_pk_add_f32 v[88:89], v[88:89], v[124:125]
	global_store_dwordx4 v80, v[86:89], s[8:9]
	v_add_u32_e32 v80, 0x8000, v80
	s_nop 0
	s_waitcnt vmcnt(7) lgkmcnt(0)
	v_pk_add_f32 v[90:91], v[90:91], v[126:127]
	v_pk_add_f32 v[92:93], v[92:93], v[128:129]
	global_store_dwordx4 v80, v[90:93], s[8:9]
	v_add_u32_e32 v80, 0x8000, v80
	s_nop 0
	s_add_i32 s18, s18, s74
	s_cmpk_lt_i32 s18, 0x200
	s_cbranch_scc1 .LBB0_701
	s_branch .LBB0_718

.LBB0_847:
	v_or_b32_e32 v160, 0x10000, v156
	v_or_b32_e32 v162, 0x10000, v158
	v_or_b32_e32 v161, 0x10000, v157
	ds_read_b128 v[170:173], v160
	ds_read_b128 v[174:177], v161
	v_or_b32_e32 v163, 0x10000, v159
	ds_read_b128 v[178:181], v162
	ds_read_b128 v[182:185], v163
	s_add_u32 s36, s19, s16
	s_addc_u32 s37, s34, s17
	s_add_u32 s36, s36, 0x80
	v_add_u32_e32 v164, 0xc000, v137
	s_addc_u32 s37, s37, 0
	v_readfirstlane_b32 s38, v164
	ds_read_b128 v[186:189], v140
	ds_read_b128 v[190:193], v140 offset:1024
	ds_read_b128 v[194:197], v143
	ds_read_b128 v[198:201], v143 offset:1024
	ds_read_b128 v[202:205], v142
	ds_read_b128 v[206:209], v142 offset:1024
	ds_read_b128 v[212:215], v141
	ds_read_b128 v[224:227], v141 offset:1024
	s_mov_b32 m0, s38
	v_lshl_add_u64 v[166:167], s[36:37], 0, v[132:133]
	v_add_u32_e32 v165, 0xe000, v137
	global_load_lds_dwordx4 v[166:167], off
	v_lshl_add_u64 v[166:167], s[36:37], 0, v[130:131]
	v_readfirstlane_b32 s36, v165
	s_mov_b32 m0, s36
	s_nop 0
	global_load_lds_dwordx4 v[166:167], off
	s_waitcnt lgkmcnt(8)
	s_barrier
	s_waitcnt lgkmcnt(0)
	s_setprio 1
	s_waitcnt lgkmcnt(0)
	v_mfma_f32_16x16x32_bf16 v[126:129], v[186:189], v[170:173], v[126:129]
	v_mfma_f32_16x16x32_bf16 v[122:125], v[186:189], v[178:181], v[122:125]
	v_mfma_f32_16x16x32_bf16 v[118:121], v[194:197], v[170:173], v[118:121]
	v_mfma_f32_16x16x32_bf16 v[114:117], v[194:197], v[178:181], v[114:117]
	v_mfma_f32_16x16x32_bf16 v[110:113], v[202:205], v[170:173], v[110:113]
	v_mfma_f32_16x16x32_bf16 v[106:109], v[202:205], v[178:181], v[106:109]
	v_mfma_f32_16x16x32_bf16 v[102:105], v[212:215], v[170:173], v[102:105]
	v_mfma_f32_16x16x32_bf16 v[98:101], v[212:215], v[178:181], v[98:101]
	v_mfma_f32_16x16x32_bf16 v[126:129], v[190:193], v[174:177], v[126:129]
	v_mfma_f32_16x16x32_bf16 v[122:125], v[190:193], v[182:185], v[122:125]
	v_mfma_f32_16x16x32_bf16 v[118:121], v[198:201], v[174:177], v[118:121]
	v_mfma_f32_16x16x32_bf16 v[114:117], v[198:201], v[182:185], v[114:117]
	v_mfma_f32_16x16x32_bf16 v[110:113], v[206:209], v[174:177], v[110:113]
	v_mfma_f32_16x16x32_bf16 v[106:109], v[206:209], v[182:185], v[106:109]
	v_mfma_f32_16x16x32_bf16 v[102:105], v[224:227], v[174:177], v[102:105]
	v_mfma_f32_16x16x32_bf16 v[98:101], v[224:227], v[182:185], v[98:101]
	s_setprio 0
	s_barrier
	s_add_u32 s38, s8, s16
	s_addc_u32 s39, s9, s17
	s_add_u32 s36, s38, 0x100
	v_or_b32_e32 v166, 0x14000, v156
	v_or_b32_e32 v168, 0x14000, v158
	s_addc_u32 s37, s39, 0
	v_readfirstlane_b32 s40, v144
	v_or_b32_e32 v167, 0x14000, v157
	ds_read_b128 v[228:231], v166
	ds_read_b128 v[232:235], v167
	v_or_b32_e32 v169, 0x14000, v159
	ds_read_b128 v[236:239], v168
	ds_read_b128 v[240:243], v169
	s_mov_b32 m0, s40
	v_lshl_add_u64 v[216:217], s[36:37], 0, v[132:133]
	global_load_lds_dwordx4 v[216:217], off
	v_lshl_add_u64 v[216:217], s[36:37], 0, v[130:131]
	v_readfirstlane_b32 s36, v145
	s_mov_b32 m0, s36
	s_nop 0
	global_load_lds_dwordx4 v[216:217], off
	s_barrier
	s_waitcnt lgkmcnt(0)
	s_setprio 1
	s_waitcnt lgkmcnt(0)
	v_mfma_f32_16x16x32_bf16 v[94:97], v[186:189], v[228:231], v[94:97]
	v_mfma_f32_16x16x32_bf16 v[90:93], v[186:189], v[236:239], v[90:93]
	v_mfma_f32_16x16x32_bf16 v[86:89], v[194:197], v[228:231], v[86:89]
	v_mfma_f32_16x16x32_bf16 v[82:85], v[194:197], v[236:239], v[82:85]
	v_mfma_f32_16x16x32_bf16 v[78:81], v[202:205], v[228:231], v[78:81]
	v_mfma_f32_16x16x32_bf16 v[74:77], v[202:205], v[236:239], v[74:77]
	v_mfma_f32_16x16x32_bf16 v[70:73], v[212:215], v[228:231], v[70:73]
	v_mfma_f32_16x16x32_bf16 v[66:69], v[212:215], v[236:239], v[66:69]
	v_mfma_f32_16x16x32_bf16 v[94:97], v[190:193], v[232:235], v[94:97]
	v_mfma_f32_16x16x32_bf16 v[90:93], v[190:193], v[240:243], v[90:93]
	v_mfma_f32_16x16x32_bf16 v[86:89], v[198:201], v[232:235], v[86:89]
	v_mfma_f32_16x16x32_bf16 v[82:85], v[198:201], v[240:243], v[82:85]
	v_mfma_f32_16x16x32_bf16 v[78:81], v[206:209], v[232:235], v[78:81]
	v_mfma_f32_16x16x32_bf16 v[74:77], v[206:209], v[240:243], v[74:77]
	v_mfma_f32_16x16x32_bf16 v[70:73], v[224:227], v[232:235], v[70:73]
	v_mfma_f32_16x16x32_bf16 v[66:69], v[224:227], v[240:243], v[66:69]
	s_setprio 0
	s_add_u32 s40, s10, s16
	s_addc_u32 s41, s11, s17
	s_add_u32 s36, s40, 0x100
	s_addc_u32 s37, s41, 0
	v_readfirstlane_b32 s42, v137
	s_barrier
	ds_read_b128 v[186:189], v140 offset:16384
	ds_read_b128 v[190:193], v140 offset:17408
	ds_read_b128 v[194:197], v143 offset:16384
	ds_read_b128 v[198:201], v143 offset:17408
	ds_read_b128 v[202:205], v142 offset:16384
	ds_read_b128 v[206:209], v142 offset:17408
	ds_read_b128 v[212:215], v141 offset:16384
	ds_read_b128 v[224:227], v141 offset:17408
	s_mov_b32 m0, s42
	v_lshl_add_u64 v[216:217], s[36:37], 0, v[132:133]
	global_load_lds_dwordx4 v[216:217], off
	v_lshl_add_u64 v[216:217], s[36:37], 0, v[130:131]
	v_readfirstlane_b32 s36, v138
	s_mov_b32 m0, s36
	s_nop 0
	global_load_lds_dwordx4 v[216:217], off
	s_barrier
	s_waitcnt lgkmcnt(0)
	s_setprio 1
	s_waitcnt lgkmcnt(0)
	v_mfma_f32_16x16x32_bf16 v[62:65], v[186:189], v[170:173], v[62:65]
	v_mfma_f32_16x16x32_bf16 v[58:61], v[186:189], v[178:181], v[58:61]
	v_mfma_f32_16x16x32_bf16 v[54:57], v[194:197], v[170:173], v[54:57]
	v_mfma_f32_16x16x32_bf16 v[50:53], v[194:197], v[178:181], v[50:53]
	v_mfma_f32_16x16x32_bf16 v[46:49], v[202:205], v[170:173], v[46:49]
	v_mfma_f32_16x16x32_bf16 v[42:45], v[202:205], v[178:181], v[42:45]
	v_mfma_f32_16x16x32_bf16 v[38:41], v[212:215], v[170:173], v[38:41]
	v_mfma_f32_16x16x32_bf16 v[34:37], v[212:215], v[178:181], v[34:37]
	v_mfma_f32_16x16x32_bf16 v[62:65], v[190:193], v[174:177], v[62:65]
	v_mfma_f32_16x16x32_bf16 v[58:61], v[190:193], v[182:185], v[58:61]
	v_mfma_f32_16x16x32_bf16 v[54:57], v[198:201], v[174:177], v[54:57]
	v_mfma_f32_16x16x32_bf16 v[50:53], v[198:201], v[182:185], v[50:53]
	v_mfma_f32_16x16x32_bf16 v[46:49], v[206:209], v[174:177], v[46:49]
	v_mfma_f32_16x16x32_bf16 v[42:45], v[206:209], v[182:185], v[42:45]
	v_mfma_f32_16x16x32_bf16 v[38:41], v[224:227], v[174:177], v[38:41]
	v_mfma_f32_16x16x32_bf16 v[34:37], v[224:227], v[182:185], v[34:37]
	s_setprio 0
	s_barrier
	s_add_u32 s42, s12, s16
	s_addc_u32 s43, s13, s17
	s_add_u32 s36, s42, 0x100
	s_addc_u32 s37, s43, 0
	v_readfirstlane_b32 s44, v146
	s_mov_b32 m0, s44
	v_lshl_add_u64 v[170:171], s[36:37], 0, v[132:133]
	global_load_lds_dwordx4 v[170:171], off
	v_lshl_add_u64 v[170:171], s[36:37], 0, v[130:131]
	v_readfirstlane_b32 s36, v147
	s_mov_b32 m0, s36
	s_nop 0
	global_load_lds_dwordx4 v[170:171], off
	s_waitcnt vmcnt(6)
	s_barrier
	s_setprio 1
	v_mfma_f32_16x16x32_bf16 v[30:33], v[186:189], v[228:231], v[30:33]
	v_mfma_f32_16x16x32_bf16 v[26:29], v[186:189], v[236:239], v[26:29]
	v_mfma_f32_16x16x32_bf16 v[22:25], v[194:197], v[228:231], v[22:25]
	v_mfma_f32_16x16x32_bf16 v[18:21], v[194:197], v[236:239], v[18:21]
	v_mfma_f32_16x16x32_bf16 v[14:17], v[202:205], v[228:231], v[14:17]
	v_mfma_f32_16x16x32_bf16 v[10:13], v[202:205], v[236:239], v[10:13]
	v_mfma_f32_16x16x32_bf16 v[6:9], v[212:215], v[228:231], v[6:9]
	v_mfma_f32_16x16x32_bf16 v[2:5], v[212:215], v[236:239], v[2:5]
	v_mfma_f32_16x16x32_bf16 v[30:33], v[190:193], v[232:235], v[30:33]
	v_mfma_f32_16x16x32_bf16 v[26:29], v[190:193], v[240:243], v[26:29]
	v_mfma_f32_16x16x32_bf16 v[22:25], v[198:201], v[232:235], v[22:25]
	v_mfma_f32_16x16x32_bf16 v[18:21], v[198:201], v[240:243], v[18:21]
	v_mfma_f32_16x16x32_bf16 v[14:17], v[206:209], v[232:235], v[14:17]
	v_mfma_f32_16x16x32_bf16 v[10:13], v[206:209], v[240:243], v[10:13]
	v_mfma_f32_16x16x32_bf16 v[6:9], v[224:227], v[232:235], v[6:9]
	v_mfma_f32_16x16x32_bf16 v[2:5], v[224:227], v[240:243], v[2:5]
	s_setprio 0
	v_or_b32_e32 v170, 0x18000, v156
	v_or_b32_e32 v172, 0x18000, v158
	s_barrier
	v_or_b32_e32 v171, 0x18000, v157
	ds_read_b128 v[178:181], v170
	ds_read_b128 v[182:185], v171
	v_or_b32_e32 v173, 0x18000, v159
	ds_read_b128 v[186:189], v172
	ds_read_b128 v[190:193], v173
	s_add_u32 s36, s5, s16
	s_addc_u32 s37, s18, s17
	v_readfirstlane_b32 s44, v148
	ds_read_b128 v[194:197], v140 offset:32768
	ds_read_b128 v[198:201], v140 offset:33792
	ds_read_b128 v[202:205], v143 offset:32768
	ds_read_b128 v[206:209], v143 offset:33792
	ds_read_b128 v[212:215], v142 offset:32768
	ds_read_b128 v[224:227], v142 offset:33792
	ds_read_b128 v[228:231], v141 offset:32768
	ds_read_b128 v[232:235], v141 offset:33792
	s_mov_b32 m0, s44
	v_lshl_add_u64 v[174:175], s[36:37], 0, v[132:133]
	global_load_lds_dwordx4 v[174:175], off
	v_lshl_add_u64 v[174:175], s[36:37], 0, v[130:131]
	v_readfirstlane_b32 s36, v149
	s_mov_b32 m0, s36
	s_nop 0
	global_load_lds_dwordx4 v[174:175], off
	s_waitcnt lgkmcnt(8)
	s_barrier
	s_waitcnt lgkmcnt(0)
	s_setprio 1
	s_waitcnt lgkmcnt(0)
	v_mfma_f32_16x16x32_bf16 v[126:129], v[194:197], v[178:181], v[126:129]
	v_mfma_f32_16x16x32_bf16 v[122:125], v[194:197], v[186:189], v[122:125]
	v_mfma_f32_16x16x32_bf16 v[118:121], v[202:205], v[178:181], v[118:121]
	v_mfma_f32_16x16x32_bf16 v[114:117], v[202:205], v[186:189], v[114:117]
	v_mfma_f32_16x16x32_bf16 v[110:113], v[212:215], v[178:181], v[110:113]
	v_mfma_f32_16x16x32_bf16 v[106:109], v[212:215], v[186:189], v[106:109]
	v_mfma_f32_16x16x32_bf16 v[102:105], v[228:231], v[178:181], v[102:105]
	v_mfma_f32_16x16x32_bf16 v[98:101], v[228:231], v[186:189], v[98:101]
	v_mfma_f32_16x16x32_bf16 v[126:129], v[198:201], v[182:185], v[126:129]
	v_mfma_f32_16x16x32_bf16 v[122:125], v[198:201], v[190:193], v[122:125]
	v_mfma_f32_16x16x32_bf16 v[118:121], v[206:209], v[182:185], v[118:121]
	v_mfma_f32_16x16x32_bf16 v[114:117], v[206:209], v[190:193], v[114:117]
	v_mfma_f32_16x16x32_bf16 v[110:113], v[224:227], v[182:185], v[110:113]
	v_mfma_f32_16x16x32_bf16 v[106:109], v[224:227], v[190:193], v[106:109]
	v_mfma_f32_16x16x32_bf16 v[102:105], v[232:235], v[182:185], v[102:105]
	v_mfma_f32_16x16x32_bf16 v[98:101], v[232:235], v[190:193], v[98:101]
	s_setprio 0
	s_barrier
	s_add_u32 s36, s38, 0x180
	v_or_b32_e32 v174, 0x1c000, v156
	v_or_b32_e32 v176, 0x1c000, v158
	s_addc_u32 s37, s39, 0
	v_readfirstlane_b32 s38, v150
	v_or_b32_e32 v175, 0x1c000, v157
	ds_read_b128 v[236:239], v174
	ds_read_b128 v[240:243], v175
	v_or_b32_e32 v177, 0x1c000, v159
	ds_read_b128 v[244:247], v176
	ds_read_b128 v[248:251], v177
	s_mov_b32 m0, s38
	v_lshl_add_u64 v[216:217], s[36:37], 0, v[132:133]
	global_load_lds_dwordx4 v[216:217], off
	v_lshl_add_u64 v[216:217], s[36:37], 0, v[130:131]
	v_readfirstlane_b32 s36, v151
	s_mov_b32 m0, s36
	s_nop 0
	global_load_lds_dwordx4 v[216:217], off
	s_barrier
	s_waitcnt lgkmcnt(0)
	s_setprio 1
	s_waitcnt lgkmcnt(0)
	v_mfma_f32_16x16x32_bf16 v[94:97], v[194:197], v[236:239], v[94:97]
	v_mfma_f32_16x16x32_bf16 v[90:93], v[194:197], v[244:247], v[90:93]
	v_mfma_f32_16x16x32_bf16 v[86:89], v[202:205], v[236:239], v[86:89]
	v_mfma_f32_16x16x32_bf16 v[82:85], v[202:205], v[244:247], v[82:85]
	v_mfma_f32_16x16x32_bf16 v[78:81], v[212:215], v[236:239], v[78:81]
	v_mfma_f32_16x16x32_bf16 v[74:77], v[212:215], v[244:247], v[74:77]
	v_mfma_f32_16x16x32_bf16 v[70:73], v[228:231], v[236:239], v[70:73]
	v_mfma_f32_16x16x32_bf16 v[66:69], v[228:231], v[244:247], v[66:69]
	v_mfma_f32_16x16x32_bf16 v[94:97], v[198:201], v[240:243], v[94:97]
	v_mfma_f32_16x16x32_bf16 v[90:93], v[198:201], v[248:251], v[90:93]
	v_mfma_f32_16x16x32_bf16 v[86:89], v[206:209], v[240:243], v[86:89]
	v_mfma_f32_16x16x32_bf16 v[82:85], v[206:209], v[248:251], v[82:85]
	v_mfma_f32_16x16x32_bf16 v[78:81], v[224:227], v[240:243], v[78:81]
	v_mfma_f32_16x16x32_bf16 v[74:77], v[224:227], v[248:251], v[74:77]
	v_mfma_f32_16x16x32_bf16 v[70:73], v[232:235], v[240:243], v[70:73]
	v_mfma_f32_16x16x32_bf16 v[66:69], v[232:235], v[248:251], v[66:69]
	s_setprio 0
	s_add_u32 s36, s40, 0x180
	s_addc_u32 s37, s41, 0
	v_readfirstlane_b32 s38, v152
	s_barrier
	ds_read_b128 v[194:197], v140 offset:49152
	ds_read_b128 v[198:201], v140 offset:50176
	ds_read_b128 v[202:205], v143 offset:49152
	ds_read_b128 v[206:209], v143 offset:50176
	ds_read_b128 v[212:215], v142 offset:49152
	ds_read_b128 v[224:227], v142 offset:50176
	ds_read_b128 v[228:231], v141 offset:49152
	ds_read_b128 v[232:235], v141 offset:50176
	s_mov_b32 m0, s38
	v_lshl_add_u64 v[216:217], s[36:37], 0, v[132:133]
	global_load_lds_dwordx4 v[216:217], off
	v_lshl_add_u64 v[216:217], s[36:37], 0, v[130:131]
	v_readfirstlane_b32 s36, v153
	s_mov_b32 m0, s36
	s_nop 0
	global_load_lds_dwordx4 v[216:217], off
	s_barrier
	s_waitcnt lgkmcnt(0)
	s_setprio 1
	s_waitcnt lgkmcnt(0)
	v_mfma_f32_16x16x32_bf16 v[62:65], v[194:197], v[178:181], v[62:65]
	v_mfma_f32_16x16x32_bf16 v[58:61], v[194:197], v[186:189], v[58:61]
	v_mfma_f32_16x16x32_bf16 v[54:57], v[202:205], v[178:181], v[54:57]
	v_mfma_f32_16x16x32_bf16 v[50:53], v[202:205], v[186:189], v[50:53]
	v_mfma_f32_16x16x32_bf16 v[46:49], v[212:215], v[178:181], v[46:49]
	v_mfma_f32_16x16x32_bf16 v[42:45], v[212:215], v[186:189], v[42:45]
	v_mfma_f32_16x16x32_bf16 v[38:41], v[228:231], v[178:181], v[38:41]
	v_mfma_f32_16x16x32_bf16 v[34:37], v[228:231], v[186:189], v[34:37]
	v_mfma_f32_16x16x32_bf16 v[62:65], v[198:201], v[182:185], v[62:65]
	v_mfma_f32_16x16x32_bf16 v[58:61], v[198:201], v[190:193], v[58:61]
	v_mfma_f32_16x16x32_bf16 v[54:57], v[206:209], v[182:185], v[54:57]
	v_mfma_f32_16x16x32_bf16 v[50:53], v[206:209], v[190:193], v[50:53]
	v_mfma_f32_16x16x32_bf16 v[46:49], v[224:227], v[182:185], v[46:49]
	v_mfma_f32_16x16x32_bf16 v[42:45], v[224:227], v[190:193], v[42:45]
	v_mfma_f32_16x16x32_bf16 v[38:41], v[232:235], v[182:185], v[38:41]
	v_mfma_f32_16x16x32_bf16 v[34:37], v[232:235], v[190:193], v[34:37]
	s_setprio 0
	s_barrier
	s_add_u32 s36, s42, 0x180
	s_addc_u32 s37, s43, 0
	v_readfirstlane_b32 s38, v154
	s_mov_b32 m0, s38
	v_lshl_add_u64 v[178:179], s[36:37], 0, v[132:133]
	global_load_lds_dwordx4 v[178:179], off
	v_lshl_add_u64 v[178:179], s[36:37], 0, v[130:131]
	v_readfirstlane_b32 s36, v155
	s_mov_b32 m0, s36
	s_nop 0
	global_load_lds_dwordx4 v[178:179], off
	s_waitcnt vmcnt(6)
	s_barrier
	s_setprio 1
	v_mfma_f32_16x16x32_bf16 v[30:33], v[194:197], v[236:239], v[30:33]
	v_mfma_f32_16x16x32_bf16 v[26:29], v[194:197], v[244:247], v[26:29]
	v_mfma_f32_16x16x32_bf16 v[22:25], v[202:205], v[236:239], v[22:25]
	v_mfma_f32_16x16x32_bf16 v[18:21], v[202:205], v[244:247], v[18:21]
	v_mfma_f32_16x16x32_bf16 v[14:17], v[212:215], v[236:239], v[14:17]
	v_mfma_f32_16x16x32_bf16 v[10:13], v[212:215], v[244:247], v[10:13]
	v_mfma_f32_16x16x32_bf16 v[6:9], v[228:231], v[236:239], v[6:9]
	v_mfma_f32_16x16x32_bf16 v[2:5], v[228:231], v[244:247], v[2:5]
	v_mfma_f32_16x16x32_bf16 v[30:33], v[198:201], v[240:243], v[30:33]
	v_mfma_f32_16x16x32_bf16 v[26:29], v[198:201], v[248:251], v[26:29]
	v_mfma_f32_16x16x32_bf16 v[22:25], v[206:209], v[240:243], v[22:25]
	v_mfma_f32_16x16x32_bf16 v[18:21], v[206:209], v[248:251], v[18:21]
	v_mfma_f32_16x16x32_bf16 v[14:17], v[224:227], v[240:243], v[14:17]
	v_mfma_f32_16x16x32_bf16 v[10:13], v[224:227], v[248:251], v[10:13]
	v_mfma_f32_16x16x32_bf16 v[6:9], v[232:235], v[240:243], v[6:9]
	v_mfma_f32_16x16x32_bf16 v[2:5], v[232:235], v[248:251], v[2:5]
	s_setprio 0
	s_add_i32 s35, s35, 2
	s_add_u32 s16, s16, 0x100
	s_addc_u32 s17, s17, 0
	s_cmp_lt_u32 s35, 12
	s_barrier
	s_cbranch_scc1 .LBB0_847
	s_add_u32 s8, s14, 0x780
	s_addc_u32 s9, s15, 0
	v_readfirstlane_b32 s5, v164
	ds_read_b128 v[144:147], v160
	ds_read_b128 v[148:151], v161
	ds_read_b128 v[152:155], v162
	ds_read_b128 v[156:159], v163
	ds_read_b128 v[160:163], v140
	ds_read_b128 v[178:181], v140 offset:1024
	ds_read_b128 v[182:185], v143
	ds_read_b128 v[186:189], v143 offset:1024
	ds_read_b128 v[190:193], v142
	ds_read_b128 v[194:197], v142 offset:1024
	ds_read_b128 v[198:201], v141
	ds_read_b128 v[202:205], v141 offset:1024
	s_mov_b32 m0, s5
	v_lshl_add_u64 v[132:133], s[8:9], 0, v[132:133]
	v_readfirstlane_b32 s5, v165
	global_load_lds_dwordx4 v[132:133], off
	v_lshl_add_u64 v[130:131], s[8:9], 0, v[130:131]
	s_mov_b32 m0, s5
	s_nop 0
	global_load_lds_dwordx4 v[130:131], off
	s_barrier
	s_waitcnt lgkmcnt(0)
	s_setprio 1
	s_waitcnt lgkmcnt(0)
	v_mfma_f32_16x16x32_bf16 v[126:129], v[160:163], v[144:147], v[126:129]
	v_mfma_f32_16x16x32_bf16 v[122:125], v[160:163], v[152:155], v[122:125]
	v_mfma_f32_16x16x32_bf16 v[110:113], v[190:193], v[144:147], v[110:113]
	v_mfma_f32_16x16x32_bf16 v[106:109], v[190:193], v[152:155], v[106:109]
	v_mfma_f32_16x16x32_bf16 v[126:129], v[178:181], v[148:151], v[126:129]
	v_mfma_f32_16x16x32_bf16 v[122:125], v[178:181], v[156:159], v[122:125]
	v_mfma_f32_16x16x32_bf16 v[118:121], v[182:185], v[144:147], v[118:121]
	v_mfma_f32_16x16x32_bf16 v[114:117], v[182:185], v[152:155], v[114:117]
	v_mfma_f32_16x16x32_bf16 v[110:113], v[194:197], v[148:151], v[110:113]
	v_mfma_f32_16x16x32_bf16 v[106:109], v[194:197], v[156:159], v[106:109]
	v_mfma_f32_16x16x32_bf16 v[102:105], v[198:201], v[144:147], v[102:105]
	v_mfma_f32_16x16x32_bf16 v[98:101], v[198:201], v[152:155], v[98:101]
	v_mfma_f32_16x16x32_bf16 v[130:133], v[186:189], v[148:151], v[118:121]
	v_mfma_f32_16x16x32_bf16 v[206:209], v[186:189], v[156:159], v[114:117]
	v_mfma_f32_16x16x32_bf16 v[212:215], v[202:205], v[148:151], v[102:105]
	v_mfma_f32_16x16x32_bf16 v[224:227], v[202:205], v[156:159], v[98:101]
	s_setprio 0
	s_barrier
	s_nop 0
	ds_read_b128 v[98:101], v166
	ds_read_b128 v[102:105], v167
	ds_read_b128 v[114:117], v168
	ds_read_b128 v[118:121], v169
	s_barrier
	s_waitcnt lgkmcnt(0)
	s_setprio 1
	s_waitcnt lgkmcnt(3)
	v_mfma_f32_16x16x32_bf16 v[94:97], v[160:163], v[98:101], v[94:97]
	s_waitcnt lgkmcnt(1)
	v_mfma_f32_16x16x32_bf16 v[90:93], v[160:163], v[114:117], v[90:93]
	v_mfma_f32_16x16x32_bf16 v[78:81], v[190:193], v[98:101], v[78:81]
	v_mfma_f32_16x16x32_bf16 v[74:77], v[190:193], v[114:117], v[74:77]
	v_mfma_f32_16x16x32_bf16 v[94:97], v[178:181], v[102:105], v[94:97]
	s_waitcnt lgkmcnt(0)
	v_mfma_f32_16x16x32_bf16 v[90:93], v[178:181], v[118:121], v[90:93]
	v_mfma_f32_16x16x32_bf16 v[86:89], v[182:185], v[98:101], v[86:89]
	v_mfma_f32_16x16x32_bf16 v[82:85], v[182:185], v[114:117], v[82:85]
	v_mfma_f32_16x16x32_bf16 v[78:81], v[194:197], v[102:105], v[78:81]
	v_mfma_f32_16x16x32_bf16 v[74:77], v[194:197], v[118:121], v[74:77]
	v_mfma_f32_16x16x32_bf16 v[70:73], v[198:201], v[98:101], v[70:73]
	v_mfma_f32_16x16x32_bf16 v[66:69], v[198:201], v[114:117], v[66:69]
	v_mfma_f32_16x16x32_bf16 v[160:163], v[186:189], v[102:105], v[86:89]
	v_mfma_f32_16x16x32_bf16 v[164:167], v[186:189], v[118:121], v[82:85]
	v_mfma_f32_16x16x32_bf16 v[178:181], v[202:205], v[102:105], v[70:73]
	v_mfma_f32_16x16x32_bf16 v[182:185], v[202:205], v[118:121], v[66:69]
	s_setprio 0
	s_barrier
	s_nop 1
	ds_read_b128 v[66:69], v140 offset:16384
	ds_read_b128 v[70:73], v140 offset:17408
	ds_read_b128 v[82:85], v143 offset:16384
	ds_read_b128 v[86:89], v143 offset:17408
	ds_read_b128 v[186:189], v142 offset:16384
	ds_read_b128 v[190:193], v142 offset:17408
	ds_read_b128 v[194:197], v141 offset:16384
	ds_read_b128 v[198:201], v141 offset:17408
	s_waitcnt vmcnt(4)
	s_barrier
	s_waitcnt lgkmcnt(0)
	s_setprio 1
	s_waitcnt lgkmcnt(7)
	v_mfma_f32_16x16x32_bf16 v[62:65], v[66:69], v[144:147], v[62:65]
	v_mfma_f32_16x16x32_bf16 v[58:61], v[66:69], v[152:155], v[58:61]
	s_waitcnt lgkmcnt(3)
	v_mfma_f32_16x16x32_bf16 v[46:49], v[186:189], v[144:147], v[46:49]
	v_mfma_f32_16x16x32_bf16 v[42:45], v[186:189], v[152:155], v[42:45]
	v_mfma_f32_16x16x32_bf16 v[62:65], v[70:73], v[148:151], v[62:65]
	v_mfma_f32_16x16x32_bf16 v[58:61], v[70:73], v[156:159], v[58:61]
	v_mfma_f32_16x16x32_bf16 v[54:57], v[82:85], v[144:147], v[54:57]
	v_mfma_f32_16x16x32_bf16 v[50:53], v[82:85], v[152:155], v[50:53]
	s_waitcnt lgkmcnt(2)
	v_mfma_f32_16x16x32_bf16 v[46:49], v[190:193], v[148:151], v[46:49]
	v_mfma_f32_16x16x32_bf16 v[42:45], v[190:193], v[156:159], v[42:45]
	s_waitcnt lgkmcnt(1)
	v_mfma_f32_16x16x32_bf16 v[38:41], v[194:197], v[144:147], v[38:41]
	v_mfma_f32_16x16x32_bf16 v[34:37], v[194:197], v[152:155], v[34:37]
	v_mfma_f32_16x16x32_bf16 v[202:205], v[86:89], v[148:151], v[54:57]
	v_mfma_f32_16x16x32_bf16 v[228:231], v[86:89], v[156:159], v[50:53]
	s_waitcnt lgkmcnt(0)
	v_mfma_f32_16x16x32_bf16 v[144:147], v[198:201], v[148:151], v[38:41]
	v_mfma_f32_16x16x32_bf16 v[148:151], v[198:201], v[156:159], v[34:37]
	s_setprio 0
	s_setprio 1
	v_mfma_f32_16x16x32_bf16 v[30:33], v[66:69], v[98:101], v[30:33]
	v_mfma_f32_16x16x32_bf16 v[26:29], v[66:69], v[114:117], v[26:29]
	v_mfma_f32_16x16x32_bf16 v[14:17], v[186:189], v[98:101], v[14:17]
	v_mfma_f32_16x16x32_bf16 v[10:13], v[186:189], v[114:117], v[10:13]
	v_mfma_f32_16x16x32_bf16 v[30:33], v[70:73], v[102:105], v[30:33]
	v_mfma_f32_16x16x32_bf16 v[26:29], v[70:73], v[118:121], v[26:29]
	v_mfma_f32_16x16x32_bf16 v[22:25], v[82:85], v[98:101], v[22:25]
	v_mfma_f32_16x16x32_bf16 v[18:21], v[82:85], v[114:117], v[18:21]
	v_mfma_f32_16x16x32_bf16 v[14:17], v[190:193], v[102:105], v[14:17]
	v_mfma_f32_16x16x32_bf16 v[10:13], v[190:193], v[118:121], v[10:13]
	v_mfma_f32_16x16x32_bf16 v[6:9], v[194:197], v[98:101], v[6:9]
	v_mfma_f32_16x16x32_bf16 v[2:5], v[194:197], v[114:117], v[2:5]
	v_mfma_f32_16x16x32_bf16 v[152:155], v[86:89], v[102:105], v[22:25]
	v_mfma_f32_16x16x32_bf16 v[156:159], v[86:89], v[118:121], v[18:21]
	v_mfma_f32_16x16x32_bf16 v[186:189], v[198:201], v[102:105], v[6:9]
	v_mfma_f32_16x16x32_bf16 v[190:193], v[198:201], v[118:121], v[2:5]
	s_setprio 0
	s_barrier
	s_nop 1
	ds_read_b128 v[2:5], v170
	ds_read_b128 v[6:9], v171
	ds_read_b128 v[168:171], v172
	ds_read_b128 v[194:197], v173
	ds_read_b128 v[18:21], v140 offset:32768
	ds_read_b128 v[22:25], v140 offset:33792
	ds_read_b128 v[34:37], v143 offset:32768
	ds_read_b128 v[38:41], v143 offset:33792
	ds_read_b128 v[50:53], v142 offset:32768
	ds_read_b128 v[54:57], v142 offset:33792
	ds_read_b128 v[198:201], v141 offset:32768
	ds_read_b128 v[232:235], v141 offset:33792
	s_waitcnt vmcnt(2)
	s_barrier
	s_waitcnt lgkmcnt(0)
	s_setprio 1
	s_waitcnt lgkmcnt(7)
	v_mfma_f32_16x16x32_bf16 v[66:69], v[18:21], v[2:5], v[126:129]
	s_waitcnt lgkmcnt(6)
	v_mfma_f32_16x16x32_bf16 v[114:117], v[22:25], v[6:9], v[66:69]
	v_mfma_f32_16x16x32_bf16 v[66:69], v[18:21], v[168:171], v[122:125]
	v_mfma_f32_16x16x32_bf16 v[118:121], v[22:25], v[194:197], v[66:69]
	s_waitcnt lgkmcnt(5)
	v_mfma_f32_16x16x32_bf16 v[66:69], v[34:37], v[2:5], v[130:133]
	s_waitcnt lgkmcnt(4)
	v_mfma_f32_16x16x32_bf16 v[98:101], v[38:41], v[6:9], v[66:69]
	v_mfma_f32_16x16x32_bf16 v[66:69], v[34:37], v[168:171], v[206:209]
	v_mfma_f32_16x16x32_bf16 v[102:105], v[38:41], v[194:197], v[66:69]
	s_waitcnt lgkmcnt(3)
	v_mfma_f32_16x16x32_bf16 v[66:69], v[50:53], v[2:5], v[110:113]
	s_waitcnt lgkmcnt(2)
	v_mfma_f32_16x16x32_bf16 v[82:85], v[54:57], v[6:9], v[66:69]
	v_mfma_f32_16x16x32_bf16 v[66:69], v[50:53], v[168:171], v[106:109]
	v_mfma_f32_16x16x32_bf16 v[86:89], v[54:57], v[194:197], v[66:69]
	s_waitcnt lgkmcnt(1)
	v_mfma_f32_16x16x32_bf16 v[66:69], v[198:201], v[2:5], v[212:215]
	v_mfma_f32_16x16x32_bf16 v[70:73], v[198:201], v[168:171], v[224:227]
	s_waitcnt lgkmcnt(0)
	v_mfma_f32_16x16x32_bf16 v[66:69], v[232:235], v[6:9], v[66:69]
	v_mfma_f32_16x16x32_bf16 v[70:73], v[232:235], v[194:197], v[70:73]
	s_setprio 0
	s_barrier
	ds_read_b128 v[130:133], v174
	ds_read_b128 v[172:175], v175
	ds_read_b128 v[206:209], v176
	ds_read_b128 v[212:215], v177
	s_waitcnt vmcnt(0)
	s_barrier
	s_waitcnt lgkmcnt(0)
	s_setprio 1
	s_waitcnt lgkmcnt(3)
	v_mfma_f32_16x16x32_bf16 v[94:97], v[18:21], v[130:133], v[94:97]
	s_waitcnt lgkmcnt(1)
	v_mfma_f32_16x16x32_bf16 v[18:21], v[18:21], v[206:209], v[90:93]
	s_waitcnt lgkmcnt(0)
	v_mfma_f32_16x16x32_bf16 v[126:129], v[22:25], v[212:215], v[18:21]
	v_mfma_f32_16x16x32_bf16 v[18:21], v[34:37], v[130:133], v[160:163]
	v_mfma_f32_16x16x32_bf16 v[106:109], v[38:41], v[172:175], v[18:21]
	v_mfma_f32_16x16x32_bf16 v[18:21], v[34:37], v[206:209], v[164:167]
	v_mfma_f32_16x16x32_bf16 v[110:113], v[38:41], v[212:215], v[18:21]
	v_mfma_f32_16x16x32_bf16 v[18:21], v[50:53], v[130:133], v[78:81]
	v_mfma_f32_16x16x32_bf16 v[90:93], v[54:57], v[172:175], v[18:21]
	v_mfma_f32_16x16x32_bf16 v[18:21], v[50:53], v[206:209], v[74:77]
	v_mfma_f32_16x16x32_bf16 v[122:125], v[22:25], v[172:175], v[94:97]
	v_mfma_f32_16x16x32_bf16 v[94:97], v[54:57], v[212:215], v[18:21]
	v_mfma_f32_16x16x32_bf16 v[18:21], v[198:201], v[130:133], v[178:181]
	v_mfma_f32_16x16x32_bf16 v[74:77], v[232:235], v[172:175], v[18:21]
	v_mfma_f32_16x16x32_bf16 v[18:21], v[198:201], v[206:209], v[182:185]
	v_mfma_f32_16x16x32_bf16 v[78:81], v[232:235], v[212:215], v[18:21]
	s_setprio 0
	s_barrier
	ds_read_b128 v[160:163], v140 offset:49152
	ds_read_b128 v[164:167], v140 offset:50176
	ds_read_b128 v[176:179], v143 offset:49152
	ds_read_b128 v[180:183], v143 offset:50176
	ds_read_b128 v[198:201], v142 offset:49152
	ds_read_b128 v[224:227], v142 offset:50176
	ds_read_b128 v[232:235], v141 offset:49152
	ds_read_b128 v[140:143], v141 offset:50176
	s_barrier
	s_waitcnt lgkmcnt(0)
	s_setprio 1
	s_waitcnt lgkmcnt(7)
	v_mfma_f32_16x16x32_bf16 v[18:21], v[160:163], v[2:5], v[62:65]
	s_waitcnt lgkmcnt(6)
	v_mfma_f32_16x16x32_bf16 v[50:53], v[164:167], v[6:9], v[18:21]
	v_mfma_f32_16x16x32_bf16 v[18:21], v[160:163], v[168:171], v[58:61]
	v_mfma_f32_16x16x32_bf16 v[54:57], v[164:167], v[194:197], v[18:21]
	s_waitcnt lgkmcnt(5)
	v_mfma_f32_16x16x32_bf16 v[18:21], v[176:179], v[2:5], v[202:205]
	s_waitcnt lgkmcnt(4)
	v_mfma_f32_16x16x32_bf16 v[34:37], v[180:183], v[6:9], v[18:21]
	v_mfma_f32_16x16x32_bf16 v[18:21], v[176:179], v[168:171], v[228:231]
	v_mfma_f32_16x16x32_bf16 v[38:41], v[180:183], v[194:197], v[18:21]
	s_waitcnt lgkmcnt(3)
	v_mfma_f32_16x16x32_bf16 v[18:21], v[198:201], v[2:5], v[46:49]
	s_waitcnt lgkmcnt(1)
	v_mfma_f32_16x16x32_bf16 v[2:5], v[232:235], v[2:5], v[144:147]
	v_mfma_f32_16x16x32_bf16 v[18:21], v[224:227], v[6:9], v[18:21]
	v_mfma_f32_16x16x32_bf16 v[22:25], v[198:201], v[168:171], v[42:45]
	s_waitcnt lgkmcnt(0)
	v_mfma_f32_16x16x32_bf16 v[2:5], v[140:143], v[6:9], v[2:5]
	v_mfma_f32_16x16x32_bf16 v[6:9], v[232:235], v[168:171], v[148:151]
	v_mfma_f32_16x16x32_bf16 v[22:25], v[224:227], v[194:197], v[22:25]
	v_mfma_f32_16x16x32_bf16 v[6:9], v[140:143], v[194:197], v[6:9]
	s_setprio 0
	s_setprio 1
	v_mfma_f32_16x16x32_bf16 v[26:29], v[160:163], v[206:209], v[26:29]
	v_mfma_f32_16x16x32_bf16 v[62:65], v[164:167], v[212:215], v[26:29]
	v_mfma_f32_16x16x32_bf16 v[26:29], v[176:179], v[130:133], v[152:155]
	v_mfma_f32_16x16x32_bf16 v[30:33], v[160:163], v[130:133], v[30:33]
	v_mfma_f32_16x16x32_bf16 v[42:45], v[180:183], v[172:175], v[26:29]
	v_mfma_f32_16x16x32_bf16 v[26:29], v[176:179], v[206:209], v[156:159]
	v_mfma_f32_16x16x32_bf16 v[14:17], v[198:201], v[130:133], v[14:17]
	v_mfma_f32_16x16x32_bf16 v[10:13], v[198:201], v[206:209], v[10:13]
	v_mfma_f32_16x16x32_bf16 v[58:61], v[164:167], v[172:175], v[30:33]
	v_mfma_f32_16x16x32_bf16 v[46:49], v[180:183], v[212:215], v[26:29]
	v_mfma_f32_16x16x32_bf16 v[26:29], v[224:227], v[172:175], v[14:17]
	v_mfma_f32_16x16x32_bf16 v[30:33], v[224:227], v[212:215], v[10:13]
	v_mfma_f32_16x16x32_bf16 v[10:13], v[232:235], v[130:133], v[186:189]
	v_mfma_f32_16x16x32_bf16 v[14:17], v[232:235], v[206:209], v[190:193]
	v_mfma_f32_16x16x32_bf16 v[10:13], v[140:143], v[172:175], v[10:13]
	v_mfma_f32_16x16x32_bf16 v[14:17], v[140:143], v[212:215], v[14:17]
	s_setprio 0
	s_movk_i32 s5, 0x100
	v_cmp_gt_u32_e32 vcc, s5, v134
	s_barrier
	s_and_saveexec_b64 s[8:9], vcc
	s_cbranch_execz .LBB0_850
	s_barrier

.LBB0_1353:
	v_or_b32_e32 v164, 0x10000, v160
	v_or_b32_e32 v166, 0x10000, v162
	v_or_b32_e32 v165, 0x10000, v161
	ds_read_b128 v[174:177], v164
	ds_read_b128 v[178:181], v165
	v_or_b32_e32 v167, 0x10000, v163
	ds_read_b128 v[182:185], v166
	ds_read_b128 v[186:189], v167
	s_add_u32 s25, s22, s12
	s_addc_u32 s27, s23, s13
	s_add_u32 s26, s25, 0x80
	v_add_u32_e32 v168, 0xc000, v142
	s_addc_u32 s27, s27, 0
	v_readfirstlane_b32 s25, v168
	v_add_u32_e32 v169, 0xe000, v142
	ds_read_b128 v[190:193], v144
	ds_read_b128 v[194:197], v144 offset:1024
	ds_read_b128 v[198:201], v147
	ds_read_b128 v[202:205], v147 offset:1024
	ds_read_b128 v[206:209], v146
	ds_read_b128 v[212:215], v146 offset:1024
	ds_read_b128 v[224:227], v145
	ds_read_b128 v[228:231], v145 offset:1024
	s_mov_b32 m0, s25
	v_lshl_add_u64 v[170:171], s[26:27], 0, v[132:133]
	v_readfirstlane_b32 s25, v169
	global_load_lds_dwordx4 v[170:171], off
	v_lshl_add_u64 v[170:171], s[26:27], 0, v[130:131]
	s_mov_b32 m0, s25
	s_nop 0
	global_load_lds_dwordx4 v[170:171], off
	s_waitcnt lgkmcnt(8)
	s_barrier
	s_waitcnt lgkmcnt(0)
	s_setprio 1
	s_waitcnt lgkmcnt(0)
	v_mfma_f32_16x16x32_bf16 v[126:129], v[190:193], v[174:177], v[126:129]
	v_mfma_f32_16x16x32_bf16 v[122:125], v[190:193], v[182:185], v[122:125]
	v_mfma_f32_16x16x32_bf16 v[118:121], v[198:201], v[174:177], v[118:121]
	v_mfma_f32_16x16x32_bf16 v[114:117], v[198:201], v[182:185], v[114:117]
	v_mfma_f32_16x16x32_bf16 v[110:113], v[206:209], v[174:177], v[110:113]
	v_mfma_f32_16x16x32_bf16 v[106:109], v[206:209], v[182:185], v[106:109]
	v_mfma_f32_16x16x32_bf16 v[102:105], v[224:227], v[174:177], v[102:105]
	v_mfma_f32_16x16x32_bf16 v[98:101], v[224:227], v[182:185], v[98:101]
	v_mfma_f32_16x16x32_bf16 v[126:129], v[194:197], v[178:181], v[126:129]
	v_mfma_f32_16x16x32_bf16 v[122:125], v[194:197], v[186:189], v[122:125]
	v_mfma_f32_16x16x32_bf16 v[118:121], v[202:205], v[178:181], v[118:121]
	v_mfma_f32_16x16x32_bf16 v[114:117], v[202:205], v[186:189], v[114:117]
	v_mfma_f32_16x16x32_bf16 v[110:113], v[212:215], v[178:181], v[110:113]
	v_mfma_f32_16x16x32_bf16 v[106:109], v[212:215], v[186:189], v[106:109]
	v_mfma_f32_16x16x32_bf16 v[102:105], v[228:231], v[178:181], v[102:105]
	v_mfma_f32_16x16x32_bf16 v[98:101], v[228:231], v[186:189], v[98:101]
	s_setprio 0
	s_barrier
	s_add_u32 s25, s4, s12
	s_addc_u32 s28, s5, s13
	s_add_u32 s26, s25, 0x100
	v_or_b32_e32 v170, 0x14000, v160
	v_or_b32_e32 v172, 0x14000, v162
	s_addc_u32 s27, s28, 0
	v_readfirstlane_b32 s29, v148
	v_or_b32_e32 v171, 0x14000, v161
	ds_read_b128 v[232:235], v170
	ds_read_b128 v[236:239], v171
	v_or_b32_e32 v173, 0x14000, v163
	ds_read_b128 v[240:243], v172
	ds_read_b128 v[244:247], v173
	s_mov_b32 m0, s29
	v_lshl_add_u64 v[216:217], s[26:27], 0, v[134:135]
	global_load_lds_dwordx4 v[216:217], off
	v_lshl_add_u64 v[216:217], s[26:27], 0, v[136:137]
	v_readfirstlane_b32 s26, v149
	s_mov_b32 m0, s26
	s_nop 0
	global_load_lds_dwordx4 v[216:217], off
	s_barrier
	s_waitcnt lgkmcnt(0)
	s_setprio 1
	s_waitcnt lgkmcnt(0)
	v_mfma_f32_16x16x32_bf16 v[94:97], v[190:193], v[232:235], v[94:97]
	v_mfma_f32_16x16x32_bf16 v[90:93], v[190:193], v[240:243], v[90:93]
	v_mfma_f32_16x16x32_bf16 v[86:89], v[198:201], v[232:235], v[86:89]
	v_mfma_f32_16x16x32_bf16 v[82:85], v[198:201], v[240:243], v[82:85]
	v_mfma_f32_16x16x32_bf16 v[78:81], v[206:209], v[232:235], v[78:81]
	v_mfma_f32_16x16x32_bf16 v[74:77], v[206:209], v[240:243], v[74:77]
	v_mfma_f32_16x16x32_bf16 v[70:73], v[224:227], v[232:235], v[70:73]
	v_mfma_f32_16x16x32_bf16 v[66:69], v[224:227], v[240:243], v[66:69]
	v_mfma_f32_16x16x32_bf16 v[94:97], v[194:197], v[236:239], v[94:97]
	v_mfma_f32_16x16x32_bf16 v[90:93], v[194:197], v[244:247], v[90:93]
	v_mfma_f32_16x16x32_bf16 v[86:89], v[202:205], v[236:239], v[86:89]
	v_mfma_f32_16x16x32_bf16 v[82:85], v[202:205], v[244:247], v[82:85]
	v_mfma_f32_16x16x32_bf16 v[78:81], v[212:215], v[236:239], v[78:81]
	v_mfma_f32_16x16x32_bf16 v[74:77], v[212:215], v[244:247], v[74:77]
	v_mfma_f32_16x16x32_bf16 v[70:73], v[228:231], v[236:239], v[70:73]
	v_mfma_f32_16x16x32_bf16 v[66:69], v[228:231], v[244:247], v[66:69]
	s_setprio 0
	s_add_u32 s29, s6, s12
	s_addc_u32 s30, s7, s13
	s_add_u32 s26, s29, 0x100
	s_addc_u32 s27, s30, 0
	v_readfirstlane_b32 s31, v142
	s_barrier
	ds_read_b128 v[190:193], v144 offset:16384
	ds_read_b128 v[194:197], v144 offset:17408
	ds_read_b128 v[198:201], v147 offset:16384
	ds_read_b128 v[202:205], v147 offset:17408
	ds_read_b128 v[206:209], v146 offset:16384
	ds_read_b128 v[212:215], v146 offset:17408
	ds_read_b128 v[224:227], v145 offset:16384
	ds_read_b128 v[228:231], v145 offset:17408
	s_mov_b32 m0, s31
	v_lshl_add_u64 v[216:217], s[26:27], 0, v[132:133]
	global_load_lds_dwordx4 v[216:217], off
	v_lshl_add_u64 v[216:217], s[26:27], 0, v[130:131]
	v_readfirstlane_b32 s26, v143
	s_mov_b32 m0, s26
	s_nop 0
	global_load_lds_dwordx4 v[216:217], off
	s_barrier
	s_waitcnt lgkmcnt(0)
	s_setprio 1
	s_waitcnt lgkmcnt(0)
	v_mfma_f32_16x16x32_bf16 v[62:65], v[190:193], v[174:177], v[62:65]
	v_mfma_f32_16x16x32_bf16 v[58:61], v[190:193], v[182:185], v[58:61]
	v_mfma_f32_16x16x32_bf16 v[54:57], v[198:201], v[174:177], v[54:57]
	v_mfma_f32_16x16x32_bf16 v[50:53], v[198:201], v[182:185], v[50:53]
	v_mfma_f32_16x16x32_bf16 v[46:49], v[206:209], v[174:177], v[46:49]
	v_mfma_f32_16x16x32_bf16 v[42:45], v[206:209], v[182:185], v[42:45]
	v_mfma_f32_16x16x32_bf16 v[38:41], v[224:227], v[174:177], v[38:41]
	v_mfma_f32_16x16x32_bf16 v[34:37], v[224:227], v[182:185], v[34:37]
	v_mfma_f32_16x16x32_bf16 v[62:65], v[194:197], v[178:181], v[62:65]
	v_mfma_f32_16x16x32_bf16 v[58:61], v[194:197], v[186:189], v[58:61]
	v_mfma_f32_16x16x32_bf16 v[54:57], v[202:205], v[178:181], v[54:57]
	v_mfma_f32_16x16x32_bf16 v[50:53], v[202:205], v[186:189], v[50:53]
	v_mfma_f32_16x16x32_bf16 v[46:49], v[212:215], v[178:181], v[46:49]
	v_mfma_f32_16x16x32_bf16 v[42:45], v[212:215], v[186:189], v[42:45]
	v_mfma_f32_16x16x32_bf16 v[38:41], v[228:231], v[178:181], v[38:41]
	v_mfma_f32_16x16x32_bf16 v[34:37], v[228:231], v[186:189], v[34:37]
	s_setprio 0
	s_barrier
	s_add_u32 s31, s8, s12
	s_addc_u32 s34, s9, s13
	s_add_u32 s26, s31, 0x100
	s_addc_u32 s27, s34, 0
	v_readfirstlane_b32 s35, v150
	s_mov_b32 m0, s35
	v_lshl_add_u64 v[174:175], s[26:27], 0, v[134:135]
	global_load_lds_dwordx4 v[174:175], off
	v_lshl_add_u64 v[174:175], s[26:27], 0, v[136:137]
	v_readfirstlane_b32 s26, v151
	s_mov_b32 m0, s26
	s_nop 0
	global_load_lds_dwordx4 v[174:175], off
	s_waitcnt vmcnt(6)
	s_barrier
	s_setprio 1
	v_mfma_f32_16x16x32_bf16 v[30:33], v[190:193], v[232:235], v[30:33]
	v_mfma_f32_16x16x32_bf16 v[26:29], v[190:193], v[240:243], v[26:29]
	v_mfma_f32_16x16x32_bf16 v[22:25], v[198:201], v[232:235], v[22:25]
	v_mfma_f32_16x16x32_bf16 v[18:21], v[198:201], v[240:243], v[18:21]
	v_mfma_f32_16x16x32_bf16 v[14:17], v[206:209], v[232:235], v[14:17]
	v_mfma_f32_16x16x32_bf16 v[10:13], v[206:209], v[240:243], v[10:13]
	v_mfma_f32_16x16x32_bf16 v[6:9], v[224:227], v[232:235], v[6:9]
	v_mfma_f32_16x16x32_bf16 v[2:5], v[224:227], v[240:243], v[2:5]
	v_mfma_f32_16x16x32_bf16 v[30:33], v[194:197], v[236:239], v[30:33]
	v_mfma_f32_16x16x32_bf16 v[26:29], v[194:197], v[244:247], v[26:29]
	v_mfma_f32_16x16x32_bf16 v[22:25], v[202:205], v[236:239], v[22:25]
	v_mfma_f32_16x16x32_bf16 v[18:21], v[202:205], v[244:247], v[18:21]
	v_mfma_f32_16x16x32_bf16 v[14:17], v[212:215], v[236:239], v[14:17]
	v_mfma_f32_16x16x32_bf16 v[10:13], v[212:215], v[244:247], v[10:13]
	v_mfma_f32_16x16x32_bf16 v[6:9], v[228:231], v[236:239], v[6:9]
	v_mfma_f32_16x16x32_bf16 v[2:5], v[228:231], v[244:247], v[2:5]
	s_setprio 0
	v_or_b32_e32 v174, 0x18000, v160
	v_or_b32_e32 v176, 0x18000, v162
	s_barrier
	v_or_b32_e32 v175, 0x18000, v161
	ds_read_b128 v[182:185], v174
	ds_read_b128 v[186:189], v175
	v_or_b32_e32 v177, 0x18000, v163
	ds_read_b128 v[190:193], v176
	ds_read_b128 v[194:197], v177
	s_add_u32 s26, s20, s12
	s_addc_u32 s27, s21, s13
	v_readfirstlane_b32 s35, v152
	ds_read_b128 v[198:201], v144 offset:32768
	ds_read_b128 v[202:205], v144 offset:33792
	ds_read_b128 v[206:209], v147 offset:32768
	ds_read_b128 v[212:215], v147 offset:33792
	ds_read_b128 v[224:227], v146 offset:32768
	ds_read_b128 v[228:231], v146 offset:33792
	ds_read_b128 v[232:235], v145 offset:32768
	ds_read_b128 v[236:239], v145 offset:33792
	s_mov_b32 m0, s35
	v_lshl_add_u64 v[178:179], s[26:27], 0, v[132:133]
	global_load_lds_dwordx4 v[178:179], off
	v_lshl_add_u64 v[178:179], s[26:27], 0, v[130:131]
	v_readfirstlane_b32 s26, v153
	s_mov_b32 m0, s26
	s_nop 0
	global_load_lds_dwordx4 v[178:179], off
	s_waitcnt lgkmcnt(8)
	s_barrier
	s_waitcnt lgkmcnt(0)
	s_setprio 1
	s_waitcnt lgkmcnt(0)
	v_mfma_f32_16x16x32_bf16 v[126:129], v[198:201], v[182:185], v[126:129]
	v_mfma_f32_16x16x32_bf16 v[122:125], v[198:201], v[190:193], v[122:125]
	v_mfma_f32_16x16x32_bf16 v[118:121], v[206:209], v[182:185], v[118:121]
	v_mfma_f32_16x16x32_bf16 v[114:117], v[206:209], v[190:193], v[114:117]
	v_mfma_f32_16x16x32_bf16 v[110:113], v[224:227], v[182:185], v[110:113]
	v_mfma_f32_16x16x32_bf16 v[106:109], v[224:227], v[190:193], v[106:109]
	v_mfma_f32_16x16x32_bf16 v[102:105], v[232:235], v[182:185], v[102:105]
	v_mfma_f32_16x16x32_bf16 v[98:101], v[232:235], v[190:193], v[98:101]
	v_mfma_f32_16x16x32_bf16 v[126:129], v[202:205], v[186:189], v[126:129]
	v_mfma_f32_16x16x32_bf16 v[122:125], v[202:205], v[194:197], v[122:125]
	v_mfma_f32_16x16x32_bf16 v[118:121], v[212:215], v[186:189], v[118:121]
	v_mfma_f32_16x16x32_bf16 v[114:117], v[212:215], v[194:197], v[114:117]
	v_mfma_f32_16x16x32_bf16 v[110:113], v[228:231], v[186:189], v[110:113]
	v_mfma_f32_16x16x32_bf16 v[106:109], v[228:231], v[194:197], v[106:109]
	v_mfma_f32_16x16x32_bf16 v[102:105], v[236:239], v[186:189], v[102:105]
	v_mfma_f32_16x16x32_bf16 v[98:101], v[236:239], v[194:197], v[98:101]
	s_setprio 0
	s_barrier
	s_add_u32 s26, s25, 0x180
	v_or_b32_e32 v178, 0x1c000, v160
	v_or_b32_e32 v180, 0x1c000, v162
	s_addc_u32 s27, s28, 0
	v_readfirstlane_b32 s25, v154
	v_or_b32_e32 v179, 0x1c000, v161
	ds_read_b128 v[240:243], v178
	ds_read_b128 v[244:247], v179
	v_or_b32_e32 v181, 0x1c000, v163
	ds_read_b128 v[248:251], v180
	ds_read_b128 v[216:219], v181
	s_mov_b32 m0, s25
	v_lshl_add_u64 v[252:253], s[26:27], 0, v[134:135]
	v_readfirstlane_b32 s25, v155
	global_load_lds_dwordx4 v[252:253], off
	v_lshl_add_u64 v[252:253], s[26:27], 0, v[136:137]
	s_mov_b32 m0, s25
	s_nop 0
	global_load_lds_dwordx4 v[252:253], off
	s_barrier
	s_waitcnt lgkmcnt(0)
	s_setprio 1
	s_waitcnt lgkmcnt(0)
	v_mfma_f32_16x16x32_bf16 v[94:97], v[198:201], v[240:243], v[94:97]
	v_mfma_f32_16x16x32_bf16 v[90:93], v[198:201], v[248:251], v[90:93]
	v_mfma_f32_16x16x32_bf16 v[86:89], v[206:209], v[240:243], v[86:89]
	v_mfma_f32_16x16x32_bf16 v[82:85], v[206:209], v[248:251], v[82:85]
	v_mfma_f32_16x16x32_bf16 v[78:81], v[224:227], v[240:243], v[78:81]
	v_mfma_f32_16x16x32_bf16 v[74:77], v[224:227], v[248:251], v[74:77]
	v_mfma_f32_16x16x32_bf16 v[70:73], v[232:235], v[240:243], v[70:73]
	v_mfma_f32_16x16x32_bf16 v[66:69], v[232:235], v[248:251], v[66:69]
	v_mfma_f32_16x16x32_bf16 v[94:97], v[202:205], v[244:247], v[94:97]
	v_mfma_f32_16x16x32_bf16 v[90:93], v[202:205], v[216:219], v[90:93]
	v_mfma_f32_16x16x32_bf16 v[86:89], v[212:215], v[244:247], v[86:89]
	v_mfma_f32_16x16x32_bf16 v[82:85], v[212:215], v[216:219], v[82:85]
	v_mfma_f32_16x16x32_bf16 v[78:81], v[228:231], v[244:247], v[78:81]
	v_mfma_f32_16x16x32_bf16 v[74:77], v[228:231], v[216:219], v[74:77]
	v_mfma_f32_16x16x32_bf16 v[70:73], v[236:239], v[244:247], v[70:73]
	v_mfma_f32_16x16x32_bf16 v[66:69], v[236:239], v[216:219], v[66:69]
	s_setprio 0
	s_add_u32 s26, s29, 0x180
	s_addc_u32 s27, s30, 0
	v_readfirstlane_b32 s25, v156
	s_barrier
	ds_read_b128 v[198:201], v144 offset:49152
	ds_read_b128 v[202:205], v144 offset:50176
	ds_read_b128 v[206:209], v147 offset:49152
	ds_read_b128 v[212:215], v147 offset:50176
	ds_read_b128 v[224:227], v146 offset:49152
	ds_read_b128 v[228:231], v146 offset:50176
	ds_read_b128 v[232:235], v145 offset:49152
	ds_read_b128 v[236:239], v145 offset:50176
	s_mov_b32 m0, s25
	v_lshl_add_u64 v[252:253], s[26:27], 0, v[132:133]
	v_readfirstlane_b32 s25, v157
	global_load_lds_dwordx4 v[252:253], off
	v_lshl_add_u64 v[252:253], s[26:27], 0, v[130:131]
	s_mov_b32 m0, s25
	s_nop 0
	global_load_lds_dwordx4 v[252:253], off
	s_barrier
	s_waitcnt lgkmcnt(0)
	s_setprio 1
	s_waitcnt lgkmcnt(0)
	v_mfma_f32_16x16x32_bf16 v[62:65], v[198:201], v[182:185], v[62:65]
	v_mfma_f32_16x16x32_bf16 v[58:61], v[198:201], v[190:193], v[58:61]
	v_mfma_f32_16x16x32_bf16 v[54:57], v[206:209], v[182:185], v[54:57]
	v_mfma_f32_16x16x32_bf16 v[50:53], v[206:209], v[190:193], v[50:53]
	v_mfma_f32_16x16x32_bf16 v[46:49], v[224:227], v[182:185], v[46:49]
	v_mfma_f32_16x16x32_bf16 v[42:45], v[224:227], v[190:193], v[42:45]
	v_mfma_f32_16x16x32_bf16 v[38:41], v[232:235], v[182:185], v[38:41]
	v_mfma_f32_16x16x32_bf16 v[34:37], v[232:235], v[190:193], v[34:37]
	v_mfma_f32_16x16x32_bf16 v[62:65], v[202:205], v[186:189], v[62:65]
	v_mfma_f32_16x16x32_bf16 v[58:61], v[202:205], v[194:197], v[58:61]
	v_mfma_f32_16x16x32_bf16 v[54:57], v[212:215], v[186:189], v[54:57]
	v_mfma_f32_16x16x32_bf16 v[50:53], v[212:215], v[194:197], v[50:53]
	v_mfma_f32_16x16x32_bf16 v[46:49], v[228:231], v[186:189], v[46:49]
	v_mfma_f32_16x16x32_bf16 v[42:45], v[228:231], v[194:197], v[42:45]
	v_mfma_f32_16x16x32_bf16 v[38:41], v[236:239], v[186:189], v[38:41]
	v_mfma_f32_16x16x32_bf16 v[34:37], v[236:239], v[194:197], v[34:37]
	s_setprio 0
	s_barrier
	s_add_u32 s26, s31, 0x180
	s_addc_u32 s27, s34, 0
	v_readfirstlane_b32 s25, v158
	s_mov_b32 m0, s25
	v_lshl_add_u64 v[182:183], s[26:27], 0, v[134:135]
	v_readfirstlane_b32 s25, v159
	global_load_lds_dwordx4 v[182:183], off
	v_lshl_add_u64 v[182:183], s[26:27], 0, v[136:137]
	s_mov_b32 m0, s25
	s_nop 0
	global_load_lds_dwordx4 v[182:183], off
	s_waitcnt vmcnt(6)
	s_barrier
	s_setprio 1
	v_mfma_f32_16x16x32_bf16 v[30:33], v[198:201], v[240:243], v[30:33]
	v_mfma_f32_16x16x32_bf16 v[26:29], v[198:201], v[248:251], v[26:29]
	v_mfma_f32_16x16x32_bf16 v[22:25], v[206:209], v[240:243], v[22:25]
	v_mfma_f32_16x16x32_bf16 v[18:21], v[206:209], v[248:251], v[18:21]
	v_mfma_f32_16x16x32_bf16 v[14:17], v[224:227], v[240:243], v[14:17]
	v_mfma_f32_16x16x32_bf16 v[10:13], v[224:227], v[248:251], v[10:13]
	v_mfma_f32_16x16x32_bf16 v[6:9], v[232:235], v[240:243], v[6:9]
	v_mfma_f32_16x16x32_bf16 v[2:5], v[232:235], v[248:251], v[2:5]
	v_mfma_f32_16x16x32_bf16 v[30:33], v[202:205], v[244:247], v[30:33]
	v_mfma_f32_16x16x32_bf16 v[26:29], v[202:205], v[216:219], v[26:29]
	v_mfma_f32_16x16x32_bf16 v[22:25], v[212:215], v[244:247], v[22:25]
	v_mfma_f32_16x16x32_bf16 v[18:21], v[212:215], v[216:219], v[18:21]
	v_mfma_f32_16x16x32_bf16 v[14:17], v[228:231], v[244:247], v[14:17]
	v_mfma_f32_16x16x32_bf16 v[10:13], v[228:231], v[216:219], v[10:13]
	v_mfma_f32_16x16x32_bf16 v[6:9], v[236:239], v[244:247], v[6:9]
	v_mfma_f32_16x16x32_bf16 v[2:5], v[236:239], v[216:219], v[2:5]
	s_setprio 0
	s_add_i32 s24, s24, 2
	s_add_u32 s12, s12, 0x100
	s_addc_u32 s13, s13, 0
	s_cmp_lt_u32 s24, 28
	s_barrier
	s_cbranch_scc1 .LBB0_1353
	s_add_u32 s4, s10, 0xf80
	s_addc_u32 s5, s11, 0
	ds_read_b128 v[134:137], v164
	ds_read_b128 v[148:151], v165
	ds_read_b128 v[152:155], v166
	ds_read_b128 v[156:159], v167
	ds_read_b128 v[160:163], v144
	ds_read_b128 v[164:167], v144 offset:1024
	ds_read_b128 v[182:185], v147
	ds_read_b128 v[186:189], v147 offset:1024
	ds_read_b128 v[190:193], v146
	ds_read_b128 v[194:197], v146 offset:1024
	ds_read_b128 v[198:201], v145
	ds_read_b128 v[202:205], v145 offset:1024
	v_readfirstlane_b32 s6, v168
	v_lshl_add_u64 v[132:133], s[4:5], 0, v[132:133]
	s_mov_b32 m0, s6
	v_lshl_add_u64 v[130:131], s[4:5], 0, v[130:131]
	v_readfirstlane_b32 s4, v169
	global_load_lds_dwordx4 v[132:133], off
	s_mov_b32 m0, s4
	s_nop 0
	global_load_lds_dwordx4 v[130:131], off
	s_barrier
	s_waitcnt lgkmcnt(0)
	s_setprio 1
	s_waitcnt lgkmcnt(0)
	v_mfma_f32_16x16x32_bf16 v[126:129], v[160:163], v[134:137], v[126:129]
	v_mfma_f32_16x16x32_bf16 v[122:125], v[160:163], v[152:155], v[122:125]
	v_mfma_f32_16x16x32_bf16 v[118:121], v[182:185], v[134:137], v[118:121]
	v_mfma_f32_16x16x32_bf16 v[114:117], v[182:185], v[152:155], v[114:117]
	v_mfma_f32_16x16x32_bf16 v[110:113], v[190:193], v[134:137], v[110:113]
	v_mfma_f32_16x16x32_bf16 v[106:109], v[190:193], v[152:155], v[106:109]
	v_mfma_f32_16x16x32_bf16 v[98:101], v[198:201], v[152:155], v[98:101]
	v_mfma_f32_16x16x32_bf16 v[126:129], v[164:167], v[148:151], v[126:129]
	v_mfma_f32_16x16x32_bf16 v[122:125], v[164:167], v[156:159], v[122:125]
	v_mfma_f32_16x16x32_bf16 v[118:121], v[186:189], v[148:151], v[118:121]
	v_mfma_f32_16x16x32_bf16 v[114:117], v[186:189], v[156:159], v[114:117]
	v_mfma_f32_16x16x32_bf16 v[110:113], v[194:197], v[148:151], v[110:113]
	v_mfma_f32_16x16x32_bf16 v[106:109], v[194:197], v[156:159], v[106:109]
	v_mfma_f32_16x16x32_bf16 v[102:105], v[198:201], v[134:137], v[102:105]
	v_mfma_f32_16x16x32_bf16 v[98:101], v[202:205], v[156:159], v[98:101]
	v_mfma_f32_16x16x32_bf16 v[130:133], v[202:205], v[148:151], v[102:105]
	s_setprio 0
	s_barrier
	s_nop 2
	ds_read_b128 v[102:105], v170
	ds_read_b128 v[168:171], v171
	ds_read_b128 v[206:209], v172
	ds_read_b128 v[212:215], v173
	s_barrier
	s_waitcnt lgkmcnt(0)
	s_setprio 1
	s_waitcnt lgkmcnt(1)
	v_mfma_f32_16x16x32_bf16 v[90:93], v[160:163], v[206:209], v[90:93]
	v_mfma_f32_16x16x32_bf16 v[94:97], v[160:163], v[102:105], v[94:97]
	s_waitcnt lgkmcnt(0)
	v_mfma_f32_16x16x32_bf16 v[90:93], v[164:167], v[212:215], v[90:93]
	v_mfma_f32_16x16x32_bf16 v[86:89], v[182:185], v[102:105], v[86:89]
	v_mfma_f32_16x16x32_bf16 v[82:85], v[182:185], v[206:209], v[82:85]
	v_mfma_f32_16x16x32_bf16 v[78:81], v[190:193], v[102:105], v[78:81]
	v_mfma_f32_16x16x32_bf16 v[74:77], v[190:193], v[206:209], v[74:77]
	v_mfma_f32_16x16x32_bf16 v[70:73], v[198:201], v[102:105], v[70:73]
	v_mfma_f32_16x16x32_bf16 v[66:69], v[198:201], v[206:209], v[66:69]
	v_mfma_f32_16x16x32_bf16 v[216:219], v[164:167], v[168:171], v[94:97]
	v_mfma_f32_16x16x32_bf16 v[160:163], v[186:189], v[168:171], v[86:89]
	v_mfma_f32_16x16x32_bf16 v[164:167], v[186:189], v[212:215], v[82:85]
	v_mfma_f32_16x16x32_bf16 v[182:185], v[194:197], v[168:171], v[78:81]
	v_mfma_f32_16x16x32_bf16 v[186:189], v[194:197], v[212:215], v[74:77]
	v_mfma_f32_16x16x32_bf16 v[190:193], v[202:205], v[168:171], v[70:73]
	v_mfma_f32_16x16x32_bf16 v[194:197], v[202:205], v[212:215], v[66:69]
	s_setprio 0
	s_barrier
	s_nop 0
	ds_read_b128 v[66:69], v144 offset:16384
	ds_read_b128 v[70:73], v144 offset:17408
	ds_read_b128 v[74:77], v147 offset:16384
	ds_read_b128 v[78:81], v147 offset:17408
	ds_read_b128 v[82:85], v146 offset:16384
	ds_read_b128 v[86:89], v146 offset:17408
	ds_read_b128 v[94:97], v145 offset:16384
	ds_read_b128 v[198:201], v145 offset:17408
	s_waitcnt vmcnt(4)
	s_barrier
	s_waitcnt lgkmcnt(0)
	s_setprio 1
	s_waitcnt lgkmcnt(7)
	v_mfma_f32_16x16x32_bf16 v[62:65], v[66:69], v[134:137], v[62:65]
	v_mfma_f32_16x16x32_bf16 v[58:61], v[66:69], v[152:155], v[58:61]
	s_waitcnt lgkmcnt(5)
	v_mfma_f32_16x16x32_bf16 v[54:57], v[74:77], v[134:137], v[54:57]
	v_mfma_f32_16x16x32_bf16 v[50:53], v[74:77], v[152:155], v[50:53]
	s_waitcnt lgkmcnt(3)
	v_mfma_f32_16x16x32_bf16 v[46:49], v[82:85], v[134:137], v[46:49]
	v_mfma_f32_16x16x32_bf16 v[42:45], v[82:85], v[152:155], v[42:45]
	s_waitcnt lgkmcnt(1)
	v_mfma_f32_16x16x32_bf16 v[38:41], v[94:97], v[134:137], v[38:41]
	v_mfma_f32_16x16x32_bf16 v[34:37], v[94:97], v[152:155], v[34:37]
	v_mfma_f32_16x16x32_bf16 v[62:65], v[70:73], v[148:151], v[62:65]
	v_mfma_f32_16x16x32_bf16 v[58:61], v[70:73], v[156:159], v[58:61]
	v_mfma_f32_16x16x32_bf16 v[54:57], v[78:81], v[148:151], v[54:57]
	v_mfma_f32_16x16x32_bf16 v[50:53], v[78:81], v[156:159], v[50:53]
	v_mfma_f32_16x16x32_bf16 v[46:49], v[86:89], v[148:151], v[46:49]
	v_mfma_f32_16x16x32_bf16 v[42:45], v[86:89], v[156:159], v[42:45]
	s_waitcnt lgkmcnt(0)
	v_mfma_f32_16x16x32_bf16 v[38:41], v[198:201], v[148:151], v[38:41]
	v_mfma_f32_16x16x32_bf16 v[34:37], v[198:201], v[156:159], v[34:37]
	s_setprio 0
	s_setprio 1
	v_mfma_f32_16x16x32_bf16 v[30:33], v[66:69], v[102:105], v[30:33]
	v_mfma_f32_16x16x32_bf16 v[26:29], v[66:69], v[206:209], v[26:29]
	v_mfma_f32_16x16x32_bf16 v[22:25], v[74:77], v[102:105], v[22:25]
	v_mfma_f32_16x16x32_bf16 v[18:21], v[74:77], v[206:209], v[18:21]
	v_mfma_f32_16x16x32_bf16 v[14:17], v[82:85], v[102:105], v[14:17]
	v_mfma_f32_16x16x32_bf16 v[10:13], v[82:85], v[206:209], v[10:13]
	v_mfma_f32_16x16x32_bf16 v[6:9], v[94:97], v[102:105], v[6:9]
	v_mfma_f32_16x16x32_bf16 v[2:5], v[94:97], v[206:209], v[2:5]
	v_mfma_f32_16x16x32_bf16 v[134:137], v[70:73], v[168:171], v[30:33]
	v_mfma_f32_16x16x32_bf16 v[148:151], v[70:73], v[212:215], v[26:29]
	v_mfma_f32_16x16x32_bf16 v[152:155], v[78:81], v[168:171], v[22:25]
	v_mfma_f32_16x16x32_bf16 v[156:159], v[78:81], v[212:215], v[18:21]
	v_mfma_f32_16x16x32_bf16 v[202:205], v[86:89], v[168:171], v[14:17]
	v_mfma_f32_16x16x32_bf16 v[224:227], v[86:89], v[212:215], v[10:13]
	v_mfma_f32_16x16x32_bf16 v[168:171], v[198:201], v[168:171], v[6:9]
	v_mfma_f32_16x16x32_bf16 v[198:201], v[198:201], v[212:215], v[2:5]
	s_setprio 0
	s_barrier
	s_nop 0
	ds_read_b128 v[2:5], v174
	ds_read_b128 v[6:9], v175
	ds_read_b128 v[172:175], v176
	ds_read_b128 v[206:209], v177
	ds_read_b128 v[10:13], v144 offset:32768
	ds_read_b128 v[14:17], v144 offset:33792
	ds_read_b128 v[18:21], v147 offset:32768
	ds_read_b128 v[22:25], v147 offset:33792
	ds_read_b128 v[26:29], v146 offset:32768
	ds_read_b128 v[30:33], v146 offset:33792
	ds_read_b128 v[212:215], v145 offset:32768
	ds_read_b128 v[228:231], v145 offset:33792
	s_waitcnt vmcnt(2)
	s_barrier
	s_waitcnt lgkmcnt(0)
	s_setprio 1
	s_waitcnt lgkmcnt(7)
	v_mfma_f32_16x16x32_bf16 v[66:69], v[10:13], v[2:5], v[126:129]
	s_waitcnt lgkmcnt(6)
	v_mfma_f32_16x16x32_bf16 v[94:97], v[14:17], v[6:9], v[66:69]
	v_mfma_f32_16x16x32_bf16 v[66:69], v[10:13], v[172:175], v[122:125]
	v_mfma_f32_16x16x32_bf16 v[102:105], v[14:17], v[206:209], v[66:69]
	s_waitcnt lgkmcnt(5)
	v_mfma_f32_16x16x32_bf16 v[66:69], v[18:21], v[2:5], v[118:121]
	s_waitcnt lgkmcnt(4)
	v_mfma_f32_16x16x32_bf16 v[82:85], v[22:25], v[6:9], v[66:69]
	v_mfma_f32_16x16x32_bf16 v[66:69], v[18:21], v[172:175], v[114:117]
	v_mfma_f32_16x16x32_bf16 v[86:89], v[22:25], v[206:209], v[66:69]
	s_waitcnt lgkmcnt(3)
	v_mfma_f32_16x16x32_bf16 v[66:69], v[26:29], v[2:5], v[110:113]
	s_waitcnt lgkmcnt(2)
	v_mfma_f32_16x16x32_bf16 v[74:77], v[30:33], v[6:9], v[66:69]
	v_mfma_f32_16x16x32_bf16 v[66:69], v[26:29], v[172:175], v[106:109]
	v_mfma_f32_16x16x32_bf16 v[78:81], v[30:33], v[206:209], v[66:69]
	s_waitcnt lgkmcnt(1)
	v_mfma_f32_16x16x32_bf16 v[66:69], v[212:215], v[2:5], v[130:133]
	v_mfma_f32_16x16x32_bf16 v[70:73], v[212:215], v[172:175], v[98:101]
	s_waitcnt lgkmcnt(0)
	v_mfma_f32_16x16x32_bf16 v[66:69], v[228:231], v[6:9], v[66:69]
	v_mfma_f32_16x16x32_bf16 v[70:73], v[228:231], v[206:209], v[70:73]
	s_setprio 0
	s_barrier
	ds_read_b128 v[130:133], v178
	ds_read_b128 v[176:179], v179
	ds_read_b128 v[232:235], v180
	ds_read_b128 v[236:239], v181
	s_waitcnt vmcnt(0)
	s_barrier
	s_waitcnt lgkmcnt(0)
	s_setprio 1
	s_waitcnt lgkmcnt(3)
	v_mfma_f32_16x16x32_bf16 v[98:101], v[10:13], v[130:133], v[216:219]
	s_waitcnt lgkmcnt(1)
	v_mfma_f32_16x16x32_bf16 v[10:13], v[10:13], v[232:235], v[90:93]
	s_waitcnt lgkmcnt(0)
	v_mfma_f32_16x16x32_bf16 v[126:129], v[14:17], v[236:239], v[10:13]
	v_mfma_f32_16x16x32_bf16 v[10:13], v[18:21], v[130:133], v[160:163]
	v_mfma_f32_16x16x32_bf16 v[114:117], v[22:25], v[176:179], v[10:13]
	v_mfma_f32_16x16x32_bf16 v[10:13], v[18:21], v[232:235], v[164:167]
	v_mfma_f32_16x16x32_bf16 v[118:121], v[22:25], v[236:239], v[10:13]
	v_mfma_f32_16x16x32_bf16 v[10:13], v[26:29], v[130:133], v[182:185]
	v_mfma_f32_16x16x32_bf16 v[106:109], v[30:33], v[176:179], v[10:13]
	v_mfma_f32_16x16x32_bf16 v[10:13], v[26:29], v[232:235], v[186:189]
	v_mfma_f32_16x16x32_bf16 v[110:113], v[30:33], v[236:239], v[10:13]
	v_mfma_f32_16x16x32_bf16 v[10:13], v[212:215], v[130:133], v[190:193]
	v_mfma_f32_16x16x32_bf16 v[90:93], v[228:231], v[176:179], v[10:13]
	v_mfma_f32_16x16x32_bf16 v[10:13], v[212:215], v[232:235], v[194:197]
	v_mfma_f32_16x16x32_bf16 v[122:125], v[14:17], v[176:179], v[98:101]
	v_mfma_f32_16x16x32_bf16 v[98:101], v[228:231], v[236:239], v[10:13]
	s_setprio 0
	s_barrier
	ds_read_b128 v[160:163], v144 offset:49152
	ds_read_b128 v[164:167], v144 offset:50176
	ds_read_b128 v[180:183], v147 offset:49152
	ds_read_b128 v[184:187], v147 offset:50176
	ds_read_b128 v[188:191], v146 offset:49152
	ds_read_b128 v[192:195], v146 offset:50176
	ds_read_b128 v[212:215], v145 offset:49152
	ds_read_b128 v[142:145], v145 offset:50176
	s_barrier
	s_waitcnt lgkmcnt(0)
	s_setprio 1
	s_waitcnt lgkmcnt(7)
	v_mfma_f32_16x16x32_bf16 v[10:13], v[160:163], v[2:5], v[62:65]
	s_waitcnt lgkmcnt(6)
	v_mfma_f32_16x16x32_bf16 v[26:29], v[164:167], v[6:9], v[10:13]
	v_mfma_f32_16x16x32_bf16 v[10:13], v[160:163], v[172:175], v[58:61]
	v_mfma_f32_16x16x32_bf16 v[30:33], v[164:167], v[206:209], v[10:13]
	s_waitcnt lgkmcnt(5)
	v_mfma_f32_16x16x32_bf16 v[10:13], v[180:183], v[2:5], v[54:57]
	s_waitcnt lgkmcnt(4)
	v_mfma_f32_16x16x32_bf16 v[18:21], v[184:187], v[6:9], v[10:13]
	v_mfma_f32_16x16x32_bf16 v[10:13], v[180:183], v[172:175], v[50:53]
	v_mfma_f32_16x16x32_bf16 v[22:25], v[184:187], v[206:209], v[10:13]
	s_waitcnt lgkmcnt(3)
	v_mfma_f32_16x16x32_bf16 v[10:13], v[188:191], v[2:5], v[46:49]
	s_waitcnt lgkmcnt(1)
	v_mfma_f32_16x16x32_bf16 v[2:5], v[212:215], v[2:5], v[38:41]
	v_mfma_f32_16x16x32_bf16 v[10:13], v[192:195], v[6:9], v[10:13]
	v_mfma_f32_16x16x32_bf16 v[14:17], v[188:191], v[172:175], v[42:45]
	s_waitcnt lgkmcnt(0)
	v_mfma_f32_16x16x32_bf16 v[2:5], v[142:145], v[6:9], v[2:5]
	v_mfma_f32_16x16x32_bf16 v[6:9], v[212:215], v[172:175], v[34:37]
	v_mfma_f32_16x16x32_bf16 v[14:17], v[192:195], v[206:209], v[14:17]
	v_mfma_f32_16x16x32_bf16 v[6:9], v[142:145], v[206:209], v[6:9]
	s_setprio 0
	s_setprio 1
	v_mfma_f32_16x16x32_bf16 v[34:37], v[160:163], v[130:133], v[134:137]
	v_mfma_f32_16x16x32_bf16 v[58:61], v[164:167], v[176:179], v[34:37]
	v_mfma_f32_16x16x32_bf16 v[34:37], v[160:163], v[232:235], v[148:151]
	v_mfma_f32_16x16x32_bf16 v[62:65], v[164:167], v[236:239], v[34:37]
	v_mfma_f32_16x16x32_bf16 v[34:37], v[180:183], v[130:133], v[152:155]
	v_mfma_f32_16x16x32_bf16 v[50:53], v[184:187], v[176:179], v[34:37]
	v_mfma_f32_16x16x32_bf16 v[34:37], v[180:183], v[232:235], v[156:159]
	v_mfma_f32_16x16x32_bf16 v[54:57], v[184:187], v[236:239], v[34:37]
	v_mfma_f32_16x16x32_bf16 v[34:37], v[188:191], v[130:133], v[202:205]
	v_mfma_f32_16x16x32_bf16 v[42:45], v[192:195], v[176:179], v[34:37]
	v_mfma_f32_16x16x32_bf16 v[34:37], v[188:191], v[232:235], v[224:227]
	v_mfma_f32_16x16x32_bf16 v[46:49], v[192:195], v[236:239], v[34:37]
	v_mfma_f32_16x16x32_bf16 v[34:37], v[212:215], v[130:133], v[168:171]
	v_mfma_f32_16x16x32_bf16 v[38:41], v[212:215], v[232:235], v[198:201]
	v_mfma_f32_16x16x32_bf16 v[34:37], v[142:145], v[176:179], v[34:37]
	v_mfma_f32_16x16x32_bf16 v[38:41], v[142:145], v[236:239], v[38:41]
	s_setprio 0
	s_movk_i32 s4, 0x100
	v_cmp_gt_u32_e32 vcc, s4, v1
	s_barrier
	s_and_saveexec_b64 s[4:5], vcc
	s_cbranch_execz .LBB0_1356
	s_barrier
.LBB0_1356:
	s_or_b64 exec, exec, s[4:5]
	v_lshlrev_b32_e32 v132, 2, v139
	v_lshl_or_b32 v131, v140, 2, v141
	v_lshl_or_b32 v132, v138, 7, v132
	v_mov_b32_e32 v1, v210
	v_mad_u64_u32 v[132:133], s[4:5], v131, s96, v[132:133]
	s_barrier
	ds_write2_b32 v132, v94, v102 offset1:16
	ds_write2_b32 v132, v122, v126 offset0:128 offset1:144
	v_add_u32_e32 v94, 0x400, v132
	ds_write2_b32 v94, v95, v103 offset0:4 offset1:20
	ds_write2_b32 v94, v123, v127 offset0:132 offset1:148
	v_add_u32_e32 v95, 0x800, v132
	ds_write2_b32 v95, v96, v104 offset0:8 offset1:24
	ds_write2_b32 v95, v124, v128 offset0:136 offset1:152
	v_add_u32_e32 v96, 0xc00, v132
	ds_write2_b32 v96, v97, v105 offset0:12 offset1:28
	ds_write2_b32 v96, v125, v129 offset0:140 offset1:156
	v_add_u32_e32 v97, 0x4000, v132
	ds_write2_b32 v97, v82, v86 offset0:64 offset1:80
	ds_write2_b32 v97, v114, v118 offset0:192 offset1:208
	v_add_u32_e32 v82, 0x4400, v132
	ds_write2_b32 v82, v83, v87 offset0:68 offset1:84
	ds_write2_b32 v82, v115, v119 offset0:196 offset1:212
	v_add_u32_e32 v83, 0x4800, v132
	ds_write2_b32 v83, v84, v88 offset0:72 offset1:88
	ds_write2_b32 v83, v116, v120 offset0:200 offset1:216
	v_add_u32_e32 v84, 0x4c00, v132
	ds_write2_b32 v84, v85, v89 offset0:76 offset1:92
	ds_write2_b32 v84, v117, v121 offset0:204 offset1:220
	v_add_u32_e32 v85, 0x8000, v132
	ds_write2_b32 v85, v74, v78 offset0:128 offset1:144
	v_add_u32_e32 v74, 0x8400, v132
	ds_write2_b32 v74, v106, v110 offset1:16
	ds_write2_b32 v74, v75, v79 offset0:132 offset1:148
	v_add_u32_e32 v75, 0x8800, v132
	ds_write2_b32 v75, v107, v111 offset0:4 offset1:20
	ds_write2_b32 v75, v76, v80 offset0:136 offset1:152
	v_add_u32_e32 v76, 0x8c00, v132
	v_add_u32_e32 v78, 0xc000, v132
	v_readlane_b32 s4, v254, 60
	ds_write2_b32 v76, v108, v112 offset0:8 offset1:24
	ds_write2_b32 v76, v77, v81 offset0:140 offset1:156
	v_add_u32_e32 v77, 0x9000, v132
	ds_write2_b32 v78, v66, v70 offset0:192 offset1:208
	v_add_u32_e32 v70, 0xc400, v132
	s_add_i32 s4, s19, s4
	s_lshl_b64 s[0:1], s[0:1], 2
	v_readlane_b32 s8, v254, 37
	v_lshlrev_b32_e32 v130, 4, v1
	ds_write2_b32 v77, v109, v113 offset0:12 offset1:28
	ds_write2_b32 v70, v90, v98 offset0:64 offset1:80
	ds_write2_b32 v70, v67, v71 offset0:196 offset1:212
	v_add_u32_e32 v71, 0xc800, v132
	v_readlane_b32 s9, v254, 38
	s_add_u32 s0, s8, s0
	v_and_b32_e32 v130, 0x3f0, v130
	ds_write2_b32 v71, v91, v99 offset0:68 offset1:84
	ds_write2_b32 v71, v68, v72 offset0:200 offset1:216
	v_add_u32_e32 v68, 0xcc00, v132
	s_addc_u32 s1, s9, s1
	v_mov_b32_e32 v131, v0
	ds_write2_b32 v68, v92, v100 offset0:72 offset1:88
	ds_write2_b32 v68, v69, v73 offset0:204 offset1:220
	v_add_u32_e32 v69, 0xd000, v132
	v_lshl_add_u64 v[66:67], s[0:1], 0, v[130:131]
	s_mov_b32 s0, 0
	ds_write2_b32 v69, v93, v101 offset0:76 offset1:92
	s_waitcnt lgkmcnt(0)
	s_barrier
	v_readlane_b32 s10, v254, 39
	v_readlane_b32 s11, v254, 40
	v_readfirstlane_b32 s6, v66
	v_readfirstlane_b32 s7, v67
	v_lshrrev_b32_e32 v81, 6, v1
	v_lshlrev_b32_e32 v80, 12, v81
	v_or_b32_e32 v79, v80, v130
	v_mov_b32_e32 v80, v79
	v_mad_u32_u24 v81, v81, s96, v130
	s_nop 3
	s_lshl_b32 s0, s4, 12
	s_add_u32 s6, s6, s0
	s_addc_u32 s7, s7, 0
	global_load_dwordx4 v[98:101], v79, s[6:7]
	v_add_u32_e32 v79, 0x8000, v79
	global_load_dwordx4 v[102:105], v79, s[6:7]
	v_add_u32_e32 v79, 0x8000, v79
	global_load_dwordx4 v[106:109], v79, s[6:7]
	v_add_u32_e32 v79, 0x8000, v79
	global_load_dwordx4 v[110:113], v79, s[6:7]
	v_add_u32_e32 v79, 0x8000, v79
	global_load_dwordx4 v[114:117], v79, s[6:7]
	v_add_u32_e32 v79, 0x8000, v79
	global_load_dwordx4 v[118:121], v79, s[6:7]
	v_add_u32_e32 v79, 0x8000, v79
	global_load_dwordx4 v[122:125], v79, s[6:7]
	v_add_u32_e32 v79, 0x8000, v79
	global_load_dwordx4 v[126:129], v79, s[6:7]
	v_add_u32_e32 v79, 0x8000, v79
	ds_read_b128 v[86:89], v81
	ds_read_b128 v[90:93], v81 offset:8320
	s_waitcnt vmcnt(7) lgkmcnt(1)
	v_pk_add_f32 v[86:87], v[86:87], v[98:99]
	v_pk_add_f32 v[88:89], v[88:89], v[100:101]
	global_store_dwordx4 v80, v[86:89], s[6:7]
	v_add_u32_e32 v80, 0x8000, v80
	global_load_dwordx4 v[98:101], v79, s[6:7]
	v_add_u32_e32 v79, 0x8000, v79
	ds_read_b128 v[86:89], v81 offset:16640
	s_waitcnt vmcnt(8) lgkmcnt(1)
	v_pk_add_f32 v[90:91], v[90:91], v[102:103]
	v_pk_add_f32 v[92:93], v[92:93], v[104:105]
	global_store_dwordx4 v80, v[90:93], s[6:7]
	v_add_u32_e32 v80, 0x8000, v80
	global_load_dwordx4 v[102:105], v79, s[6:7]
	v_add_u32_e32 v79, 0x8000, v79
	ds_read_b128 v[90:93], v81 offset:24960
	s_waitcnt vmcnt(9) lgkmcnt(1)
	v_pk_add_f32 v[86:87], v[86:87], v[106:107]
	v_pk_add_f32 v[88:89], v[88:89], v[108:109]
	global_store_dwordx4 v80, v[86:89], s[6:7]
	v_add_u32_e32 v80, 0x8000, v80
	global_load_dwordx4 v[106:109], v79, s[6:7]
	v_add_u32_e32 v79, 0x8000, v79
	ds_read_b128 v[86:89], v81 offset:33280
	s_waitcnt vmcnt(10) lgkmcnt(1)
	v_pk_add_f32 v[90:91], v[90:91], v[110:111]
	v_pk_add_f32 v[92:93], v[92:93], v[112:113]
	global_store_dwordx4 v80, v[90:93], s[6:7]
	v_add_u32_e32 v80, 0x8000, v80
	global_load_dwordx4 v[110:113], v79, s[6:7]
	v_add_u32_e32 v79, 0x8000, v79
	ds_read_b128 v[90:93], v81 offset:41600
	s_waitcnt vmcnt(11) lgkmcnt(1)
	v_pk_add_f32 v[86:87], v[86:87], v[114:115]
	v_pk_add_f32 v[88:89], v[88:89], v[116:117]
	global_store_dwordx4 v80, v[86:89], s[6:7]
	v_add_u32_e32 v80, 0x8000, v80
	global_load_dwordx4 v[114:117], v79, s[6:7]
	v_add_u32_e32 v79, 0x8000, v79
	ds_read_b128 v[86:89], v81 offset:49920
	s_waitcnt vmcnt(12) lgkmcnt(1)
	v_pk_add_f32 v[90:91], v[90:91], v[118:119]
	v_pk_add_f32 v[92:93], v[92:93], v[120:121]
	global_store_dwordx4 v80, v[90:93], s[6:7]
	v_add_u32_e32 v80, 0x8000, v80
	global_load_dwordx4 v[118:121], v79, s[6:7]
	v_add_u32_e32 v79, 0x8000, v79
	ds_read_b128 v[90:93], v81 offset:58240
	s_waitcnt vmcnt(13) lgkmcnt(1)
	v_pk_add_f32 v[86:87], v[86:87], v[122:123]
	v_pk_add_f32 v[88:89], v[88:89], v[124:125]
	global_store_dwordx4 v80, v[86:89], s[6:7]
	v_add_u32_e32 v80, 0x8000, v80
	global_load_dwordx4 v[122:125], v79, s[6:7]
	v_add_u32_e32 v79, 0x8000, v79
	v_add_u32_e32 v81, 0x10400, v81
	ds_read_b128 v[86:89], v81
	s_waitcnt vmcnt(14) lgkmcnt(1)
	v_pk_add_f32 v[90:91], v[90:91], v[126:127]
	v_pk_add_f32 v[92:93], v[92:93], v[128:129]
	global_store_dwordx4 v80, v[90:93], s[6:7]
	v_add_u32_e32 v80, 0x8000, v80
	global_load_dwordx4 v[126:129], v79, s[6:7]
	v_add_u32_e32 v79, 0x8000, v79
	ds_read_b128 v[90:93], v81 offset:8320
	s_waitcnt vmcnt(14) lgkmcnt(1)
	v_pk_add_f32 v[86:87], v[86:87], v[98:99]
	v_pk_add_f32 v[88:89], v[88:89], v[100:101]
	global_store_dwordx4 v80, v[86:89], s[6:7]
	v_add_u32_e32 v80, 0x8000, v80
	global_load_dwordx4 v[98:101], v79, s[6:7]
	v_add_u32_e32 v79, 0x8000, v79
	ds_read_b128 v[86:89], v81 offset:16640
	s_waitcnt vmcnt(14) lgkmcnt(1)
	v_pk_add_f32 v[90:91], v[90:91], v[102:103]
	v_pk_add_f32 v[92:93], v[92:93], v[104:105]
	global_store_dwordx4 v80, v[90:93], s[6:7]
	v_add_u32_e32 v80, 0x8000, v80
	global_load_dwordx4 v[102:105], v79, s[6:7]
	v_add_u32_e32 v79, 0x8000, v79
	ds_read_b128 v[90:93], v81 offset:24960
	s_waitcnt vmcnt(14) lgkmcnt(1)
	v_pk_add_f32 v[86:87], v[86:87], v[106:107]
	v_pk_add_f32 v[88:89], v[88:89], v[108:109]
	global_store_dwordx4 v80, v[86:89], s[6:7]
	v_add_u32_e32 v80, 0x8000, v80
	global_load_dwordx4 v[106:109], v79, s[6:7]
	v_add_u32_e32 v79, 0x8000, v79
	ds_read_b128 v[86:89], v81 offset:33280
	s_waitcnt vmcnt(14) lgkmcnt(1)
	v_pk_add_f32 v[90:91], v[90:91], v[110:111]
	v_pk_add_f32 v[92:93], v[92:93], v[112:113]
	global_store_dwordx4 v80, v[90:93], s[6:7]
	v_add_u32_e32 v80, 0x8000, v80
	global_load_dwordx4 v[110:113], v79, s[6:7]
	v_add_u32_e32 v79, 0x8000, v79
	ds_read_b128 v[90:93], v81 offset:41600
	s_waitcnt vmcnt(14) lgkmcnt(1)
	v_pk_add_f32 v[86:87], v[86:87], v[114:115]
	v_pk_add_f32 v[88:89], v[88:89], v[116:117]
	global_store_dwordx4 v80, v[86:89], s[6:7]
	v_add_u32_e32 v80, 0x8000, v80
	global_load_dwordx4 v[114:117], v79, s[6:7]
	v_add_u32_e32 v79, 0x8000, v79
	ds_read_b128 v[86:89], v81 offset:49920
	s_waitcnt vmcnt(14) lgkmcnt(1)
	v_pk_add_f32 v[90:91], v[90:91], v[118:119]
	v_pk_add_f32 v[92:93], v[92:93], v[120:121]
	global_store_dwordx4 v80, v[90:93], s[6:7]
	v_add_u32_e32 v80, 0x8000, v80
	global_load_dwordx4 v[118:121], v79, s[6:7]
	v_add_u32_e32 v79, 0x8000, v79
	ds_read_b128 v[90:93], v81 offset:58240
	s_waitcnt vmcnt(14) lgkmcnt(1)
	v_pk_add_f32 v[86:87], v[86:87], v[122:123]
	v_pk_add_f32 v[88:89], v[88:89], v[124:125]
	global_store_dwordx4 v80, v[86:89], s[6:7]
	v_add_u32_e32 v80, 0x8000, v80
	global_load_dwordx4 v[122:125], v79, s[6:7]
	v_add_u32_e32 v79, 0x8000, v79
	s_waitcnt vmcnt(14) lgkmcnt(0)
	v_pk_add_f32 v[90:91], v[90:91], v[126:127]
	v_pk_add_f32 v[92:93], v[92:93], v[128:129]
	global_store_dwordx4 v80, v[90:93], s[6:7]
	v_add_u32_e32 v80, 0x8000, v80
	global_load_dwordx4 v[126:129], v79, s[6:7]
	v_add_u32_e32 v79, 0x8000, v79
	v_readlane_b32 s0, v254, 61
	s_add_i32 s0, s0, s19
	s_mov_b32 s1, 0
	s_barrier
	ds_write2_b32 v132, v26, v30 offset1:16
	ds_write2_b32 v132, v58, v62 offset0:128 offset1:144
	ds_write2_b32 v94, v27, v31 offset0:4 offset1:20
	ds_write2_b32 v94, v59, v63 offset0:132 offset1:148
	ds_write2_b32 v95, v28, v32 offset0:8 offset1:24
	ds_write2_b32 v95, v60, v64 offset0:136 offset1:152
	ds_write2_b32 v96, v29, v33 offset0:12 offset1:28
	ds_write2_b32 v96, v61, v65 offset0:140 offset1:156
	ds_write2_b32 v97, v18, v22 offset0:64 offset1:80
	ds_write2_b32 v97, v50, v54 offset0:192 offset1:208
	ds_write2_b32 v82, v19, v23 offset0:68 offset1:84
	ds_write2_b32 v82, v51, v55 offset0:196 offset1:212
	ds_write2_b32 v83, v20, v24 offset0:72 offset1:88
	ds_write2_b32 v83, v52, v56 offset0:200 offset1:216
	ds_write2_b32 v84, v21, v25 offset0:76 offset1:92
	ds_write2_b32 v84, v53, v57 offset0:204 offset1:220
	ds_write2_b32 v85, v10, v14 offset0:128 offset1:144
	ds_write2_b32 v74, v42, v46 offset1:16
	ds_write2_b32 v74, v11, v15 offset0:132 offset1:148
	ds_write2_b32 v75, v43, v47 offset0:4 offset1:20
	ds_write2_b32 v75, v12, v16 offset0:136 offset1:152
	ds_write2_b32 v76, v44, v48 offset0:8 offset1:24
	ds_write2_b32 v76, v13, v17 offset0:140 offset1:156
	ds_write2_b32 v77, v45, v49 offset0:12 offset1:28
	ds_write2_b32 v78, v2, v6 offset0:192 offset1:208
	ds_write2_b32 v70, v34, v38 offset0:64 offset1:80
	ds_write2_b32 v70, v3, v7 offset0:196 offset1:212
	ds_write2_b32 v71, v35, v39 offset0:68 offset1:84
	ds_write2_b32 v71, v4, v8 offset0:200 offset1:216
	ds_write2_b32 v68, v36, v40 offset0:72 offset1:88
	ds_write2_b32 v68, v5, v9 offset0:204 offset1:220
	ds_write2_b32 v69, v37, v41 offset0:76 offset1:92
	s_waitcnt lgkmcnt(0)
	s_barrier
	v_add_u32_e32 v81, 0xfffefc00, v81
	ds_read_b128 v[86:89], v81
	ds_read_b128 v[90:93], v81 offset:8320
	s_waitcnt vmcnt(14) lgkmcnt(1)
	v_pk_add_f32 v[86:87], v[86:87], v[98:99]
	v_pk_add_f32 v[88:89], v[88:89], v[100:101]
	global_store_dwordx4 v80, v[86:89], s[6:7]
	v_add_u32_e32 v80, 0x8000, v80
	global_load_dwordx4 v[98:101], v79, s[6:7]
	v_add_u32_e32 v79, 0x8000, v79
	ds_read_b128 v[86:89], v81 offset:16640
	s_waitcnt vmcnt(14) lgkmcnt(1)
	v_pk_add_f32 v[90:91], v[90:91], v[102:103]
	v_pk_add_f32 v[92:93], v[92:93], v[104:105]
	global_store_dwordx4 v80, v[90:93], s[6:7]
	v_add_u32_e32 v80, 0x8000, v80
	global_load_dwordx4 v[102:105], v79, s[6:7]
	v_add_u32_e32 v79, 0x8000, v79
	ds_read_b128 v[90:93], v81 offset:24960
	s_waitcnt vmcnt(14) lgkmcnt(1)
	v_pk_add_f32 v[86:87], v[86:87], v[106:107]
	v_pk_add_f32 v[88:89], v[88:89], v[108:109]
	global_store_dwordx4 v80, v[86:89], s[6:7]
	v_add_u32_e32 v80, 0x8000, v80
	global_load_dwordx4 v[106:109], v79, s[6:7]
	v_add_u32_e32 v79, 0x8000, v79
	ds_read_b128 v[86:89], v81 offset:33280
	s_waitcnt vmcnt(14) lgkmcnt(1)
	v_pk_add_f32 v[90:91], v[90:91], v[110:111]
	v_pk_add_f32 v[92:93], v[92:93], v[112:113]
	global_store_dwordx4 v80, v[90:93], s[6:7]
	v_add_u32_e32 v80, 0x8000, v80
	global_load_dwordx4 v[110:113], v79, s[6:7]
	v_add_u32_e32 v79, 0x8000, v79
	ds_read_b128 v[90:93], v81 offset:41600
	s_waitcnt vmcnt(14) lgkmcnt(1)
	v_pk_add_f32 v[86:87], v[86:87], v[114:115]
	v_pk_add_f32 v[88:89], v[88:89], v[116:117]
	global_store_dwordx4 v80, v[86:89], s[6:7]
	v_add_u32_e32 v80, 0x8000, v80
	global_load_dwordx4 v[114:117], v79, s[6:7]
	v_add_u32_e32 v79, 0x8000, v79
	ds_read_b128 v[86:89], v81 offset:49920
	s_waitcnt vmcnt(14) lgkmcnt(1)
	v_pk_add_f32 v[90:91], v[90:91], v[118:119]
	v_pk_add_f32 v[92:93], v[92:93], v[120:121]
	global_store_dwordx4 v80, v[90:93], s[6:7]
	v_add_u32_e32 v80, 0x8000, v80
	global_load_dwordx4 v[118:121], v79, s[6:7]
	v_add_u32_e32 v79, 0x8000, v79
	ds_read_b128 v[90:93], v81 offset:58240
	s_waitcnt vmcnt(14) lgkmcnt(1)
	v_pk_add_f32 v[86:87], v[86:87], v[122:123]
	v_pk_add_f32 v[88:89], v[88:89], v[124:125]
	global_store_dwordx4 v80, v[86:89], s[6:7]
	v_add_u32_e32 v80, 0x8000, v80
	global_load_dwordx4 v[122:125], v79, s[6:7]
	v_add_u32_e32 v79, 0x8000, v79
	v_add_u32_e32 v81, 0x10400, v81
	ds_read_b128 v[86:89], v81
	s_waitcnt vmcnt(14) lgkmcnt(1)
	v_pk_add_f32 v[90:91], v[90:91], v[126:127]
	v_pk_add_f32 v[92:93], v[92:93], v[128:129]
	global_store_dwordx4 v80, v[90:93], s[6:7]
	v_add_u32_e32 v80, 0x8000, v80
	global_load_dwordx4 v[126:129], v79, s[6:7]
	v_add_u32_e32 v79, 0x8000, v79
	ds_read_b128 v[90:93], v81 offset:8320
	s_waitcnt vmcnt(14) lgkmcnt(1)
	v_pk_add_f32 v[86:87], v[86:87], v[98:99]
	v_pk_add_f32 v[88:89], v[88:89], v[100:101]
	global_store_dwordx4 v80, v[86:89], s[6:7]
	v_add_u32_e32 v80, 0x8000, v80
	s_nop 0
	ds_read_b128 v[86:89], v81 offset:16640
	s_waitcnt vmcnt(13) lgkmcnt(1)
	v_pk_add_f32 v[90:91], v[90:91], v[102:103]
	v_pk_add_f32 v[92:93], v[92:93], v[104:105]
	global_store_dwordx4 v80, v[90:93], s[6:7]
	v_add_u32_e32 v80, 0x8000, v80
	s_nop 0
	ds_read_b128 v[90:93], v81 offset:24960
	s_waitcnt vmcnt(12) lgkmcnt(1)
	v_pk_add_f32 v[86:87], v[86:87], v[106:107]
	v_pk_add_f32 v[88:89], v[88:89], v[108:109]
	global_store_dwordx4 v80, v[86:89], s[6:7]
	v_add_u32_e32 v80, 0x8000, v80
	s_nop 0
	ds_read_b128 v[86:89], v81 offset:33280
	s_waitcnt vmcnt(11) lgkmcnt(1)
	v_pk_add_f32 v[90:91], v[90:91], v[110:111]
	v_pk_add_f32 v[92:93], v[92:93], v[112:113]
	global_store_dwordx4 v80, v[90:93], s[6:7]
	v_add_u32_e32 v80, 0x8000, v80
	s_nop 0
	ds_read_b128 v[90:93], v81 offset:41600
	s_waitcnt vmcnt(10) lgkmcnt(1)
	v_pk_add_f32 v[86:87], v[86:87], v[114:115]
	v_pk_add_f32 v[88:89], v[88:89], v[116:117]
	global_store_dwordx4 v80, v[86:89], s[6:7]
	v_add_u32_e32 v80, 0x8000, v80
	s_nop 0
	ds_read_b128 v[86:89], v81 offset:49920
	s_waitcnt vmcnt(9) lgkmcnt(1)
	v_pk_add_f32 v[90:91], v[90:91], v[118:119]
	v_pk_add_f32 v[92:93], v[92:93], v[120:121]
	global_store_dwordx4 v80, v[90:93], s[6:7]
	v_add_u32_e32 v80, 0x8000, v80
	s_nop 0
	ds_read_b128 v[90:93], v81 offset:58240
	s_waitcnt vmcnt(8) lgkmcnt(1)
	v_pk_add_f32 v[86:87], v[86:87], v[122:123]
	v_pk_add_f32 v[88:89], v[88:89], v[124:125]
	global_store_dwordx4 v80, v[86:89], s[6:7]
	v_add_u32_e32 v80, 0x8000, v80
	s_nop 0
	s_waitcnt vmcnt(7) lgkmcnt(0)
	v_pk_add_f32 v[90:91], v[90:91], v[126:127]
	v_pk_add_f32 v[92:93], v[92:93], v[128:129]
	global_store_dwordx4 v80, v[90:93], s[6:7]
	v_add_u32_e32 v80, 0x8000, v80
	s_nop 0
	s_add_i32 s14, s14, s74
	s_cmpk_lt_i32 s14, 0x200
	v_mov_b32_e32 v252, v223
	s_cbranch_scc1 .LBB0_1345
	s_branch .LBB0_1362

.LBB0_1491:
	v_or_b32_e32 v161, 0x10000, v157
	v_or_b32_e32 v163, 0x10000, v159
	v_or_b32_e32 v162, 0x10000, v158
	ds_read_b128 v[172:175], v161
	ds_read_b128 v[176:179], v162
	v_or_b32_e32 v164, 0x10000, v160
	ds_read_b128 v[180:183], v163
	ds_read_b128 v[184:187], v164
	s_add_u32 s43, s25, s22
	s_addc_u32 s45, s41, s23
	s_add_u32 s44, s43, 0x80
	v_add_u32_e32 v165, 0xc000, v139
	s_addc_u32 s45, s45, 0
	v_readfirstlane_b32 s43, v165
	ds_read_b128 v[188:191], v141
	ds_read_b128 v[192:195], v141 offset:1024
	ds_read_b128 v[196:199], v144
	ds_read_b128 v[200:203], v144 offset:1024
	ds_read_b128 v[204:207], v143
	ds_read_b128 v[212:215], v143 offset:1024
	ds_read_b128 v[216:219], v142
	ds_read_b128 v[224:227], v142 offset:1024
	s_mov_b32 m0, s43
	v_lshl_add_u64 v[166:167], s[44:45], 0, v[132:133]
	global_load_lds_dwordx4 v[166:167], off
	v_add_u32_e32 v166, 0xe000, v139
	v_lshl_add_u64 v[168:169], s[44:45], 0, v[130:131]
	v_readfirstlane_b32 s43, v166
	s_mov_b32 m0, s43
	s_nop 0
	global_load_lds_dwordx4 v[168:169], off
	s_waitcnt lgkmcnt(8)
	s_barrier
	s_waitcnt lgkmcnt(0)
	s_setprio 1
	s_waitcnt lgkmcnt(0)
	v_mfma_f32_16x16x32_bf16 v[126:129], v[188:191], v[172:175], v[126:129]
	v_mfma_f32_16x16x32_bf16 v[122:125], v[188:191], v[180:183], v[122:125]
	v_mfma_f32_16x16x32_bf16 v[118:121], v[196:199], v[172:175], v[118:121]
	v_mfma_f32_16x16x32_bf16 v[114:117], v[196:199], v[180:183], v[114:117]
	v_mfma_f32_16x16x32_bf16 v[110:113], v[204:207], v[172:175], v[110:113]
	v_mfma_f32_16x16x32_bf16 v[106:109], v[204:207], v[180:183], v[106:109]
	v_mfma_f32_16x16x32_bf16 v[102:105], v[216:219], v[172:175], v[102:105]
	v_mfma_f32_16x16x32_bf16 v[98:101], v[216:219], v[180:183], v[98:101]
	v_mfma_f32_16x16x32_bf16 v[126:129], v[192:195], v[176:179], v[126:129]
	v_mfma_f32_16x16x32_bf16 v[122:125], v[192:195], v[184:187], v[122:125]
	v_mfma_f32_16x16x32_bf16 v[118:121], v[200:203], v[176:179], v[118:121]
	v_mfma_f32_16x16x32_bf16 v[114:117], v[200:203], v[184:187], v[114:117]
	v_mfma_f32_16x16x32_bf16 v[110:113], v[212:215], v[176:179], v[110:113]
	v_mfma_f32_16x16x32_bf16 v[106:109], v[212:215], v[184:187], v[106:109]
	v_mfma_f32_16x16x32_bf16 v[102:105], v[224:227], v[176:179], v[102:105]
	v_mfma_f32_16x16x32_bf16 v[98:101], v[224:227], v[184:187], v[98:101]
	s_setprio 0
	s_barrier
	s_add_u32 s43, s14, s22
	s_addc_u32 s46, s15, s23
	s_add_u32 s44, s43, 0x100
	v_or_b32_e32 v167, 0x14000, v157
	v_or_b32_e32 v169, 0x14000, v159
	s_addc_u32 s45, s46, 0
	v_readfirstlane_b32 s47, v145
	v_or_b32_e32 v168, 0x14000, v158
	ds_read_b128 v[228:231], v167
	ds_read_b128 v[232:235], v168
	v_or_b32_e32 v170, 0x14000, v160
	ds_read_b128 v[236:239], v169
	ds_read_b128 v[240:243], v170
	s_mov_b32 m0, s47
	v_lshl_add_u64 v[208:209], s[44:45], 0, v[132:133]
	global_load_lds_dwordx4 v[208:209], off
	v_lshl_add_u64 v[208:209], s[44:45], 0, v[130:131]
	v_readfirstlane_b32 s44, v146
	s_mov_b32 m0, s44
	s_nop 0
	global_load_lds_dwordx4 v[208:209], off
	s_barrier
	s_waitcnt lgkmcnt(0)
	s_setprio 1
	s_waitcnt lgkmcnt(0)
	v_mfma_f32_16x16x32_bf16 v[94:97], v[188:191], v[228:231], v[94:97]
	v_mfma_f32_16x16x32_bf16 v[90:93], v[188:191], v[236:239], v[90:93]
	v_mfma_f32_16x16x32_bf16 v[86:89], v[196:199], v[228:231], v[86:89]
	v_mfma_f32_16x16x32_bf16 v[82:85], v[196:199], v[236:239], v[82:85]
	v_mfma_f32_16x16x32_bf16 v[78:81], v[204:207], v[228:231], v[78:81]
	v_mfma_f32_16x16x32_bf16 v[74:77], v[204:207], v[236:239], v[74:77]
	v_mfma_f32_16x16x32_bf16 v[70:73], v[216:219], v[228:231], v[70:73]
	v_mfma_f32_16x16x32_bf16 v[66:69], v[216:219], v[236:239], v[66:69]
	v_mfma_f32_16x16x32_bf16 v[94:97], v[192:195], v[232:235], v[94:97]
	v_mfma_f32_16x16x32_bf16 v[90:93], v[192:195], v[240:243], v[90:93]
	v_mfma_f32_16x16x32_bf16 v[86:89], v[200:203], v[232:235], v[86:89]
	v_mfma_f32_16x16x32_bf16 v[82:85], v[200:203], v[240:243], v[82:85]
	v_mfma_f32_16x16x32_bf16 v[78:81], v[212:215], v[232:235], v[78:81]
	v_mfma_f32_16x16x32_bf16 v[74:77], v[212:215], v[240:243], v[74:77]
	v_mfma_f32_16x16x32_bf16 v[70:73], v[224:227], v[232:235], v[70:73]
	v_mfma_f32_16x16x32_bf16 v[66:69], v[224:227], v[240:243], v[66:69]
	s_setprio 0
	s_add_u32 s47, s16, s22
	s_addc_u32 s50, s17, s23
	s_add_u32 s44, s47, 0x100
	s_addc_u32 s45, s50, 0
	v_readfirstlane_b32 s51, v139
	s_barrier
	ds_read_b128 v[188:191], v141 offset:16384
	ds_read_b128 v[192:195], v141 offset:17408
	ds_read_b128 v[196:199], v144 offset:16384
	ds_read_b128 v[200:203], v144 offset:17408
	ds_read_b128 v[204:207], v143 offset:16384
	ds_read_b128 v[212:215], v143 offset:17408
	ds_read_b128 v[216:219], v142 offset:16384
	ds_read_b128 v[224:227], v142 offset:17408
	s_mov_b32 m0, s51
	v_lshl_add_u64 v[208:209], s[44:45], 0, v[132:133]
	global_load_lds_dwordx4 v[208:209], off
	v_lshl_add_u64 v[208:209], s[44:45], 0, v[130:131]
	v_readfirstlane_b32 s44, v140
	s_mov_b32 m0, s44
	s_nop 0
	global_load_lds_dwordx4 v[208:209], off
	s_barrier
	s_waitcnt lgkmcnt(0)
	s_setprio 1
	s_waitcnt lgkmcnt(0)
	v_mfma_f32_16x16x32_bf16 v[62:65], v[188:191], v[172:175], v[62:65]
	v_mfma_f32_16x16x32_bf16 v[58:61], v[188:191], v[180:183], v[58:61]
	v_mfma_f32_16x16x32_bf16 v[54:57], v[196:199], v[172:175], v[54:57]
	v_mfma_f32_16x16x32_bf16 v[50:53], v[196:199], v[180:183], v[50:53]
	v_mfma_f32_16x16x32_bf16 v[46:49], v[204:207], v[172:175], v[46:49]
	v_mfma_f32_16x16x32_bf16 v[42:45], v[204:207], v[180:183], v[42:45]
	v_mfma_f32_16x16x32_bf16 v[38:41], v[216:219], v[172:175], v[38:41]
	v_mfma_f32_16x16x32_bf16 v[34:37], v[216:219], v[180:183], v[34:37]
	v_mfma_f32_16x16x32_bf16 v[62:65], v[192:195], v[176:179], v[62:65]
	v_mfma_f32_16x16x32_bf16 v[58:61], v[192:195], v[184:187], v[58:61]
	v_mfma_f32_16x16x32_bf16 v[54:57], v[200:203], v[176:179], v[54:57]
	v_mfma_f32_16x16x32_bf16 v[50:53], v[200:203], v[184:187], v[50:53]
	v_mfma_f32_16x16x32_bf16 v[46:49], v[212:215], v[176:179], v[46:49]
	v_mfma_f32_16x16x32_bf16 v[42:45], v[212:215], v[184:187], v[42:45]
	v_mfma_f32_16x16x32_bf16 v[38:41], v[224:227], v[176:179], v[38:41]
	v_mfma_f32_16x16x32_bf16 v[34:37], v[224:227], v[184:187], v[34:37]
	s_setprio 0
	s_barrier
	s_add_u32 s51, s18, s22
	s_addc_u32 s52, s19, s23
	s_add_u32 s44, s51, 0x100
	s_addc_u32 s45, s52, 0
	v_readfirstlane_b32 s53, v147
	s_mov_b32 m0, s53
	v_lshl_add_u64 v[172:173], s[44:45], 0, v[132:133]
	global_load_lds_dwordx4 v[172:173], off
	v_lshl_add_u64 v[172:173], s[44:45], 0, v[130:131]
	v_readfirstlane_b32 s44, v148
	s_mov_b32 m0, s44
	s_nop 0
	global_load_lds_dwordx4 v[172:173], off
	s_waitcnt vmcnt(6)
	s_barrier
	s_setprio 1
	v_mfma_f32_16x16x32_bf16 v[30:33], v[188:191], v[228:231], v[30:33]
	v_mfma_f32_16x16x32_bf16 v[26:29], v[188:191], v[236:239], v[26:29]
	v_mfma_f32_16x16x32_bf16 v[22:25], v[196:199], v[228:231], v[22:25]
	v_mfma_f32_16x16x32_bf16 v[18:21], v[196:199], v[236:239], v[18:21]
	v_mfma_f32_16x16x32_bf16 v[14:17], v[204:207], v[228:231], v[14:17]
	v_mfma_f32_16x16x32_bf16 v[10:13], v[204:207], v[236:239], v[10:13]
	v_mfma_f32_16x16x32_bf16 v[6:9], v[216:219], v[228:231], v[6:9]
	v_mfma_f32_16x16x32_bf16 v[2:5], v[216:219], v[236:239], v[2:5]
	v_mfma_f32_16x16x32_bf16 v[30:33], v[192:195], v[232:235], v[30:33]
	v_mfma_f32_16x16x32_bf16 v[26:29], v[192:195], v[240:243], v[26:29]
	v_mfma_f32_16x16x32_bf16 v[22:25], v[200:203], v[232:235], v[22:25]
	v_mfma_f32_16x16x32_bf16 v[18:21], v[200:203], v[240:243], v[18:21]
	v_mfma_f32_16x16x32_bf16 v[14:17], v[212:215], v[232:235], v[14:17]
	v_mfma_f32_16x16x32_bf16 v[10:13], v[212:215], v[240:243], v[10:13]
	v_mfma_f32_16x16x32_bf16 v[6:9], v[224:227], v[232:235], v[6:9]
	v_mfma_f32_16x16x32_bf16 v[2:5], v[224:227], v[240:243], v[2:5]
	s_setprio 0
	v_or_b32_e32 v171, 0x18000, v157
	v_or_b32_e32 v173, 0x18000, v159
	s_barrier
	v_or_b32_e32 v172, 0x18000, v158
	ds_read_b128 v[180:183], v171
	ds_read_b128 v[184:187], v172
	v_or_b32_e32 v174, 0x18000, v160
	ds_read_b128 v[188:191], v173
	ds_read_b128 v[192:195], v174
	s_add_u32 s44, s11, s22
	s_addc_u32 s45, s24, s23
	v_readfirstlane_b32 s53, v149
	ds_read_b128 v[196:199], v141 offset:32768
	ds_read_b128 v[200:203], v141 offset:33792
	ds_read_b128 v[204:207], v144 offset:32768
	ds_read_b128 v[212:215], v144 offset:33792
	ds_read_b128 v[216:219], v143 offset:32768
	ds_read_b128 v[224:227], v143 offset:33792
	ds_read_b128 v[228:231], v142 offset:32768
	ds_read_b128 v[232:235], v142 offset:33792
	s_mov_b32 m0, s53
	v_lshl_add_u64 v[176:177], s[44:45], 0, v[132:133]
	global_load_lds_dwordx4 v[176:177], off
	v_lshl_add_u64 v[176:177], s[44:45], 0, v[130:131]
	v_readfirstlane_b32 s44, v150
	s_mov_b32 m0, s44
	s_nop 0
	global_load_lds_dwordx4 v[176:177], off
	s_waitcnt lgkmcnt(8)
	s_barrier
	s_waitcnt lgkmcnt(0)
	s_setprio 1
	s_waitcnt lgkmcnt(0)
	v_mfma_f32_16x16x32_bf16 v[126:129], v[196:199], v[180:183], v[126:129]
	v_mfma_f32_16x16x32_bf16 v[122:125], v[196:199], v[188:191], v[122:125]
	v_mfma_f32_16x16x32_bf16 v[118:121], v[204:207], v[180:183], v[118:121]
	v_mfma_f32_16x16x32_bf16 v[114:117], v[204:207], v[188:191], v[114:117]
	v_mfma_f32_16x16x32_bf16 v[110:113], v[216:219], v[180:183], v[110:113]
	v_mfma_f32_16x16x32_bf16 v[106:109], v[216:219], v[188:191], v[106:109]
	v_mfma_f32_16x16x32_bf16 v[102:105], v[228:231], v[180:183], v[102:105]
	v_mfma_f32_16x16x32_bf16 v[98:101], v[228:231], v[188:191], v[98:101]
	v_mfma_f32_16x16x32_bf16 v[126:129], v[200:203], v[184:187], v[126:129]
	v_mfma_f32_16x16x32_bf16 v[122:125], v[200:203], v[192:195], v[122:125]
	v_mfma_f32_16x16x32_bf16 v[118:121], v[212:215], v[184:187], v[118:121]
	v_mfma_f32_16x16x32_bf16 v[114:117], v[212:215], v[192:195], v[114:117]
	v_mfma_f32_16x16x32_bf16 v[110:113], v[224:227], v[184:187], v[110:113]
	v_mfma_f32_16x16x32_bf16 v[106:109], v[224:227], v[192:195], v[106:109]
	v_mfma_f32_16x16x32_bf16 v[102:105], v[232:235], v[184:187], v[102:105]
	v_mfma_f32_16x16x32_bf16 v[98:101], v[232:235], v[192:195], v[98:101]
	s_setprio 0
	s_barrier
	s_add_u32 s44, s43, 0x180
	v_or_b32_e32 v175, 0x1c000, v157
	v_or_b32_e32 v177, 0x1c000, v159
	s_addc_u32 s45, s46, 0
	v_readfirstlane_b32 s43, v151
	v_or_b32_e32 v176, 0x1c000, v158
	ds_read_b128 v[236:239], v175
	ds_read_b128 v[240:243], v176
	v_or_b32_e32 v178, 0x1c000, v160
	ds_read_b128 v[244:247], v177
	ds_read_b128 v[248:251], v178
	s_mov_b32 m0, s43
	v_lshl_add_u64 v[208:209], s[44:45], 0, v[132:133]
	v_readfirstlane_b32 s43, v152
	global_load_lds_dwordx4 v[208:209], off
	v_lshl_add_u64 v[208:209], s[44:45], 0, v[130:131]
	s_mov_b32 m0, s43
	s_nop 0
	global_load_lds_dwordx4 v[208:209], off
	s_barrier
	s_waitcnt lgkmcnt(0)
	s_setprio 1
	s_waitcnt lgkmcnt(0)
	v_mfma_f32_16x16x32_bf16 v[94:97], v[196:199], v[236:239], v[94:97]
	v_mfma_f32_16x16x32_bf16 v[90:93], v[196:199], v[244:247], v[90:93]
	v_mfma_f32_16x16x32_bf16 v[86:89], v[204:207], v[236:239], v[86:89]
	v_mfma_f32_16x16x32_bf16 v[82:85], v[204:207], v[244:247], v[82:85]
	v_mfma_f32_16x16x32_bf16 v[78:81], v[216:219], v[236:239], v[78:81]
	v_mfma_f32_16x16x32_bf16 v[74:77], v[216:219], v[244:247], v[74:77]
	v_mfma_f32_16x16x32_bf16 v[70:73], v[228:231], v[236:239], v[70:73]
	v_mfma_f32_16x16x32_bf16 v[66:69], v[228:231], v[244:247], v[66:69]
	v_mfma_f32_16x16x32_bf16 v[94:97], v[200:203], v[240:243], v[94:97]
	v_mfma_f32_16x16x32_bf16 v[90:93], v[200:203], v[248:251], v[90:93]
	v_mfma_f32_16x16x32_bf16 v[86:89], v[212:215], v[240:243], v[86:89]
	v_mfma_f32_16x16x32_bf16 v[82:85], v[212:215], v[248:251], v[82:85]
	v_mfma_f32_16x16x32_bf16 v[78:81], v[224:227], v[240:243], v[78:81]
	v_mfma_f32_16x16x32_bf16 v[74:77], v[224:227], v[248:251], v[74:77]
	v_mfma_f32_16x16x32_bf16 v[70:73], v[232:235], v[240:243], v[70:73]
	v_mfma_f32_16x16x32_bf16 v[66:69], v[232:235], v[248:251], v[66:69]
	s_setprio 0
	s_add_u32 s44, s47, 0x180
	s_addc_u32 s45, s50, 0
	v_readfirstlane_b32 s43, v153
	s_barrier
	ds_read_b128 v[196:199], v141 offset:49152
	ds_read_b128 v[200:203], v141 offset:50176
	ds_read_b128 v[204:207], v144 offset:49152
	ds_read_b128 v[212:215], v144 offset:50176
	ds_read_b128 v[216:219], v143 offset:49152
	ds_read_b128 v[224:227], v143 offset:50176
	ds_read_b128 v[228:231], v142 offset:49152
	ds_read_b128 v[232:235], v142 offset:50176
	s_mov_b32 m0, s43
	v_lshl_add_u64 v[208:209], s[44:45], 0, v[132:133]
	v_readfirstlane_b32 s43, v154
	global_load_lds_dwordx4 v[208:209], off
	v_lshl_add_u64 v[208:209], s[44:45], 0, v[130:131]
	s_mov_b32 m0, s43
	s_nop 0
	global_load_lds_dwordx4 v[208:209], off
	s_barrier
	s_waitcnt lgkmcnt(0)
	s_setprio 1
	s_waitcnt lgkmcnt(0)
	v_mfma_f32_16x16x32_bf16 v[62:65], v[196:199], v[180:183], v[62:65]
	v_mfma_f32_16x16x32_bf16 v[58:61], v[196:199], v[188:191], v[58:61]
	v_mfma_f32_16x16x32_bf16 v[54:57], v[204:207], v[180:183], v[54:57]
	v_mfma_f32_16x16x32_bf16 v[50:53], v[204:207], v[188:191], v[50:53]
	v_mfma_f32_16x16x32_bf16 v[46:49], v[216:219], v[180:183], v[46:49]
	v_mfma_f32_16x16x32_bf16 v[42:45], v[216:219], v[188:191], v[42:45]
	v_mfma_f32_16x16x32_bf16 v[38:41], v[228:231], v[180:183], v[38:41]
	v_mfma_f32_16x16x32_bf16 v[34:37], v[228:231], v[188:191], v[34:37]
	v_mfma_f32_16x16x32_bf16 v[62:65], v[200:203], v[184:187], v[62:65]
	v_mfma_f32_16x16x32_bf16 v[58:61], v[200:203], v[192:195], v[58:61]
	v_mfma_f32_16x16x32_bf16 v[54:57], v[212:215], v[184:187], v[54:57]
	v_mfma_f32_16x16x32_bf16 v[50:53], v[212:215], v[192:195], v[50:53]
	v_mfma_f32_16x16x32_bf16 v[46:49], v[224:227], v[184:187], v[46:49]
	v_mfma_f32_16x16x32_bf16 v[42:45], v[224:227], v[192:195], v[42:45]
	v_mfma_f32_16x16x32_bf16 v[38:41], v[232:235], v[184:187], v[38:41]
	v_mfma_f32_16x16x32_bf16 v[34:37], v[232:235], v[192:195], v[34:37]
	s_setprio 0
	s_barrier
	s_add_u32 s44, s51, 0x180
	s_addc_u32 s45, s52, 0
	v_readfirstlane_b32 s43, v155
	s_mov_b32 m0, s43
	v_lshl_add_u64 v[180:181], s[44:45], 0, v[132:133]
	v_readfirstlane_b32 s43, v156
	global_load_lds_dwordx4 v[180:181], off
	v_lshl_add_u64 v[180:181], s[44:45], 0, v[130:131]
	s_mov_b32 m0, s43
	s_nop 0
	global_load_lds_dwordx4 v[180:181], off
	s_waitcnt vmcnt(6)
	s_barrier
	s_setprio 1
	v_mfma_f32_16x16x32_bf16 v[30:33], v[196:199], v[236:239], v[30:33]
	v_mfma_f32_16x16x32_bf16 v[26:29], v[196:199], v[244:247], v[26:29]
	v_mfma_f32_16x16x32_bf16 v[22:25], v[204:207], v[236:239], v[22:25]
	v_mfma_f32_16x16x32_bf16 v[18:21], v[204:207], v[244:247], v[18:21]
	v_mfma_f32_16x16x32_bf16 v[14:17], v[216:219], v[236:239], v[14:17]
	v_mfma_f32_16x16x32_bf16 v[10:13], v[216:219], v[244:247], v[10:13]
	v_mfma_f32_16x16x32_bf16 v[6:9], v[228:231], v[236:239], v[6:9]
	v_mfma_f32_16x16x32_bf16 v[2:5], v[228:231], v[244:247], v[2:5]
	v_mfma_f32_16x16x32_bf16 v[30:33], v[200:203], v[240:243], v[30:33]
	v_mfma_f32_16x16x32_bf16 v[26:29], v[200:203], v[248:251], v[26:29]
	v_mfma_f32_16x16x32_bf16 v[22:25], v[212:215], v[240:243], v[22:25]
	v_mfma_f32_16x16x32_bf16 v[18:21], v[212:215], v[248:251], v[18:21]
	v_mfma_f32_16x16x32_bf16 v[14:17], v[224:227], v[240:243], v[14:17]
	v_mfma_f32_16x16x32_bf16 v[10:13], v[224:227], v[248:251], v[10:13]
	v_mfma_f32_16x16x32_bf16 v[6:9], v[232:235], v[240:243], v[6:9]
	v_mfma_f32_16x16x32_bf16 v[2:5], v[232:235], v[248:251], v[2:5]
	s_setprio 0
	s_add_i32 s42, s42, 2
	s_add_u32 s22, s22, 0x100
	s_addc_u32 s23, s23, 0
	s_cmp_lt_u32 s42, 12
	s_barrier
	s_cbranch_scc1 .LBB0_1491
	s_add_u32 s14, s20, 0x780
	s_addc_u32 s15, s21, 0
	v_readfirstlane_b32 s11, v165
	ds_read_b128 v[146:149], v161
	ds_read_b128 v[150:153], v162
	ds_read_b128 v[154:157], v163
	ds_read_b128 v[158:161], v164
	ds_read_b128 v[180:183], v141
	ds_read_b128 v[184:187], v141 offset:1024
	ds_read_b128 v[188:191], v144
	ds_read_b128 v[192:195], v144 offset:1024
	ds_read_b128 v[196:199], v143
	ds_read_b128 v[200:203], v143 offset:1024
	ds_read_b128 v[204:207], v142
	ds_read_b128 v[212:215], v142 offset:1024
	s_mov_b32 m0, s11
	v_lshl_add_u64 v[132:133], s[14:15], 0, v[132:133]
	v_readfirstlane_b32 s11, v166
	global_load_lds_dwordx4 v[132:133], off
	v_lshl_add_u64 v[130:131], s[14:15], 0, v[130:131]
	s_mov_b32 m0, s11
	s_nop 0
	global_load_lds_dwordx4 v[130:131], off
	s_barrier
	s_waitcnt lgkmcnt(0)
	s_setprio 1
	s_waitcnt lgkmcnt(0)
	v_mfma_f32_16x16x32_bf16 v[126:129], v[180:183], v[146:149], v[126:129]
	v_mfma_f32_16x16x32_bf16 v[122:125], v[180:183], v[154:157], v[122:125]
	v_mfma_f32_16x16x32_bf16 v[110:113], v[196:199], v[146:149], v[110:113]
	v_mfma_f32_16x16x32_bf16 v[106:109], v[196:199], v[154:157], v[106:109]
	v_mfma_f32_16x16x32_bf16 v[126:129], v[184:187], v[150:153], v[126:129]
	v_mfma_f32_16x16x32_bf16 v[122:125], v[184:187], v[158:161], v[122:125]
	v_mfma_f32_16x16x32_bf16 v[118:121], v[188:191], v[146:149], v[118:121]
	v_mfma_f32_16x16x32_bf16 v[114:117], v[188:191], v[154:157], v[114:117]
	v_mfma_f32_16x16x32_bf16 v[110:113], v[200:203], v[150:153], v[110:113]
	v_mfma_f32_16x16x32_bf16 v[106:109], v[200:203], v[158:161], v[106:109]
	v_mfma_f32_16x16x32_bf16 v[102:105], v[204:207], v[146:149], v[102:105]
	v_mfma_f32_16x16x32_bf16 v[98:101], v[204:207], v[154:157], v[98:101]
	v_mfma_f32_16x16x32_bf16 v[130:133], v[192:195], v[150:153], v[118:121]
	v_mfma_f32_16x16x32_bf16 v[162:165], v[192:195], v[158:161], v[114:117]
	v_mfma_f32_16x16x32_bf16 v[216:219], v[212:215], v[150:153], v[102:105]
	v_mfma_f32_16x16x32_bf16 v[224:227], v[212:215], v[158:161], v[98:101]
	s_setprio 0
	s_barrier
	s_nop 0
	ds_read_b128 v[98:101], v167
	ds_read_b128 v[102:105], v168
	ds_read_b128 v[114:117], v169
	ds_read_b128 v[118:121], v170
	s_barrier
	s_waitcnt lgkmcnt(0)
	s_setprio 1
	s_waitcnt lgkmcnt(3)
	v_mfma_f32_16x16x32_bf16 v[94:97], v[180:183], v[98:101], v[94:97]
	s_waitcnt lgkmcnt(1)
	v_mfma_f32_16x16x32_bf16 v[90:93], v[180:183], v[114:117], v[90:93]
	v_mfma_f32_16x16x32_bf16 v[78:81], v[196:199], v[98:101], v[78:81]
	v_mfma_f32_16x16x32_bf16 v[74:77], v[196:199], v[114:117], v[74:77]
	v_mfma_f32_16x16x32_bf16 v[94:97], v[184:187], v[102:105], v[94:97]
	s_waitcnt lgkmcnt(0)
	v_mfma_f32_16x16x32_bf16 v[90:93], v[184:187], v[118:121], v[90:93]
	v_mfma_f32_16x16x32_bf16 v[86:89], v[188:191], v[98:101], v[86:89]
	v_mfma_f32_16x16x32_bf16 v[82:85], v[188:191], v[114:117], v[82:85]
	v_mfma_f32_16x16x32_bf16 v[78:81], v[200:203], v[102:105], v[78:81]
	v_mfma_f32_16x16x32_bf16 v[74:77], v[200:203], v[118:121], v[74:77]
	v_mfma_f32_16x16x32_bf16 v[70:73], v[204:207], v[98:101], v[70:73]
	v_mfma_f32_16x16x32_bf16 v[66:69], v[204:207], v[114:117], v[66:69]
	v_mfma_f32_16x16x32_bf16 v[166:169], v[192:195], v[102:105], v[86:89]
	v_mfma_f32_16x16x32_bf16 v[180:183], v[192:195], v[118:121], v[82:85]
	v_mfma_f32_16x16x32_bf16 v[184:187], v[212:215], v[102:105], v[70:73]
	v_mfma_f32_16x16x32_bf16 v[188:191], v[212:215], v[118:121], v[66:69]
	s_setprio 0
	s_barrier
	s_nop 1
	ds_read_b128 v[66:69], v141 offset:16384
	ds_read_b128 v[70:73], v141 offset:17408
	ds_read_b128 v[82:85], v144 offset:16384
	ds_read_b128 v[86:89], v144 offset:17408
	ds_read_b128 v[192:195], v143 offset:16384
	ds_read_b128 v[196:199], v143 offset:17408
	ds_read_b128 v[200:203], v142 offset:16384
	ds_read_b128 v[204:207], v142 offset:17408
	s_waitcnt vmcnt(4)
	s_barrier
	s_waitcnt lgkmcnt(0)
	s_setprio 1
	s_waitcnt lgkmcnt(7)
	v_mfma_f32_16x16x32_bf16 v[62:65], v[66:69], v[146:149], v[62:65]
	v_mfma_f32_16x16x32_bf16 v[58:61], v[66:69], v[154:157], v[58:61]
	s_waitcnt lgkmcnt(3)
	v_mfma_f32_16x16x32_bf16 v[46:49], v[192:195], v[146:149], v[46:49]
	v_mfma_f32_16x16x32_bf16 v[42:45], v[192:195], v[154:157], v[42:45]
	v_mfma_f32_16x16x32_bf16 v[62:65], v[70:73], v[150:153], v[62:65]
	v_mfma_f32_16x16x32_bf16 v[58:61], v[70:73], v[158:161], v[58:61]
	v_mfma_f32_16x16x32_bf16 v[54:57], v[82:85], v[146:149], v[54:57]
	v_mfma_f32_16x16x32_bf16 v[50:53], v[82:85], v[154:157], v[50:53]
	s_waitcnt lgkmcnt(2)
	v_mfma_f32_16x16x32_bf16 v[46:49], v[196:199], v[150:153], v[46:49]
	v_mfma_f32_16x16x32_bf16 v[42:45], v[196:199], v[158:161], v[42:45]
	s_waitcnt lgkmcnt(1)
	v_mfma_f32_16x16x32_bf16 v[38:41], v[200:203], v[146:149], v[38:41]
	v_mfma_f32_16x16x32_bf16 v[34:37], v[200:203], v[154:157], v[34:37]
	v_mfma_f32_16x16x32_bf16 v[212:215], v[86:89], v[150:153], v[54:57]
	v_mfma_f32_16x16x32_bf16 v[228:231], v[86:89], v[158:161], v[50:53]
	s_waitcnt lgkmcnt(0)
	v_mfma_f32_16x16x32_bf16 v[146:149], v[204:207], v[150:153], v[38:41]
	v_mfma_f32_16x16x32_bf16 v[150:153], v[204:207], v[158:161], v[34:37]
	s_setprio 0
	s_setprio 1
	v_mfma_f32_16x16x32_bf16 v[30:33], v[66:69], v[98:101], v[30:33]
	v_mfma_f32_16x16x32_bf16 v[26:29], v[66:69], v[114:117], v[26:29]
	v_mfma_f32_16x16x32_bf16 v[14:17], v[192:195], v[98:101], v[14:17]
	v_mfma_f32_16x16x32_bf16 v[10:13], v[192:195], v[114:117], v[10:13]
	v_mfma_f32_16x16x32_bf16 v[30:33], v[70:73], v[102:105], v[30:33]
	v_mfma_f32_16x16x32_bf16 v[26:29], v[70:73], v[118:121], v[26:29]
	v_mfma_f32_16x16x32_bf16 v[22:25], v[82:85], v[98:101], v[22:25]
	v_mfma_f32_16x16x32_bf16 v[18:21], v[82:85], v[114:117], v[18:21]
	v_mfma_f32_16x16x32_bf16 v[14:17], v[196:199], v[102:105], v[14:17]
	v_mfma_f32_16x16x32_bf16 v[10:13], v[196:199], v[118:121], v[10:13]
	v_mfma_f32_16x16x32_bf16 v[6:9], v[200:203], v[98:101], v[6:9]
	v_mfma_f32_16x16x32_bf16 v[2:5], v[200:203], v[114:117], v[2:5]
	v_mfma_f32_16x16x32_bf16 v[154:157], v[86:89], v[102:105], v[22:25]
	v_mfma_f32_16x16x32_bf16 v[158:161], v[86:89], v[118:121], v[18:21]
	v_mfma_f32_16x16x32_bf16 v[192:195], v[204:207], v[102:105], v[6:9]
	v_mfma_f32_16x16x32_bf16 v[196:199], v[204:207], v[118:121], v[2:5]
	s_setprio 0
	s_barrier
	s_nop 1
	ds_read_b128 v[2:5], v171
	ds_read_b128 v[6:9], v172
	ds_read_b128 v[170:173], v173
	ds_read_b128 v[200:203], v174
	ds_read_b128 v[18:21], v141 offset:32768
	ds_read_b128 v[22:25], v141 offset:33792
	ds_read_b128 v[34:37], v144 offset:32768
	ds_read_b128 v[38:41], v144 offset:33792
	ds_read_b128 v[50:53], v143 offset:32768
	ds_read_b128 v[54:57], v143 offset:33792
	ds_read_b128 v[204:207], v142 offset:32768
	ds_read_b128 v[232:235], v142 offset:33792
	s_waitcnt vmcnt(2)
	s_barrier
	s_waitcnt lgkmcnt(0)
	s_setprio 1
	s_waitcnt lgkmcnt(7)
	v_mfma_f32_16x16x32_bf16 v[66:69], v[18:21], v[2:5], v[126:129]
	s_waitcnt lgkmcnt(6)
	v_mfma_f32_16x16x32_bf16 v[114:117], v[22:25], v[6:9], v[66:69]
	v_mfma_f32_16x16x32_bf16 v[66:69], v[18:21], v[170:173], v[122:125]
	v_mfma_f32_16x16x32_bf16 v[118:121], v[22:25], v[200:203], v[66:69]
	s_waitcnt lgkmcnt(5)
	v_mfma_f32_16x16x32_bf16 v[66:69], v[34:37], v[2:5], v[130:133]
	s_waitcnt lgkmcnt(4)
	v_mfma_f32_16x16x32_bf16 v[98:101], v[38:41], v[6:9], v[66:69]
	v_mfma_f32_16x16x32_bf16 v[66:69], v[34:37], v[170:173], v[162:165]
	v_mfma_f32_16x16x32_bf16 v[102:105], v[38:41], v[200:203], v[66:69]
	s_waitcnt lgkmcnt(3)
	v_mfma_f32_16x16x32_bf16 v[66:69], v[50:53], v[2:5], v[110:113]
	s_waitcnt lgkmcnt(2)
	v_mfma_f32_16x16x32_bf16 v[82:85], v[54:57], v[6:9], v[66:69]
	v_mfma_f32_16x16x32_bf16 v[66:69], v[50:53], v[170:173], v[106:109]
	v_mfma_f32_16x16x32_bf16 v[86:89], v[54:57], v[200:203], v[66:69]
	s_waitcnt lgkmcnt(1)
	v_mfma_f32_16x16x32_bf16 v[66:69], v[204:207], v[2:5], v[216:219]
	v_mfma_f32_16x16x32_bf16 v[70:73], v[204:207], v[170:173], v[224:227]
	s_waitcnt lgkmcnt(0)
	v_mfma_f32_16x16x32_bf16 v[66:69], v[232:235], v[6:9], v[66:69]
	v_mfma_f32_16x16x32_bf16 v[70:73], v[232:235], v[200:203], v[70:73]
	s_setprio 0
	s_barrier
	ds_read_b128 v[130:133], v175
	ds_read_b128 v[162:165], v176
	ds_read_b128 v[174:177], v177
	ds_read_b128 v[216:219], v178
	s_waitcnt vmcnt(0)
	s_barrier
	s_waitcnt lgkmcnt(0)
	s_setprio 1
	s_waitcnt lgkmcnt(3)
	v_mfma_f32_16x16x32_bf16 v[94:97], v[18:21], v[130:133], v[94:97]
	s_waitcnt lgkmcnt(1)
	v_mfma_f32_16x16x32_bf16 v[18:21], v[18:21], v[174:177], v[90:93]
	s_waitcnt lgkmcnt(0)
	v_mfma_f32_16x16x32_bf16 v[126:129], v[22:25], v[216:219], v[18:21]
	v_mfma_f32_16x16x32_bf16 v[18:21], v[34:37], v[130:133], v[166:169]
	v_mfma_f32_16x16x32_bf16 v[106:109], v[38:41], v[162:165], v[18:21]
	v_mfma_f32_16x16x32_bf16 v[18:21], v[34:37], v[174:177], v[180:183]
	v_mfma_f32_16x16x32_bf16 v[110:113], v[38:41], v[216:219], v[18:21]
	v_mfma_f32_16x16x32_bf16 v[18:21], v[50:53], v[130:133], v[78:81]
	v_mfma_f32_16x16x32_bf16 v[90:93], v[54:57], v[162:165], v[18:21]
	v_mfma_f32_16x16x32_bf16 v[18:21], v[50:53], v[174:177], v[74:77]
	v_mfma_f32_16x16x32_bf16 v[122:125], v[22:25], v[162:165], v[94:97]
	v_mfma_f32_16x16x32_bf16 v[94:97], v[54:57], v[216:219], v[18:21]
	v_mfma_f32_16x16x32_bf16 v[18:21], v[204:207], v[130:133], v[184:187]
	v_mfma_f32_16x16x32_bf16 v[74:77], v[232:235], v[162:165], v[18:21]
	v_mfma_f32_16x16x32_bf16 v[18:21], v[204:207], v[174:177], v[188:191]
	v_mfma_f32_16x16x32_bf16 v[78:81], v[232:235], v[216:219], v[18:21]
	s_setprio 0
	s_barrier
	ds_read_b128 v[166:169], v141 offset:49152
	ds_read_b128 v[178:181], v141 offset:50176
	ds_read_b128 v[182:185], v144 offset:49152
	ds_read_b128 v[186:189], v144 offset:50176
	ds_read_b128 v[204:207], v143 offset:49152
	ds_read_b128 v[224:227], v143 offset:50176
	ds_read_b128 v[232:235], v142 offset:49152
	ds_read_b128 v[140:143], v142 offset:50176
	s_barrier
	s_waitcnt lgkmcnt(0)
	s_setprio 1
	s_waitcnt lgkmcnt(7)
	v_mfma_f32_16x16x32_bf16 v[18:21], v[166:169], v[2:5], v[62:65]
	s_waitcnt lgkmcnt(6)
	v_mfma_f32_16x16x32_bf16 v[50:53], v[178:181], v[6:9], v[18:21]
	v_mfma_f32_16x16x32_bf16 v[18:21], v[166:169], v[170:173], v[58:61]
	v_mfma_f32_16x16x32_bf16 v[54:57], v[178:181], v[200:203], v[18:21]
	s_waitcnt lgkmcnt(5)
	v_mfma_f32_16x16x32_bf16 v[18:21], v[182:185], v[2:5], v[212:215]
	s_waitcnt lgkmcnt(4)
	v_mfma_f32_16x16x32_bf16 v[34:37], v[186:189], v[6:9], v[18:21]
	v_mfma_f32_16x16x32_bf16 v[18:21], v[182:185], v[170:173], v[228:231]
	v_mfma_f32_16x16x32_bf16 v[38:41], v[186:189], v[200:203], v[18:21]
	s_waitcnt lgkmcnt(3)
	v_mfma_f32_16x16x32_bf16 v[18:21], v[204:207], v[2:5], v[46:49]
	s_waitcnt lgkmcnt(1)
	v_mfma_f32_16x16x32_bf16 v[2:5], v[232:235], v[2:5], v[146:149]
	v_mfma_f32_16x16x32_bf16 v[18:21], v[224:227], v[6:9], v[18:21]
	v_mfma_f32_16x16x32_bf16 v[22:25], v[204:207], v[170:173], v[42:45]
	s_waitcnt lgkmcnt(0)
	v_mfma_f32_16x16x32_bf16 v[2:5], v[140:143], v[6:9], v[2:5]
	v_mfma_f32_16x16x32_bf16 v[6:9], v[232:235], v[170:173], v[150:153]
	v_mfma_f32_16x16x32_bf16 v[22:25], v[224:227], v[200:203], v[22:25]
	v_mfma_f32_16x16x32_bf16 v[6:9], v[140:143], v[200:203], v[6:9]
	s_setprio 0
	s_setprio 1
	v_mfma_f32_16x16x32_bf16 v[26:29], v[166:169], v[174:177], v[26:29]
	v_mfma_f32_16x16x32_bf16 v[62:65], v[178:181], v[216:219], v[26:29]
	v_mfma_f32_16x16x32_bf16 v[26:29], v[182:185], v[130:133], v[154:157]
	v_mfma_f32_16x16x32_bf16 v[30:33], v[166:169], v[130:133], v[30:33]
	v_mfma_f32_16x16x32_bf16 v[42:45], v[186:189], v[162:165], v[26:29]
	v_mfma_f32_16x16x32_bf16 v[26:29], v[182:185], v[174:177], v[158:161]
	v_mfma_f32_16x16x32_bf16 v[14:17], v[204:207], v[130:133], v[14:17]
	v_mfma_f32_16x16x32_bf16 v[10:13], v[204:207], v[174:177], v[10:13]
	v_mfma_f32_16x16x32_bf16 v[58:61], v[178:181], v[162:165], v[30:33]
	v_mfma_f32_16x16x32_bf16 v[46:49], v[186:189], v[216:219], v[26:29]
	v_mfma_f32_16x16x32_bf16 v[26:29], v[224:227], v[162:165], v[14:17]
	v_mfma_f32_16x16x32_bf16 v[30:33], v[224:227], v[216:219], v[10:13]
	v_mfma_f32_16x16x32_bf16 v[10:13], v[232:235], v[130:133], v[192:195]
	v_mfma_f32_16x16x32_bf16 v[14:17], v[232:235], v[174:177], v[196:199]
	v_mfma_f32_16x16x32_bf16 v[10:13], v[140:143], v[162:165], v[10:13]
	v_mfma_f32_16x16x32_bf16 v[14:17], v[140:143], v[216:219], v[14:17]
	s_setprio 0
	s_movk_i32 s11, 0x100
	v_cmp_gt_u32_e32 vcc, s11, v134
	s_barrier
	s_and_saveexec_b64 s[14:15], vcc
	s_cbranch_execz .LBB0_1494
	s_barrier

.LBB0_1733:
	v_or_b32_e32 v160, 0x10000, v156
	v_or_b32_e32 v162, 0x10000, v158
	v_or_b32_e32 v161, 0x10000, v157
	ds_read_b128 v[170:173], v160
	ds_read_b128 v[174:177], v161
	v_or_b32_e32 v163, 0x10000, v159
	ds_read_b128 v[178:181], v162
	ds_read_b128 v[182:185], v163
	s_add_u32 s25, s17, s14
	s_addc_u32 s27, s23, s15
	s_add_u32 s26, s25, 0x80
	v_add_u32_e32 v164, 0xc000, v138
	s_addc_u32 s27, s27, 0
	v_readfirstlane_b32 s25, v164
	v_add_u32_e32 v165, 0xe000, v138
	ds_read_b128 v[186:189], v140
	ds_read_b128 v[190:193], v140 offset:1024
	ds_read_b128 v[194:197], v143
	ds_read_b128 v[198:201], v143 offset:1024
	ds_read_b128 v[202:205], v142
	ds_read_b128 v[206:209], v142 offset:1024
	ds_read_b128 v[212:215], v141
	ds_read_b128 v[216:219], v141 offset:1024
	s_mov_b32 m0, s25
	v_lshl_add_u64 v[166:167], s[26:27], 0, v[132:133]
	v_readfirstlane_b32 s25, v165
	global_load_lds_dwordx4 v[166:167], off
	v_lshl_add_u64 v[166:167], s[26:27], 0, v[130:131]
	s_mov_b32 m0, s25
	s_nop 0
	global_load_lds_dwordx4 v[166:167], off
	s_waitcnt lgkmcnt(8)
	s_barrier
	s_waitcnt lgkmcnt(0)
	s_setprio 1
	s_waitcnt lgkmcnt(0)
	v_mfma_f32_16x16x32_bf16 v[126:129], v[186:189], v[170:173], v[126:129]
	v_mfma_f32_16x16x32_bf16 v[122:125], v[186:189], v[178:181], v[122:125]
	v_mfma_f32_16x16x32_bf16 v[118:121], v[194:197], v[170:173], v[118:121]
	v_mfma_f32_16x16x32_bf16 v[114:117], v[194:197], v[178:181], v[114:117]
	v_mfma_f32_16x16x32_bf16 v[110:113], v[202:205], v[170:173], v[110:113]
	v_mfma_f32_16x16x32_bf16 v[106:109], v[202:205], v[178:181], v[106:109]
	v_mfma_f32_16x16x32_bf16 v[102:105], v[212:215], v[170:173], v[102:105]
	v_mfma_f32_16x16x32_bf16 v[98:101], v[212:215], v[178:181], v[98:101]
	v_mfma_f32_16x16x32_bf16 v[126:129], v[190:193], v[174:177], v[126:129]
	v_mfma_f32_16x16x32_bf16 v[122:125], v[190:193], v[182:185], v[122:125]
	v_mfma_f32_16x16x32_bf16 v[118:121], v[198:201], v[174:177], v[118:121]
	v_mfma_f32_16x16x32_bf16 v[114:117], v[198:201], v[182:185], v[114:117]
	v_mfma_f32_16x16x32_bf16 v[110:113], v[206:209], v[174:177], v[110:113]
	v_mfma_f32_16x16x32_bf16 v[106:109], v[206:209], v[182:185], v[106:109]
	v_mfma_f32_16x16x32_bf16 v[102:105], v[216:219], v[174:177], v[102:105]
	v_mfma_f32_16x16x32_bf16 v[98:101], v[216:219], v[182:185], v[98:101]
	s_setprio 0
	s_barrier
	s_add_u32 s25, s6, s14
	s_addc_u32 s28, s7, s15
	s_add_u32 s26, s25, 0x100
	v_or_b32_e32 v166, 0x14000, v156
	v_or_b32_e32 v168, 0x14000, v158
	s_addc_u32 s27, s28, 0
	v_readfirstlane_b32 s29, v144
	v_or_b32_e32 v167, 0x14000, v157
	ds_read_b128 v[224:227], v166
	ds_read_b128 v[228:231], v167
	v_or_b32_e32 v169, 0x14000, v159
	ds_read_b128 v[232:235], v168
	ds_read_b128 v[236:239], v169
	s_mov_b32 m0, s29
	v_lshl_add_u64 v[240:241], s[26:27], 0, v[132:133]
	global_load_lds_dwordx4 v[240:241], off
	v_lshl_add_u64 v[240:241], s[26:27], 0, v[130:131]
	v_readfirstlane_b32 s26, v145
	s_mov_b32 m0, s26
	s_nop 0
	global_load_lds_dwordx4 v[240:241], off
	s_barrier
	s_waitcnt lgkmcnt(0)
	s_setprio 1
	s_waitcnt lgkmcnt(0)
	v_mfma_f32_16x16x32_bf16 v[94:97], v[186:189], v[224:227], v[94:97]
	v_mfma_f32_16x16x32_bf16 v[90:93], v[186:189], v[232:235], v[90:93]
	v_mfma_f32_16x16x32_bf16 v[86:89], v[194:197], v[224:227], v[86:89]
	v_mfma_f32_16x16x32_bf16 v[82:85], v[194:197], v[232:235], v[82:85]
	v_mfma_f32_16x16x32_bf16 v[78:81], v[202:205], v[224:227], v[78:81]
	v_mfma_f32_16x16x32_bf16 v[74:77], v[202:205], v[232:235], v[74:77]
	v_mfma_f32_16x16x32_bf16 v[70:73], v[212:215], v[224:227], v[70:73]
	v_mfma_f32_16x16x32_bf16 v[66:69], v[212:215], v[232:235], v[66:69]
	v_mfma_f32_16x16x32_bf16 v[94:97], v[190:193], v[228:231], v[94:97]
	v_mfma_f32_16x16x32_bf16 v[90:93], v[190:193], v[236:239], v[90:93]
	v_mfma_f32_16x16x32_bf16 v[86:89], v[198:201], v[228:231], v[86:89]
	v_mfma_f32_16x16x32_bf16 v[82:85], v[198:201], v[236:239], v[82:85]
	v_mfma_f32_16x16x32_bf16 v[78:81], v[206:209], v[228:231], v[78:81]
	v_mfma_f32_16x16x32_bf16 v[74:77], v[206:209], v[236:239], v[74:77]
	v_mfma_f32_16x16x32_bf16 v[70:73], v[216:219], v[228:231], v[70:73]
	v_mfma_f32_16x16x32_bf16 v[66:69], v[216:219], v[236:239], v[66:69]
	s_setprio 0
	s_add_u32 s29, s8, s14
	s_addc_u32 s30, s9, s15
	s_add_u32 s26, s29, 0x100
	s_addc_u32 s27, s30, 0
	v_readfirstlane_b32 s31, v138
	s_barrier
	ds_read_b128 v[186:189], v140 offset:16384
	ds_read_b128 v[190:193], v140 offset:17408
	ds_read_b128 v[194:197], v143 offset:16384
	ds_read_b128 v[198:201], v143 offset:17408
	ds_read_b128 v[202:205], v142 offset:16384
	ds_read_b128 v[206:209], v142 offset:17408
	ds_read_b128 v[212:215], v141 offset:16384
	ds_read_b128 v[216:219], v141 offset:17408
	s_mov_b32 m0, s31
	v_lshl_add_u64 v[240:241], s[26:27], 0, v[132:133]
	global_load_lds_dwordx4 v[240:241], off
	v_lshl_add_u64 v[240:241], s[26:27], 0, v[130:131]
	v_readfirstlane_b32 s26, v139
	s_mov_b32 m0, s26
	s_nop 0
	global_load_lds_dwordx4 v[240:241], off
	s_barrier
	s_waitcnt lgkmcnt(0)
	s_setprio 1
	s_waitcnt lgkmcnt(0)
	v_mfma_f32_16x16x32_bf16 v[62:65], v[186:189], v[170:173], v[62:65]
	v_mfma_f32_16x16x32_bf16 v[58:61], v[186:189], v[178:181], v[58:61]
	v_mfma_f32_16x16x32_bf16 v[54:57], v[194:197], v[170:173], v[54:57]
	v_mfma_f32_16x16x32_bf16 v[50:53], v[194:197], v[178:181], v[50:53]
	v_mfma_f32_16x16x32_bf16 v[46:49], v[202:205], v[170:173], v[46:49]
	v_mfma_f32_16x16x32_bf16 v[42:45], v[202:205], v[178:181], v[42:45]
	v_mfma_f32_16x16x32_bf16 v[38:41], v[212:215], v[170:173], v[38:41]
	v_mfma_f32_16x16x32_bf16 v[34:37], v[212:215], v[178:181], v[34:37]
	v_mfma_f32_16x16x32_bf16 v[62:65], v[190:193], v[174:177], v[62:65]
	v_mfma_f32_16x16x32_bf16 v[58:61], v[190:193], v[182:185], v[58:61]
	v_mfma_f32_16x16x32_bf16 v[54:57], v[198:201], v[174:177], v[54:57]
	v_mfma_f32_16x16x32_bf16 v[50:53], v[198:201], v[182:185], v[50:53]
	v_mfma_f32_16x16x32_bf16 v[46:49], v[206:209], v[174:177], v[46:49]
	v_mfma_f32_16x16x32_bf16 v[42:45], v[206:209], v[182:185], v[42:45]
	v_mfma_f32_16x16x32_bf16 v[38:41], v[216:219], v[174:177], v[38:41]
	v_mfma_f32_16x16x32_bf16 v[34:37], v[216:219], v[182:185], v[34:37]
	s_setprio 0
	s_barrier
	s_add_u32 s31, s10, s14
	s_addc_u32 s34, s11, s15
	s_add_u32 s26, s31, 0x100
	s_addc_u32 s27, s34, 0
	v_readfirstlane_b32 s35, v146
	s_mov_b32 m0, s35
	v_lshl_add_u64 v[170:171], s[26:27], 0, v[132:133]
	global_load_lds_dwordx4 v[170:171], off
	v_lshl_add_u64 v[170:171], s[26:27], 0, v[130:131]
	v_readfirstlane_b32 s26, v147
	s_mov_b32 m0, s26
	s_nop 0
	global_load_lds_dwordx4 v[170:171], off
	s_waitcnt vmcnt(6)
	s_barrier
	s_setprio 1
	v_mfma_f32_16x16x32_bf16 v[30:33], v[186:189], v[224:227], v[30:33]
	v_mfma_f32_16x16x32_bf16 v[26:29], v[186:189], v[232:235], v[26:29]
	v_mfma_f32_16x16x32_bf16 v[22:25], v[194:197], v[224:227], v[22:25]
	v_mfma_f32_16x16x32_bf16 v[18:21], v[194:197], v[232:235], v[18:21]
	v_mfma_f32_16x16x32_bf16 v[14:17], v[202:205], v[224:227], v[14:17]
	v_mfma_f32_16x16x32_bf16 v[10:13], v[202:205], v[232:235], v[10:13]
	v_mfma_f32_16x16x32_bf16 v[6:9], v[212:215], v[224:227], v[6:9]
	v_mfma_f32_16x16x32_bf16 v[2:5], v[212:215], v[232:235], v[2:5]
	v_mfma_f32_16x16x32_bf16 v[30:33], v[190:193], v[228:231], v[30:33]
	v_mfma_f32_16x16x32_bf16 v[26:29], v[190:193], v[236:239], v[26:29]
	v_mfma_f32_16x16x32_bf16 v[22:25], v[198:201], v[228:231], v[22:25]
	v_mfma_f32_16x16x32_bf16 v[18:21], v[198:201], v[236:239], v[18:21]
	v_mfma_f32_16x16x32_bf16 v[14:17], v[206:209], v[228:231], v[14:17]
	v_mfma_f32_16x16x32_bf16 v[10:13], v[206:209], v[236:239], v[10:13]
	v_mfma_f32_16x16x32_bf16 v[6:9], v[216:219], v[228:231], v[6:9]
	v_mfma_f32_16x16x32_bf16 v[2:5], v[216:219], v[236:239], v[2:5]
	s_setprio 0
	v_or_b32_e32 v170, 0x18000, v156
	v_or_b32_e32 v172, 0x18000, v158
	s_barrier
	v_or_b32_e32 v171, 0x18000, v157
	ds_read_b128 v[178:181], v170
	ds_read_b128 v[182:185], v171
	v_or_b32_e32 v173, 0x18000, v159
	ds_read_b128 v[186:189], v172
	ds_read_b128 v[190:193], v173
	s_add_u32 s26, s1, s14
	s_addc_u32 s27, s16, s15
	v_readfirstlane_b32 s35, v148
	ds_read_b128 v[194:197], v140 offset:32768
	ds_read_b128 v[198:201], v140 offset:33792
	ds_read_b128 v[202:205], v143 offset:32768
	ds_read_b128 v[206:209], v143 offset:33792
	ds_read_b128 v[212:215], v142 offset:32768
	ds_read_b128 v[216:219], v142 offset:33792
	ds_read_b128 v[224:227], v141 offset:32768
	ds_read_b128 v[228:231], v141 offset:33792
	s_mov_b32 m0, s35
	v_lshl_add_u64 v[174:175], s[26:27], 0, v[132:133]
	global_load_lds_dwordx4 v[174:175], off
	v_lshl_add_u64 v[174:175], s[26:27], 0, v[130:131]
	v_readfirstlane_b32 s26, v149
	s_mov_b32 m0, s26
	s_nop 0
	global_load_lds_dwordx4 v[174:175], off
	s_waitcnt lgkmcnt(8)
	s_barrier
	s_waitcnt lgkmcnt(0)
	s_setprio 1
	s_waitcnt lgkmcnt(0)
	v_mfma_f32_16x16x32_bf16 v[126:129], v[194:197], v[178:181], v[126:129]
	v_mfma_f32_16x16x32_bf16 v[122:125], v[194:197], v[186:189], v[122:125]
	v_mfma_f32_16x16x32_bf16 v[118:121], v[202:205], v[178:181], v[118:121]
	v_mfma_f32_16x16x32_bf16 v[114:117], v[202:205], v[186:189], v[114:117]
	v_mfma_f32_16x16x32_bf16 v[110:113], v[212:215], v[178:181], v[110:113]
	v_mfma_f32_16x16x32_bf16 v[106:109], v[212:215], v[186:189], v[106:109]
	v_mfma_f32_16x16x32_bf16 v[102:105], v[224:227], v[178:181], v[102:105]
	v_mfma_f32_16x16x32_bf16 v[98:101], v[224:227], v[186:189], v[98:101]
	v_mfma_f32_16x16x32_bf16 v[126:129], v[198:201], v[182:185], v[126:129]
	v_mfma_f32_16x16x32_bf16 v[122:125], v[198:201], v[190:193], v[122:125]
	v_mfma_f32_16x16x32_bf16 v[118:121], v[206:209], v[182:185], v[118:121]
	v_mfma_f32_16x16x32_bf16 v[114:117], v[206:209], v[190:193], v[114:117]
	v_mfma_f32_16x16x32_bf16 v[110:113], v[216:219], v[182:185], v[110:113]
	v_mfma_f32_16x16x32_bf16 v[106:109], v[216:219], v[190:193], v[106:109]
	v_mfma_f32_16x16x32_bf16 v[102:105], v[228:231], v[182:185], v[102:105]
	v_mfma_f32_16x16x32_bf16 v[98:101], v[228:231], v[190:193], v[98:101]
	s_setprio 0
	s_barrier
	s_add_u32 s26, s25, 0x180
	v_or_b32_e32 v174, 0x1c000, v156
	v_or_b32_e32 v176, 0x1c000, v158
	s_addc_u32 s27, s28, 0
	v_readfirstlane_b32 s25, v150
	v_or_b32_e32 v175, 0x1c000, v157
	ds_read_b128 v[232:235], v174
	ds_read_b128 v[236:239], v175
	v_or_b32_e32 v177, 0x1c000, v159
	ds_read_b128 v[240:243], v176
	ds_read_b128 v[244:247], v177
	s_mov_b32 m0, s25
	v_lshl_add_u64 v[248:249], s[26:27], 0, v[132:133]
	v_readfirstlane_b32 s25, v151
	global_load_lds_dwordx4 v[248:249], off
	v_lshl_add_u64 v[248:249], s[26:27], 0, v[130:131]
	s_mov_b32 m0, s25
	s_nop 0
	global_load_lds_dwordx4 v[248:249], off
	s_barrier
	s_waitcnt lgkmcnt(0)
	s_setprio 1
	s_waitcnt lgkmcnt(0)
	v_mfma_f32_16x16x32_bf16 v[94:97], v[194:197], v[232:235], v[94:97]
	v_mfma_f32_16x16x32_bf16 v[90:93], v[194:197], v[240:243], v[90:93]
	v_mfma_f32_16x16x32_bf16 v[86:89], v[202:205], v[232:235], v[86:89]
	v_mfma_f32_16x16x32_bf16 v[82:85], v[202:205], v[240:243], v[82:85]
	v_mfma_f32_16x16x32_bf16 v[78:81], v[212:215], v[232:235], v[78:81]
	v_mfma_f32_16x16x32_bf16 v[74:77], v[212:215], v[240:243], v[74:77]
	v_mfma_f32_16x16x32_bf16 v[70:73], v[224:227], v[232:235], v[70:73]
	v_mfma_f32_16x16x32_bf16 v[66:69], v[224:227], v[240:243], v[66:69]
	v_mfma_f32_16x16x32_bf16 v[94:97], v[198:201], v[236:239], v[94:97]
	v_mfma_f32_16x16x32_bf16 v[90:93], v[198:201], v[244:247], v[90:93]
	v_mfma_f32_16x16x32_bf16 v[86:89], v[206:209], v[236:239], v[86:89]
	v_mfma_f32_16x16x32_bf16 v[82:85], v[206:209], v[244:247], v[82:85]
	v_mfma_f32_16x16x32_bf16 v[78:81], v[216:219], v[236:239], v[78:81]
	v_mfma_f32_16x16x32_bf16 v[74:77], v[216:219], v[244:247], v[74:77]
	v_mfma_f32_16x16x32_bf16 v[70:73], v[228:231], v[236:239], v[70:73]
	v_mfma_f32_16x16x32_bf16 v[66:69], v[228:231], v[244:247], v[66:69]
	s_setprio 0
	s_add_u32 s26, s29, 0x180
	s_addc_u32 s27, s30, 0
	v_readfirstlane_b32 s25, v152
	s_barrier
	ds_read_b128 v[194:197], v140 offset:49152
	ds_read_b128 v[198:201], v140 offset:50176
	ds_read_b128 v[202:205], v143 offset:49152
	ds_read_b128 v[206:209], v143 offset:50176
	ds_read_b128 v[212:215], v142 offset:49152
	ds_read_b128 v[216:219], v142 offset:50176
	ds_read_b128 v[224:227], v141 offset:49152
	ds_read_b128 v[228:231], v141 offset:50176
	s_mov_b32 m0, s25
	v_lshl_add_u64 v[248:249], s[26:27], 0, v[132:133]
	v_readfirstlane_b32 s25, v153
	global_load_lds_dwordx4 v[248:249], off
	v_lshl_add_u64 v[248:249], s[26:27], 0, v[130:131]
	s_mov_b32 m0, s25
	s_nop 0
	global_load_lds_dwordx4 v[248:249], off
	s_barrier
	s_waitcnt lgkmcnt(0)
	s_setprio 1
	s_waitcnt lgkmcnt(0)
	v_mfma_f32_16x16x32_bf16 v[62:65], v[194:197], v[178:181], v[62:65]
	v_mfma_f32_16x16x32_bf16 v[58:61], v[194:197], v[186:189], v[58:61]
	v_mfma_f32_16x16x32_bf16 v[54:57], v[202:205], v[178:181], v[54:57]
	v_mfma_f32_16x16x32_bf16 v[50:53], v[202:205], v[186:189], v[50:53]
	v_mfma_f32_16x16x32_bf16 v[46:49], v[212:215], v[178:181], v[46:49]
	v_mfma_f32_16x16x32_bf16 v[42:45], v[212:215], v[186:189], v[42:45]
	v_mfma_f32_16x16x32_bf16 v[38:41], v[224:227], v[178:181], v[38:41]
	v_mfma_f32_16x16x32_bf16 v[34:37], v[224:227], v[186:189], v[34:37]
	v_mfma_f32_16x16x32_bf16 v[62:65], v[198:201], v[182:185], v[62:65]
	v_mfma_f32_16x16x32_bf16 v[58:61], v[198:201], v[190:193], v[58:61]
	v_mfma_f32_16x16x32_bf16 v[54:57], v[206:209], v[182:185], v[54:57]
	v_mfma_f32_16x16x32_bf16 v[50:53], v[206:209], v[190:193], v[50:53]
	v_mfma_f32_16x16x32_bf16 v[46:49], v[216:219], v[182:185], v[46:49]
	v_mfma_f32_16x16x32_bf16 v[42:45], v[216:219], v[190:193], v[42:45]
	v_mfma_f32_16x16x32_bf16 v[38:41], v[228:231], v[182:185], v[38:41]
	v_mfma_f32_16x16x32_bf16 v[34:37], v[228:231], v[190:193], v[34:37]
	s_setprio 0
	s_barrier
	s_add_u32 s26, s31, 0x180
	s_addc_u32 s27, s34, 0
	v_readfirstlane_b32 s25, v154
	s_mov_b32 m0, s25
	v_lshl_add_u64 v[178:179], s[26:27], 0, v[132:133]
	v_readfirstlane_b32 s25, v155
	global_load_lds_dwordx4 v[178:179], off
	v_lshl_add_u64 v[178:179], s[26:27], 0, v[130:131]
	s_mov_b32 m0, s25
	s_nop 0
	global_load_lds_dwordx4 v[178:179], off
	s_waitcnt vmcnt(6)
	s_barrier
	s_setprio 1
	v_mfma_f32_16x16x32_bf16 v[30:33], v[194:197], v[232:235], v[30:33]
	v_mfma_f32_16x16x32_bf16 v[26:29], v[194:197], v[240:243], v[26:29]
	v_mfma_f32_16x16x32_bf16 v[22:25], v[202:205], v[232:235], v[22:25]
	v_mfma_f32_16x16x32_bf16 v[18:21], v[202:205], v[240:243], v[18:21]
	v_mfma_f32_16x16x32_bf16 v[14:17], v[212:215], v[232:235], v[14:17]
	v_mfma_f32_16x16x32_bf16 v[10:13], v[212:215], v[240:243], v[10:13]
	v_mfma_f32_16x16x32_bf16 v[6:9], v[224:227], v[232:235], v[6:9]
	v_mfma_f32_16x16x32_bf16 v[2:5], v[224:227], v[240:243], v[2:5]
	v_mfma_f32_16x16x32_bf16 v[30:33], v[198:201], v[236:239], v[30:33]
	v_mfma_f32_16x16x32_bf16 v[26:29], v[198:201], v[244:247], v[26:29]
	v_mfma_f32_16x16x32_bf16 v[22:25], v[206:209], v[236:239], v[22:25]
	v_mfma_f32_16x16x32_bf16 v[18:21], v[206:209], v[244:247], v[18:21]
	v_mfma_f32_16x16x32_bf16 v[14:17], v[216:219], v[236:239], v[14:17]
	v_mfma_f32_16x16x32_bf16 v[10:13], v[216:219], v[244:247], v[10:13]
	v_mfma_f32_16x16x32_bf16 v[6:9], v[228:231], v[236:239], v[6:9]
	v_mfma_f32_16x16x32_bf16 v[2:5], v[228:231], v[244:247], v[2:5]
	s_setprio 0
	s_add_i32 s24, s24, 2
	s_add_u32 s14, s14, 0x100
	s_addc_u32 s15, s15, 0
	s_cmp_lt_u32 s24, 28
	s_barrier
	s_cbranch_scc1 .LBB0_1733
	s_add_u32 s6, s12, 0xf80
	s_addc_u32 s7, s13, 0
	v_readfirstlane_b32 s1, v164
	ds_read_b128 v[144:147], v160
	ds_read_b128 v[148:151], v161
	ds_read_b128 v[152:155], v162
	ds_read_b128 v[156:159], v163
	ds_read_b128 v[160:163], v140
	ds_read_b128 v[178:181], v140 offset:1024
	ds_read_b128 v[182:185], v143
	ds_read_b128 v[186:189], v143 offset:1024
	ds_read_b128 v[190:193], v142
	ds_read_b128 v[194:197], v142 offset:1024
	ds_read_b128 v[198:201], v141
	ds_read_b128 v[202:205], v141 offset:1024
	s_mov_b32 m0, s1
	v_lshl_add_u64 v[132:133], s[6:7], 0, v[132:133]
	v_readfirstlane_b32 s1, v165
	global_load_lds_dwordx4 v[132:133], off
	v_lshl_add_u64 v[130:131], s[6:7], 0, v[130:131]
	s_mov_b32 m0, s1
	s_nop 0
	global_load_lds_dwordx4 v[130:131], off
	s_barrier
	s_waitcnt lgkmcnt(0)
	s_setprio 1
	s_waitcnt lgkmcnt(0)
	v_mfma_f32_16x16x32_bf16 v[126:129], v[160:163], v[144:147], v[126:129]
	v_mfma_f32_16x16x32_bf16 v[122:125], v[160:163], v[152:155], v[122:125]
	v_mfma_f32_16x16x32_bf16 v[118:121], v[182:185], v[144:147], v[118:121]
	v_mfma_f32_16x16x32_bf16 v[114:117], v[182:185], v[152:155], v[114:117]
	v_mfma_f32_16x16x32_bf16 v[110:113], v[190:193], v[144:147], v[110:113]
	v_mfma_f32_16x16x32_bf16 v[106:109], v[190:193], v[152:155], v[106:109]
	v_mfma_f32_16x16x32_bf16 v[98:101], v[198:201], v[152:155], v[98:101]
	v_mfma_f32_16x16x32_bf16 v[126:129], v[178:181], v[148:151], v[126:129]
	v_mfma_f32_16x16x32_bf16 v[122:125], v[178:181], v[156:159], v[122:125]
	v_mfma_f32_16x16x32_bf16 v[118:121], v[186:189], v[148:151], v[118:121]
	v_mfma_f32_16x16x32_bf16 v[114:117], v[186:189], v[156:159], v[114:117]
	v_mfma_f32_16x16x32_bf16 v[110:113], v[194:197], v[148:151], v[110:113]
	v_mfma_f32_16x16x32_bf16 v[106:109], v[194:197], v[156:159], v[106:109]
	v_mfma_f32_16x16x32_bf16 v[102:105], v[198:201], v[144:147], v[102:105]
	v_mfma_f32_16x16x32_bf16 v[98:101], v[202:205], v[156:159], v[98:101]
	v_mfma_f32_16x16x32_bf16 v[130:133], v[202:205], v[148:151], v[102:105]
	s_setprio 0
	s_barrier
	s_nop 2
	ds_read_b128 v[102:105], v166
	ds_read_b128 v[164:167], v167
	ds_read_b128 v[206:209], v168
	ds_read_b128 v[212:215], v169
	s_barrier
	s_waitcnt lgkmcnt(0)
	s_setprio 1
	s_waitcnt lgkmcnt(1)
	v_mfma_f32_16x16x32_bf16 v[90:93], v[160:163], v[206:209], v[90:93]
	v_mfma_f32_16x16x32_bf16 v[94:97], v[160:163], v[102:105], v[94:97]
	s_waitcnt lgkmcnt(0)
	v_mfma_f32_16x16x32_bf16 v[90:93], v[178:181], v[212:215], v[90:93]
	v_mfma_f32_16x16x32_bf16 v[86:89], v[182:185], v[102:105], v[86:89]
	v_mfma_f32_16x16x32_bf16 v[82:85], v[182:185], v[206:209], v[82:85]
	v_mfma_f32_16x16x32_bf16 v[78:81], v[190:193], v[102:105], v[78:81]
	v_mfma_f32_16x16x32_bf16 v[74:77], v[190:193], v[206:209], v[74:77]
	v_mfma_f32_16x16x32_bf16 v[70:73], v[198:201], v[102:105], v[70:73]
	v_mfma_f32_16x16x32_bf16 v[66:69], v[198:201], v[206:209], v[66:69]
	v_mfma_f32_16x16x32_bf16 v[216:219], v[178:181], v[164:167], v[94:97]
	v_mfma_f32_16x16x32_bf16 v[160:163], v[186:189], v[164:167], v[86:89]
	v_mfma_f32_16x16x32_bf16 v[178:181], v[186:189], v[212:215], v[82:85]
	v_mfma_f32_16x16x32_bf16 v[182:185], v[194:197], v[164:167], v[78:81]
	v_mfma_f32_16x16x32_bf16 v[186:189], v[194:197], v[212:215], v[74:77]
	v_mfma_f32_16x16x32_bf16 v[190:193], v[202:205], v[164:167], v[70:73]
	v_mfma_f32_16x16x32_bf16 v[194:197], v[202:205], v[212:215], v[66:69]
	s_setprio 0
	s_barrier
	s_nop 0
	ds_read_b128 v[66:69], v140 offset:16384
	ds_read_b128 v[70:73], v140 offset:17408
	ds_read_b128 v[74:77], v143 offset:16384
	ds_read_b128 v[78:81], v143 offset:17408
	ds_read_b128 v[82:85], v142 offset:16384
	ds_read_b128 v[86:89], v142 offset:17408
	ds_read_b128 v[94:97], v141 offset:16384
	ds_read_b128 v[198:201], v141 offset:17408
	s_waitcnt vmcnt(4)
	s_barrier
	s_waitcnt lgkmcnt(0)
	s_setprio 1
	s_waitcnt lgkmcnt(7)
	v_mfma_f32_16x16x32_bf16 v[62:65], v[66:69], v[144:147], v[62:65]
	v_mfma_f32_16x16x32_bf16 v[58:61], v[66:69], v[152:155], v[58:61]
	s_waitcnt lgkmcnt(5)
	v_mfma_f32_16x16x32_bf16 v[54:57], v[74:77], v[144:147], v[54:57]
	v_mfma_f32_16x16x32_bf16 v[50:53], v[74:77], v[152:155], v[50:53]
	s_waitcnt lgkmcnt(3)
	v_mfma_f32_16x16x32_bf16 v[46:49], v[82:85], v[144:147], v[46:49]
	v_mfma_f32_16x16x32_bf16 v[42:45], v[82:85], v[152:155], v[42:45]
	s_waitcnt lgkmcnt(1)
	v_mfma_f32_16x16x32_bf16 v[38:41], v[94:97], v[144:147], v[38:41]
	v_mfma_f32_16x16x32_bf16 v[34:37], v[94:97], v[152:155], v[34:37]
	v_mfma_f32_16x16x32_bf16 v[62:65], v[70:73], v[148:151], v[62:65]
	v_mfma_f32_16x16x32_bf16 v[58:61], v[70:73], v[156:159], v[58:61]
	v_mfma_f32_16x16x32_bf16 v[54:57], v[78:81], v[148:151], v[54:57]
	v_mfma_f32_16x16x32_bf16 v[50:53], v[78:81], v[156:159], v[50:53]
	v_mfma_f32_16x16x32_bf16 v[46:49], v[86:89], v[148:151], v[46:49]
	v_mfma_f32_16x16x32_bf16 v[42:45], v[86:89], v[156:159], v[42:45]
	s_waitcnt lgkmcnt(0)
	v_mfma_f32_16x16x32_bf16 v[38:41], v[198:201], v[148:151], v[38:41]
	v_mfma_f32_16x16x32_bf16 v[34:37], v[198:201], v[156:159], v[34:37]
	s_setprio 0
	s_setprio 1
	v_mfma_f32_16x16x32_bf16 v[30:33], v[66:69], v[102:105], v[30:33]
	v_mfma_f32_16x16x32_bf16 v[26:29], v[66:69], v[206:209], v[26:29]
	v_mfma_f32_16x16x32_bf16 v[22:25], v[74:77], v[102:105], v[22:25]
	v_mfma_f32_16x16x32_bf16 v[18:21], v[74:77], v[206:209], v[18:21]
	v_mfma_f32_16x16x32_bf16 v[14:17], v[82:85], v[102:105], v[14:17]
	v_mfma_f32_16x16x32_bf16 v[10:13], v[82:85], v[206:209], v[10:13]
	v_mfma_f32_16x16x32_bf16 v[6:9], v[94:97], v[102:105], v[6:9]
	v_mfma_f32_16x16x32_bf16 v[2:5], v[94:97], v[206:209], v[2:5]
	v_mfma_f32_16x16x32_bf16 v[144:147], v[70:73], v[164:167], v[30:33]
	v_mfma_f32_16x16x32_bf16 v[148:151], v[70:73], v[212:215], v[26:29]
	v_mfma_f32_16x16x32_bf16 v[152:155], v[78:81], v[164:167], v[22:25]
	v_mfma_f32_16x16x32_bf16 v[156:159], v[78:81], v[212:215], v[18:21]
	v_mfma_f32_16x16x32_bf16 v[202:205], v[86:89], v[164:167], v[14:17]
	v_mfma_f32_16x16x32_bf16 v[224:227], v[86:89], v[212:215], v[10:13]
	v_mfma_f32_16x16x32_bf16 v[164:167], v[198:201], v[164:167], v[6:9]
	v_mfma_f32_16x16x32_bf16 v[198:201], v[198:201], v[212:215], v[2:5]
	s_setprio 0
	s_barrier
	s_nop 0
	ds_read_b128 v[2:5], v170
	ds_read_b128 v[6:9], v171
	ds_read_b128 v[168:171], v172
	ds_read_b128 v[206:209], v173
	ds_read_b128 v[10:13], v140 offset:32768
	ds_read_b128 v[14:17], v140 offset:33792
	ds_read_b128 v[18:21], v143 offset:32768
	ds_read_b128 v[22:25], v143 offset:33792
	ds_read_b128 v[26:29], v142 offset:32768
	ds_read_b128 v[30:33], v142 offset:33792
	ds_read_b128 v[212:215], v141 offset:32768
	ds_read_b128 v[228:231], v141 offset:33792
	s_waitcnt vmcnt(2)
	s_barrier
	s_waitcnt lgkmcnt(0)
	s_setprio 1
	s_waitcnt lgkmcnt(7)
	v_mfma_f32_16x16x32_bf16 v[66:69], v[10:13], v[2:5], v[126:129]
	s_waitcnt lgkmcnt(6)
	v_mfma_f32_16x16x32_bf16 v[94:97], v[14:17], v[6:9], v[66:69]
	v_mfma_f32_16x16x32_bf16 v[66:69], v[10:13], v[168:171], v[122:125]
	v_mfma_f32_16x16x32_bf16 v[102:105], v[14:17], v[206:209], v[66:69]
	s_waitcnt lgkmcnt(5)
	v_mfma_f32_16x16x32_bf16 v[66:69], v[18:21], v[2:5], v[118:121]
	s_waitcnt lgkmcnt(4)
	v_mfma_f32_16x16x32_bf16 v[82:85], v[22:25], v[6:9], v[66:69]
	v_mfma_f32_16x16x32_bf16 v[66:69], v[18:21], v[168:171], v[114:117]
	v_mfma_f32_16x16x32_bf16 v[86:89], v[22:25], v[206:209], v[66:69]
	s_waitcnt lgkmcnt(3)
	v_mfma_f32_16x16x32_bf16 v[66:69], v[26:29], v[2:5], v[110:113]
	s_waitcnt lgkmcnt(2)
	v_mfma_f32_16x16x32_bf16 v[74:77], v[30:33], v[6:9], v[66:69]
	v_mfma_f32_16x16x32_bf16 v[66:69], v[26:29], v[168:171], v[106:109]
	v_mfma_f32_16x16x32_bf16 v[78:81], v[30:33], v[206:209], v[66:69]
	s_waitcnt lgkmcnt(1)
	v_mfma_f32_16x16x32_bf16 v[66:69], v[212:215], v[2:5], v[130:133]
	v_mfma_f32_16x16x32_bf16 v[70:73], v[212:215], v[168:171], v[98:101]
	s_waitcnt lgkmcnt(0)
	v_mfma_f32_16x16x32_bf16 v[66:69], v[228:231], v[6:9], v[66:69]
	v_mfma_f32_16x16x32_bf16 v[70:73], v[228:231], v[206:209], v[70:73]
	s_setprio 0
	s_barrier
	ds_read_b128 v[130:133], v174
	ds_read_b128 v[172:175], v175
	ds_read_b128 v[232:235], v176
	ds_read_b128 v[236:239], v177
	s_waitcnt vmcnt(0)
	s_barrier
	s_waitcnt lgkmcnt(0)
	s_setprio 1
	s_waitcnt lgkmcnt(3)
	v_mfma_f32_16x16x32_bf16 v[98:101], v[10:13], v[130:133], v[216:219]
	s_waitcnt lgkmcnt(1)
	v_mfma_f32_16x16x32_bf16 v[10:13], v[10:13], v[232:235], v[90:93]
	s_waitcnt lgkmcnt(0)
	v_mfma_f32_16x16x32_bf16 v[126:129], v[14:17], v[236:239], v[10:13]
	v_mfma_f32_16x16x32_bf16 v[10:13], v[18:21], v[130:133], v[160:163]
	v_mfma_f32_16x16x32_bf16 v[114:117], v[22:25], v[172:175], v[10:13]
	v_mfma_f32_16x16x32_bf16 v[10:13], v[18:21], v[232:235], v[178:181]
	v_mfma_f32_16x16x32_bf16 v[118:121], v[22:25], v[236:239], v[10:13]
	v_mfma_f32_16x16x32_bf16 v[10:13], v[26:29], v[130:133], v[182:185]
	v_mfma_f32_16x16x32_bf16 v[106:109], v[30:33], v[172:175], v[10:13]
	v_mfma_f32_16x16x32_bf16 v[10:13], v[26:29], v[232:235], v[186:189]
	v_mfma_f32_16x16x32_bf16 v[110:113], v[30:33], v[236:239], v[10:13]
	v_mfma_f32_16x16x32_bf16 v[10:13], v[212:215], v[130:133], v[190:193]
	v_mfma_f32_16x16x32_bf16 v[90:93], v[228:231], v[172:175], v[10:13]
	v_mfma_f32_16x16x32_bf16 v[10:13], v[212:215], v[232:235], v[194:197]
	v_mfma_f32_16x16x32_bf16 v[122:125], v[14:17], v[172:175], v[98:101]
	v_mfma_f32_16x16x32_bf16 v[98:101], v[228:231], v[236:239], v[10:13]
	s_setprio 0
	s_barrier
	ds_read_b128 v[160:163], v140 offset:49152
	ds_read_b128 v[176:179], v140 offset:50176
	ds_read_b128 v[180:183], v143 offset:49152
	ds_read_b128 v[184:187], v143 offset:50176
	ds_read_b128 v[188:191], v142 offset:49152
	ds_read_b128 v[192:195], v142 offset:50176
	ds_read_b128 v[212:215], v141 offset:49152
	ds_read_b128 v[138:141], v141 offset:50176
	s_barrier
	s_waitcnt lgkmcnt(0)
	s_setprio 1
	s_waitcnt lgkmcnt(7)
	v_mfma_f32_16x16x32_bf16 v[10:13], v[160:163], v[2:5], v[62:65]
	s_waitcnt lgkmcnt(6)
	v_mfma_f32_16x16x32_bf16 v[26:29], v[176:179], v[6:9], v[10:13]
	v_mfma_f32_16x16x32_bf16 v[10:13], v[160:163], v[168:171], v[58:61]
	v_mfma_f32_16x16x32_bf16 v[30:33], v[176:179], v[206:209], v[10:13]
	s_waitcnt lgkmcnt(5)
	v_mfma_f32_16x16x32_bf16 v[10:13], v[180:183], v[2:5], v[54:57]
	s_waitcnt lgkmcnt(4)
	v_mfma_f32_16x16x32_bf16 v[18:21], v[184:187], v[6:9], v[10:13]
	v_mfma_f32_16x16x32_bf16 v[10:13], v[180:183], v[168:171], v[50:53]
	v_mfma_f32_16x16x32_bf16 v[22:25], v[184:187], v[206:209], v[10:13]
	s_waitcnt lgkmcnt(3)
	v_mfma_f32_16x16x32_bf16 v[10:13], v[188:191], v[2:5], v[46:49]
	s_waitcnt lgkmcnt(1)
	v_mfma_f32_16x16x32_bf16 v[2:5], v[212:215], v[2:5], v[38:41]
	v_mfma_f32_16x16x32_bf16 v[10:13], v[192:195], v[6:9], v[10:13]
	v_mfma_f32_16x16x32_bf16 v[14:17], v[188:191], v[168:171], v[42:45]
	s_waitcnt lgkmcnt(0)
	v_mfma_f32_16x16x32_bf16 v[2:5], v[138:141], v[6:9], v[2:5]
	v_mfma_f32_16x16x32_bf16 v[6:9], v[212:215], v[168:171], v[34:37]
	v_mfma_f32_16x16x32_bf16 v[14:17], v[192:195], v[206:209], v[14:17]
	v_mfma_f32_16x16x32_bf16 v[6:9], v[138:141], v[206:209], v[6:9]
	s_setprio 0
	s_setprio 1
	v_mfma_f32_16x16x32_bf16 v[34:37], v[160:163], v[130:133], v[144:147]
	v_mfma_f32_16x16x32_bf16 v[58:61], v[176:179], v[172:175], v[34:37]
	v_mfma_f32_16x16x32_bf16 v[34:37], v[160:163], v[232:235], v[148:151]
	v_mfma_f32_16x16x32_bf16 v[62:65], v[176:179], v[236:239], v[34:37]
	v_mfma_f32_16x16x32_bf16 v[34:37], v[180:183], v[130:133], v[152:155]
	v_mfma_f32_16x16x32_bf16 v[50:53], v[184:187], v[172:175], v[34:37]
	v_mfma_f32_16x16x32_bf16 v[34:37], v[180:183], v[232:235], v[156:159]
	v_mfma_f32_16x16x32_bf16 v[54:57], v[184:187], v[236:239], v[34:37]
	v_mfma_f32_16x16x32_bf16 v[34:37], v[188:191], v[130:133], v[202:205]
	v_mfma_f32_16x16x32_bf16 v[42:45], v[192:195], v[172:175], v[34:37]
	v_mfma_f32_16x16x32_bf16 v[34:37], v[188:191], v[232:235], v[224:227]
	v_mfma_f32_16x16x32_bf16 v[46:49], v[192:195], v[236:239], v[34:37]
	v_mfma_f32_16x16x32_bf16 v[34:37], v[212:215], v[130:133], v[164:167]
	v_mfma_f32_16x16x32_bf16 v[38:41], v[212:215], v[232:235], v[198:201]
	v_mfma_f32_16x16x32_bf16 v[34:37], v[138:141], v[172:175], v[34:37]
	v_mfma_f32_16x16x32_bf16 v[38:41], v[138:141], v[236:239], v[38:41]
	s_setprio 0
	s_movk_i32 s1, 0x100
	v_cmp_gt_u32_e32 vcc, s1, v1
	s_barrier
	s_and_saveexec_b64 s[6:7], vcc
	s_cbranch_execz .LBB0_1736
	s_barrier
.LBB0_1736:
	s_or_b64 exec, exec, s[6:7]
	v_lshlrev_b32_e32 v132, 2, v135
	v_lshl_or_b32 v131, v136, 2, v137
	v_lshl_or_b32 v132, v134, 7, v132
	v_mov_b32_e32 v1, v210
	v_mad_u64_u32 v[132:133], s[6:7], v131, s96, v[132:133]
	s_barrier
	ds_write2_b32 v132, v94, v102 offset1:16
	ds_write2_b32 v132, v122, v126 offset0:128 offset1:144
	v_add_u32_e32 v94, 0x400, v132
	ds_write2_b32 v94, v95, v103 offset0:4 offset1:20
	ds_write2_b32 v94, v123, v127 offset0:132 offset1:148
	v_add_u32_e32 v95, 0x800, v132
	ds_write2_b32 v95, v96, v104 offset0:8 offset1:24
	ds_write2_b32 v95, v124, v128 offset0:136 offset1:152
	v_add_u32_e32 v96, 0xc00, v132
	ds_write2_b32 v96, v97, v105 offset0:12 offset1:28
	ds_write2_b32 v96, v125, v129 offset0:140 offset1:156
	v_add_u32_e32 v97, 0x4000, v132
	ds_write2_b32 v97, v82, v86 offset0:64 offset1:80
	ds_write2_b32 v97, v114, v118 offset0:192 offset1:208
	v_add_u32_e32 v82, 0x4400, v132
	ds_write2_b32 v82, v83, v87 offset0:68 offset1:84
	ds_write2_b32 v82, v115, v119 offset0:196 offset1:212
	v_add_u32_e32 v83, 0x4800, v132
	ds_write2_b32 v83, v84, v88 offset0:72 offset1:88
	ds_write2_b32 v83, v116, v120 offset0:200 offset1:216
	v_add_u32_e32 v84, 0x4c00, v132
	ds_write2_b32 v84, v85, v89 offset0:76 offset1:92
	ds_write2_b32 v84, v117, v121 offset0:204 offset1:220
	v_add_u32_e32 v85, 0x8000, v132
	ds_write2_b32 v85, v74, v78 offset0:128 offset1:144
	v_add_u32_e32 v74, 0x8400, v132
	ds_write2_b32 v74, v106, v110 offset1:16
	ds_write2_b32 v74, v75, v79 offset0:132 offset1:148
	v_add_u32_e32 v75, 0x8800, v132
	ds_write2_b32 v75, v107, v111 offset0:4 offset1:20
	ds_write2_b32 v75, v76, v80 offset0:136 offset1:152
	v_add_u32_e32 v76, 0x8c00, v132
	v_add_u32_e32 v78, 0xc000, v132
	v_readlane_b32 s1, v254, 60
	ds_write2_b32 v76, v108, v112 offset0:8 offset1:24
	ds_write2_b32 v76, v77, v81 offset0:140 offset1:156
	v_add_u32_e32 v77, 0x9000, v132
	ds_write2_b32 v78, v66, v70 offset0:192 offset1:208
	v_add_u32_e32 v70, 0xc400, v132
	s_add_i32 s1, s0, s1
	s_lshl_b64 s[4:5], s[4:5], 2
	v_lshlrev_b32_e32 v130, 4, v1
	ds_write2_b32 v77, v109, v113 offset0:12 offset1:28
	ds_write2_b32 v70, v90, v98 offset0:64 offset1:80
	ds_write2_b32 v70, v67, v71 offset0:196 offset1:212
	v_add_u32_e32 v71, 0xc800, v132
	s_add_u32 s4, s92, s4
	v_and_b32_e32 v130, 0x3f0, v130
	ds_write2_b32 v71, v91, v99 offset0:68 offset1:84
	ds_write2_b32 v71, v68, v72 offset0:200 offset1:216
	v_add_u32_e32 v68, 0xcc00, v132
	s_addc_u32 s5, s93, s5
	v_mov_b32_e32 v131, v0
	ds_write2_b32 v68, v92, v100 offset0:72 offset1:88
	ds_write2_b32 v68, v69, v73 offset0:204 offset1:220
	v_add_u32_e32 v69, 0xd000, v132
	v_lshl_add_u64 v[66:67], s[4:5], 0, v[130:131]
	s_mov_b32 s4, 0
	ds_write2_b32 v69, v93, v101 offset0:76 offset1:92
	s_waitcnt lgkmcnt(0)
	s_barrier
	v_readfirstlane_b32 s6, v66
	v_readfirstlane_b32 s7, v67
	v_lshrrev_b32_e32 v81, 6, v1
	v_lshlrev_b32_e32 v80, 12, v81
	v_or_b32_e32 v79, v80, v130
	v_mov_b32_e32 v80, v79
	v_mad_u32_u24 v81, v81, s96, v130
	s_nop 3
	s_lshl_b32 s4, s1, 12
	s_add_u32 s6, s6, s4
	s_addc_u32 s7, s7, 0
	global_load_dwordx4 v[98:101], v79, s[6:7]
	v_add_u32_e32 v79, 0x8000, v79
	global_load_dwordx4 v[102:105], v79, s[6:7]
	v_add_u32_e32 v79, 0x8000, v79
	global_load_dwordx4 v[106:109], v79, s[6:7]
	v_add_u32_e32 v79, 0x8000, v79
	global_load_dwordx4 v[110:113], v79, s[6:7]
	v_add_u32_e32 v79, 0x8000, v79
	global_load_dwordx4 v[114:117], v79, s[6:7]
	v_add_u32_e32 v79, 0x8000, v79
	global_load_dwordx4 v[118:121], v79, s[6:7]
	v_add_u32_e32 v79, 0x8000, v79
	global_load_dwordx4 v[122:125], v79, s[6:7]
	v_add_u32_e32 v79, 0x8000, v79
	global_load_dwordx4 v[126:129], v79, s[6:7]
	v_add_u32_e32 v79, 0x8000, v79
	ds_read_b128 v[86:89], v81
	ds_read_b128 v[90:93], v81 offset:8320
	s_waitcnt vmcnt(7) lgkmcnt(1)
	v_pk_add_f32 v[86:87], v[86:87], v[98:99]
	v_pk_add_f32 v[88:89], v[88:89], v[100:101]
	global_store_dwordx4 v80, v[86:89], s[6:7]
	v_add_u32_e32 v80, 0x8000, v80
	global_load_dwordx4 v[98:101], v79, s[6:7]
	v_add_u32_e32 v79, 0x8000, v79
	ds_read_b128 v[86:89], v81 offset:16640
	s_waitcnt vmcnt(8) lgkmcnt(1)
	v_pk_add_f32 v[90:91], v[90:91], v[102:103]
	v_pk_add_f32 v[92:93], v[92:93], v[104:105]
	global_store_dwordx4 v80, v[90:93], s[6:7]
	v_add_u32_e32 v80, 0x8000, v80
	global_load_dwordx4 v[102:105], v79, s[6:7]
	v_add_u32_e32 v79, 0x8000, v79
	ds_read_b128 v[90:93], v81 offset:24960
	s_waitcnt vmcnt(9) lgkmcnt(1)
	v_pk_add_f32 v[86:87], v[86:87], v[106:107]
	v_pk_add_f32 v[88:89], v[88:89], v[108:109]
	global_store_dwordx4 v80, v[86:89], s[6:7]
	v_add_u32_e32 v80, 0x8000, v80
	global_load_dwordx4 v[106:109], v79, s[6:7]
	v_add_u32_e32 v79, 0x8000, v79
	ds_read_b128 v[86:89], v81 offset:33280
	s_waitcnt vmcnt(10) lgkmcnt(1)
	v_pk_add_f32 v[90:91], v[90:91], v[110:111]
	v_pk_add_f32 v[92:93], v[92:93], v[112:113]
	global_store_dwordx4 v80, v[90:93], s[6:7]
	v_add_u32_e32 v80, 0x8000, v80
	global_load_dwordx4 v[110:113], v79, s[6:7]
	v_add_u32_e32 v79, 0x8000, v79
	ds_read_b128 v[90:93], v81 offset:41600
	s_waitcnt vmcnt(11) lgkmcnt(1)
	v_pk_add_f32 v[86:87], v[86:87], v[114:115]
	v_pk_add_f32 v[88:89], v[88:89], v[116:117]
	global_store_dwordx4 v80, v[86:89], s[6:7]
	v_add_u32_e32 v80, 0x8000, v80
	global_load_dwordx4 v[114:117], v79, s[6:7]
	v_add_u32_e32 v79, 0x8000, v79
	ds_read_b128 v[86:89], v81 offset:49920
	s_waitcnt vmcnt(12) lgkmcnt(1)
	v_pk_add_f32 v[90:91], v[90:91], v[118:119]
	v_pk_add_f32 v[92:93], v[92:93], v[120:121]
	global_store_dwordx4 v80, v[90:93], s[6:7]
	v_add_u32_e32 v80, 0x8000, v80
	global_load_dwordx4 v[118:121], v79, s[6:7]
	v_add_u32_e32 v79, 0x8000, v79
	ds_read_b128 v[90:93], v81 offset:58240
	s_waitcnt vmcnt(13) lgkmcnt(1)
	v_pk_add_f32 v[86:87], v[86:87], v[122:123]
	v_pk_add_f32 v[88:89], v[88:89], v[124:125]
	global_store_dwordx4 v80, v[86:89], s[6:7]
	v_add_u32_e32 v80, 0x8000, v80
	global_load_dwordx4 v[122:125], v79, s[6:7]
	v_add_u32_e32 v79, 0x8000, v79
	v_add_u32_e32 v81, 0x10400, v81
	ds_read_b128 v[86:89], v81
	s_waitcnt vmcnt(14) lgkmcnt(1)
	v_pk_add_f32 v[90:91], v[90:91], v[126:127]
	v_pk_add_f32 v[92:93], v[92:93], v[128:129]
	global_store_dwordx4 v80, v[90:93], s[6:7]
	v_add_u32_e32 v80, 0x8000, v80
	global_load_dwordx4 v[126:129], v79, s[6:7]
	v_add_u32_e32 v79, 0x8000, v79
	ds_read_b128 v[90:93], v81 offset:8320
	s_waitcnt vmcnt(14) lgkmcnt(1)
	v_pk_add_f32 v[86:87], v[86:87], v[98:99]
	v_pk_add_f32 v[88:89], v[88:89], v[100:101]
	global_store_dwordx4 v80, v[86:89], s[6:7]
	v_add_u32_e32 v80, 0x8000, v80
	global_load_dwordx4 v[98:101], v79, s[6:7]
	v_add_u32_e32 v79, 0x8000, v79
	ds_read_b128 v[86:89], v81 offset:16640
	s_waitcnt vmcnt(14) lgkmcnt(1)
	v_pk_add_f32 v[90:91], v[90:91], v[102:103]
	v_pk_add_f32 v[92:93], v[92:93], v[104:105]
	global_store_dwordx4 v80, v[90:93], s[6:7]
	v_add_u32_e32 v80, 0x8000, v80
	global_load_dwordx4 v[102:105], v79, s[6:7]
	v_add_u32_e32 v79, 0x8000, v79
	ds_read_b128 v[90:93], v81 offset:24960
	s_waitcnt vmcnt(14) lgkmcnt(1)
	v_pk_add_f32 v[86:87], v[86:87], v[106:107]
	v_pk_add_f32 v[88:89], v[88:89], v[108:109]
	global_store_dwordx4 v80, v[86:89], s[6:7]
	v_add_u32_e32 v80, 0x8000, v80
	global_load_dwordx4 v[106:109], v79, s[6:7]
	v_add_u32_e32 v79, 0x8000, v79
	ds_read_b128 v[86:89], v81 offset:33280
	s_waitcnt vmcnt(14) lgkmcnt(1)
	v_pk_add_f32 v[90:91], v[90:91], v[110:111]
	v_pk_add_f32 v[92:93], v[92:93], v[112:113]
	global_store_dwordx4 v80, v[90:93], s[6:7]
	v_add_u32_e32 v80, 0x8000, v80
	global_load_dwordx4 v[110:113], v79, s[6:7]
	v_add_u32_e32 v79, 0x8000, v79
	ds_read_b128 v[90:93], v81 offset:41600
	s_waitcnt vmcnt(14) lgkmcnt(1)
	v_pk_add_f32 v[86:87], v[86:87], v[114:115]
	v_pk_add_f32 v[88:89], v[88:89], v[116:117]
	global_store_dwordx4 v80, v[86:89], s[6:7]
	v_add_u32_e32 v80, 0x8000, v80
	global_load_dwordx4 v[114:117], v79, s[6:7]
	v_add_u32_e32 v79, 0x8000, v79
	ds_read_b128 v[86:89], v81 offset:49920
	s_waitcnt vmcnt(14) lgkmcnt(1)
	v_pk_add_f32 v[90:91], v[90:91], v[118:119]
	v_pk_add_f32 v[92:93], v[92:93], v[120:121]
	global_store_dwordx4 v80, v[90:93], s[6:7]
	v_add_u32_e32 v80, 0x8000, v80
	global_load_dwordx4 v[118:121], v79, s[6:7]
	v_add_u32_e32 v79, 0x8000, v79
	ds_read_b128 v[90:93], v81 offset:58240
	s_waitcnt vmcnt(14) lgkmcnt(1)
	v_pk_add_f32 v[86:87], v[86:87], v[122:123]
	v_pk_add_f32 v[88:89], v[88:89], v[124:125]
	global_store_dwordx4 v80, v[86:89], s[6:7]
	v_add_u32_e32 v80, 0x8000, v80
	global_load_dwordx4 v[122:125], v79, s[6:7]
	v_add_u32_e32 v79, 0x8000, v79
	s_waitcnt vmcnt(14) lgkmcnt(0)
	v_pk_add_f32 v[90:91], v[90:91], v[126:127]
	v_pk_add_f32 v[92:93], v[92:93], v[128:129]
	global_store_dwordx4 v80, v[90:93], s[6:7]
	v_add_u32_e32 v80, 0x8000, v80
	global_load_dwordx4 v[126:129], v79, s[6:7]
	v_add_u32_e32 v79, 0x8000, v79
	v_readlane_b32 s1, v254, 61
	s_add_i32 s0, s1, s0
	s_mov_b32 s1, 0
	s_barrier
	ds_write2_b32 v132, v26, v30 offset1:16
	ds_write2_b32 v132, v58, v62 offset0:128 offset1:144
	ds_write2_b32 v94, v27, v31 offset0:4 offset1:20
	ds_write2_b32 v94, v59, v63 offset0:132 offset1:148
	ds_write2_b32 v95, v28, v32 offset0:8 offset1:24
	ds_write2_b32 v95, v60, v64 offset0:136 offset1:152
	ds_write2_b32 v96, v29, v33 offset0:12 offset1:28
	ds_write2_b32 v96, v61, v65 offset0:140 offset1:156
	ds_write2_b32 v97, v18, v22 offset0:64 offset1:80
	ds_write2_b32 v97, v50, v54 offset0:192 offset1:208
	ds_write2_b32 v82, v19, v23 offset0:68 offset1:84
	ds_write2_b32 v82, v51, v55 offset0:196 offset1:212
	ds_write2_b32 v83, v20, v24 offset0:72 offset1:88
	ds_write2_b32 v83, v52, v56 offset0:200 offset1:216
	ds_write2_b32 v84, v21, v25 offset0:76 offset1:92
	ds_write2_b32 v84, v53, v57 offset0:204 offset1:220
	ds_write2_b32 v85, v10, v14 offset0:128 offset1:144
	ds_write2_b32 v74, v42, v46 offset1:16
	ds_write2_b32 v74, v11, v15 offset0:132 offset1:148
	ds_write2_b32 v75, v43, v47 offset0:4 offset1:20
	ds_write2_b32 v75, v12, v16 offset0:136 offset1:152
	ds_write2_b32 v76, v44, v48 offset0:8 offset1:24
	ds_write2_b32 v76, v13, v17 offset0:140 offset1:156
	ds_write2_b32 v77, v45, v49 offset0:12 offset1:28
	ds_write2_b32 v78, v2, v6 offset0:192 offset1:208
	ds_write2_b32 v70, v34, v38 offset0:64 offset1:80
	ds_write2_b32 v70, v3, v7 offset0:196 offset1:212
	ds_write2_b32 v71, v35, v39 offset0:68 offset1:84
	ds_write2_b32 v71, v4, v8 offset0:200 offset1:216
	ds_write2_b32 v68, v36, v40 offset0:72 offset1:88
	ds_write2_b32 v68, v5, v9 offset0:204 offset1:220
	ds_write2_b32 v69, v37, v41 offset0:76 offset1:92
	s_waitcnt lgkmcnt(0)
	s_barrier
	v_add_u32_e32 v81, 0xfffefc00, v81
	ds_read_b128 v[86:89], v81
	ds_read_b128 v[90:93], v81 offset:8320
	s_waitcnt vmcnt(14) lgkmcnt(1)
	v_pk_add_f32 v[86:87], v[86:87], v[98:99]
	v_pk_add_f32 v[88:89], v[88:89], v[100:101]
	global_store_dwordx4 v80, v[86:89], s[6:7]
	v_add_u32_e32 v80, 0x8000, v80
	global_load_dwordx4 v[98:101], v79, s[6:7]
	v_add_u32_e32 v79, 0x8000, v79
	ds_read_b128 v[86:89], v81 offset:16640
	s_waitcnt vmcnt(14) lgkmcnt(1)
	v_pk_add_f32 v[90:91], v[90:91], v[102:103]
	v_pk_add_f32 v[92:93], v[92:93], v[104:105]
	global_store_dwordx4 v80, v[90:93], s[6:7]
	v_add_u32_e32 v80, 0x8000, v80
	global_load_dwordx4 v[102:105], v79, s[6:7]
	v_add_u32_e32 v79, 0x8000, v79
	ds_read_b128 v[90:93], v81 offset:24960
	s_waitcnt vmcnt(14) lgkmcnt(1)
	v_pk_add_f32 v[86:87], v[86:87], v[106:107]
	v_pk_add_f32 v[88:89], v[88:89], v[108:109]
	global_store_dwordx4 v80, v[86:89], s[6:7]
	v_add_u32_e32 v80, 0x8000, v80
	global_load_dwordx4 v[106:109], v79, s[6:7]
	v_add_u32_e32 v79, 0x8000, v79
	ds_read_b128 v[86:89], v81 offset:33280
	s_waitcnt vmcnt(14) lgkmcnt(1)
	v_pk_add_f32 v[90:91], v[90:91], v[110:111]
	v_pk_add_f32 v[92:93], v[92:93], v[112:113]
	global_store_dwordx4 v80, v[90:93], s[6:7]
	v_add_u32_e32 v80, 0x8000, v80
	global_load_dwordx4 v[110:113], v79, s[6:7]
	v_add_u32_e32 v79, 0x8000, v79
	ds_read_b128 v[90:93], v81 offset:41600
	s_waitcnt vmcnt(14) lgkmcnt(1)
	v_pk_add_f32 v[86:87], v[86:87], v[114:115]
	v_pk_add_f32 v[88:89], v[88:89], v[116:117]
	global_store_dwordx4 v80, v[86:89], s[6:7]
	v_add_u32_e32 v80, 0x8000, v80
	global_load_dwordx4 v[114:117], v79, s[6:7]
	v_add_u32_e32 v79, 0x8000, v79
	ds_read_b128 v[86:89], v81 offset:49920
	s_waitcnt vmcnt(14) lgkmcnt(1)
	v_pk_add_f32 v[90:91], v[90:91], v[118:119]
	v_pk_add_f32 v[92:93], v[92:93], v[120:121]
	global_store_dwordx4 v80, v[90:93], s[6:7]
	v_add_u32_e32 v80, 0x8000, v80
	global_load_dwordx4 v[118:121], v79, s[6:7]
	v_add_u32_e32 v79, 0x8000, v79
	ds_read_b128 v[90:93], v81 offset:58240
	s_waitcnt vmcnt(14) lgkmcnt(1)
	v_pk_add_f32 v[86:87], v[86:87], v[122:123]
	v_pk_add_f32 v[88:89], v[88:89], v[124:125]
	global_store_dwordx4 v80, v[86:89], s[6:7]
	v_add_u32_e32 v80, 0x8000, v80
	global_load_dwordx4 v[122:125], v79, s[6:7]
	v_add_u32_e32 v79, 0x8000, v79
	v_add_u32_e32 v81, 0x10400, v81
	ds_read_b128 v[86:89], v81
	s_waitcnt vmcnt(14) lgkmcnt(1)
	v_pk_add_f32 v[90:91], v[90:91], v[126:127]
	v_pk_add_f32 v[92:93], v[92:93], v[128:129]
	global_store_dwordx4 v80, v[90:93], s[6:7]
	v_add_u32_e32 v80, 0x8000, v80
	global_load_dwordx4 v[126:129], v79, s[6:7]
	v_add_u32_e32 v79, 0x8000, v79
	ds_read_b128 v[90:93], v81 offset:8320
	s_waitcnt vmcnt(14) lgkmcnt(1)
	v_pk_add_f32 v[86:87], v[86:87], v[98:99]
	v_pk_add_f32 v[88:89], v[88:89], v[100:101]
	global_store_dwordx4 v80, v[86:89], s[6:7]
	v_add_u32_e32 v80, 0x8000, v80
	s_nop 0
	ds_read_b128 v[86:89], v81 offset:16640
	s_waitcnt vmcnt(13) lgkmcnt(1)
	v_pk_add_f32 v[90:91], v[90:91], v[102:103]
	v_pk_add_f32 v[92:93], v[92:93], v[104:105]
	global_store_dwordx4 v80, v[90:93], s[6:7]
	v_add_u32_e32 v80, 0x8000, v80
	s_nop 0
	ds_read_b128 v[90:93], v81 offset:24960
	s_waitcnt vmcnt(12) lgkmcnt(1)
	v_pk_add_f32 v[86:87], v[86:87], v[106:107]
	v_pk_add_f32 v[88:89], v[88:89], v[108:109]
	global_store_dwordx4 v80, v[86:89], s[6:7]
	v_add_u32_e32 v80, 0x8000, v80
	s_nop 0
	ds_read_b128 v[86:89], v81 offset:33280
	s_waitcnt vmcnt(11) lgkmcnt(1)
	v_pk_add_f32 v[90:91], v[90:91], v[110:111]
	v_pk_add_f32 v[92:93], v[92:93], v[112:113]
	global_store_dwordx4 v80, v[90:93], s[6:7]
	v_add_u32_e32 v80, 0x8000, v80
	s_nop 0
	ds_read_b128 v[90:93], v81 offset:41600
	s_waitcnt vmcnt(10) lgkmcnt(1)
	v_pk_add_f32 v[86:87], v[86:87], v[114:115]
	v_pk_add_f32 v[88:89], v[88:89], v[116:117]
	global_store_dwordx4 v80, v[86:89], s[6:7]
	v_add_u32_e32 v80, 0x8000, v80
	s_nop 0
	ds_read_b128 v[86:89], v81 offset:49920
	s_waitcnt vmcnt(9) lgkmcnt(1)
	v_pk_add_f32 v[90:91], v[90:91], v[118:119]
	v_pk_add_f32 v[92:93], v[92:93], v[120:121]
	global_store_dwordx4 v80, v[90:93], s[6:7]
	v_add_u32_e32 v80, 0x8000, v80
	s_nop 0
	ds_read_b128 v[90:93], v81 offset:58240
	s_waitcnt vmcnt(8) lgkmcnt(1)
	v_pk_add_f32 v[86:87], v[86:87], v[122:123]
	v_pk_add_f32 v[88:89], v[88:89], v[124:125]
	global_store_dwordx4 v80, v[86:89], s[6:7]
	v_add_u32_e32 v80, 0x8000, v80
	s_nop 0
	s_waitcnt vmcnt(7) lgkmcnt(0)
	v_pk_add_f32 v[90:91], v[90:91], v[126:127]
	v_pk_add_f32 v[92:93], v[92:93], v[128:129]
	global_store_dwordx4 v80, v[90:93], s[6:7]
	v_add_u32_e32 v80, 0x8000, v80
	s_nop 0
	s_add_i32 s18, s18, s74
	s_cmpk_lt_i32 s18, 0x200
	s_cbranch_scc1 .LBB0_1725
	s_branch .LBB0_1742

.LBB0_1871:
	v_or_b32_e32 v160, 0x10000, v156
	v_or_b32_e32 v162, 0x10000, v158
	v_or_b32_e32 v161, 0x10000, v157
	ds_read_b128 v[170:173], v160
	ds_read_b128 v[174:177], v161
	v_or_b32_e32 v163, 0x10000, v159
	ds_read_b128 v[178:181], v162
	ds_read_b128 v[182:185], v163
	s_add_u32 s36, s19, s16
	s_addc_u32 s37, s34, s17
	s_add_u32 s36, s36, 0x80
	v_add_u32_e32 v164, 0xc000, v137
	s_addc_u32 s37, s37, 0
	v_readfirstlane_b32 s38, v164
	ds_read_b128 v[186:189], v139
	ds_read_b128 v[190:193], v139 offset:1024
	ds_read_b128 v[194:197], v142
	ds_read_b128 v[198:201], v142 offset:1024
	ds_read_b128 v[202:205], v141
	ds_read_b128 v[206:209], v141 offset:1024
	ds_read_b128 v[212:215], v140
	ds_read_b128 v[216:219], v140 offset:1024
	s_mov_b32 m0, s38
	v_lshl_add_u64 v[166:167], s[36:37], 0, v[132:133]
	v_add_u32_e32 v165, 0xe000, v137
	global_load_lds_dwordx4 v[166:167], off
	v_lshl_add_u64 v[166:167], s[36:37], 0, v[130:131]
	v_readfirstlane_b32 s36, v165
	s_mov_b32 m0, s36
	s_nop 0
	global_load_lds_dwordx4 v[166:167], off
	s_waitcnt lgkmcnt(8)
	s_barrier
	s_waitcnt lgkmcnt(0)
	s_setprio 1
	s_waitcnt lgkmcnt(0)
	v_mfma_f32_16x16x32_bf16 v[126:129], v[186:189], v[170:173], v[126:129]
	v_mfma_f32_16x16x32_bf16 v[122:125], v[186:189], v[178:181], v[122:125]
	v_mfma_f32_16x16x32_bf16 v[118:121], v[194:197], v[170:173], v[118:121]
	v_mfma_f32_16x16x32_bf16 v[114:117], v[194:197], v[178:181], v[114:117]
	v_mfma_f32_16x16x32_bf16 v[110:113], v[202:205], v[170:173], v[110:113]
	v_mfma_f32_16x16x32_bf16 v[106:109], v[202:205], v[178:181], v[106:109]
	v_mfma_f32_16x16x32_bf16 v[102:105], v[212:215], v[170:173], v[102:105]
	v_mfma_f32_16x16x32_bf16 v[98:101], v[212:215], v[178:181], v[98:101]
	v_mfma_f32_16x16x32_bf16 v[126:129], v[190:193], v[174:177], v[126:129]
	v_mfma_f32_16x16x32_bf16 v[122:125], v[190:193], v[182:185], v[122:125]
	v_mfma_f32_16x16x32_bf16 v[118:121], v[198:201], v[174:177], v[118:121]
	v_mfma_f32_16x16x32_bf16 v[114:117], v[198:201], v[182:185], v[114:117]
	v_mfma_f32_16x16x32_bf16 v[110:113], v[206:209], v[174:177], v[110:113]
	v_mfma_f32_16x16x32_bf16 v[106:109], v[206:209], v[182:185], v[106:109]
	v_mfma_f32_16x16x32_bf16 v[102:105], v[216:219], v[174:177], v[102:105]
	v_mfma_f32_16x16x32_bf16 v[98:101], v[216:219], v[182:185], v[98:101]
	s_setprio 0
	s_barrier
	s_add_u32 s38, s0, s16
	s_addc_u32 s39, s1, s17
	s_add_u32 s36, s38, 0x100
	v_or_b32_e32 v166, 0x14000, v156
	v_or_b32_e32 v168, 0x14000, v158
	s_addc_u32 s37, s39, 0
	v_readfirstlane_b32 s40, v143
	v_or_b32_e32 v167, 0x14000, v157
	ds_read_b128 v[224:227], v166
	ds_read_b128 v[228:231], v167
	v_or_b32_e32 v169, 0x14000, v159
	ds_read_b128 v[232:235], v168
	ds_read_b128 v[236:239], v169
	s_mov_b32 m0, s40
	v_lshl_add_u64 v[240:241], s[36:37], 0, v[132:133]
	global_load_lds_dwordx4 v[240:241], off
	v_lshl_add_u64 v[240:241], s[36:37], 0, v[130:131]
	v_readfirstlane_b32 s36, v144
	s_mov_b32 m0, s36
	s_nop 0
	global_load_lds_dwordx4 v[240:241], off
	s_barrier
	s_waitcnt lgkmcnt(0)
	s_setprio 1
	s_waitcnt lgkmcnt(0)
	v_mfma_f32_16x16x32_bf16 v[94:97], v[186:189], v[224:227], v[94:97]
	v_mfma_f32_16x16x32_bf16 v[90:93], v[186:189], v[232:235], v[90:93]
	v_mfma_f32_16x16x32_bf16 v[86:89], v[194:197], v[224:227], v[86:89]
	v_mfma_f32_16x16x32_bf16 v[82:85], v[194:197], v[232:235], v[82:85]
	v_mfma_f32_16x16x32_bf16 v[78:81], v[202:205], v[224:227], v[78:81]
	v_mfma_f32_16x16x32_bf16 v[74:77], v[202:205], v[232:235], v[74:77]
	v_mfma_f32_16x16x32_bf16 v[70:73], v[212:215], v[224:227], v[70:73]
	v_mfma_f32_16x16x32_bf16 v[66:69], v[212:215], v[232:235], v[66:69]
	v_mfma_f32_16x16x32_bf16 v[94:97], v[190:193], v[228:231], v[94:97]
	v_mfma_f32_16x16x32_bf16 v[90:93], v[190:193], v[236:239], v[90:93]
	v_mfma_f32_16x16x32_bf16 v[86:89], v[198:201], v[228:231], v[86:89]
	v_mfma_f32_16x16x32_bf16 v[82:85], v[198:201], v[236:239], v[82:85]
	v_mfma_f32_16x16x32_bf16 v[78:81], v[206:209], v[228:231], v[78:81]
	v_mfma_f32_16x16x32_bf16 v[74:77], v[206:209], v[236:239], v[74:77]
	v_mfma_f32_16x16x32_bf16 v[70:73], v[216:219], v[228:231], v[70:73]
	v_mfma_f32_16x16x32_bf16 v[66:69], v[216:219], v[236:239], v[66:69]
	s_setprio 0
	s_add_u32 s40, s10, s16
	s_addc_u32 s41, s11, s17
	s_add_u32 s36, s40, 0x100
	s_addc_u32 s37, s41, 0
	v_readfirstlane_b32 s42, v137
	s_barrier
	ds_read_b128 v[186:189], v139 offset:16384
	ds_read_b128 v[190:193], v139 offset:17408
	ds_read_b128 v[194:197], v142 offset:16384
	ds_read_b128 v[198:201], v142 offset:17408
	ds_read_b128 v[202:205], v141 offset:16384
	ds_read_b128 v[206:209], v141 offset:17408
	ds_read_b128 v[212:215], v140 offset:16384
	ds_read_b128 v[216:219], v140 offset:17408
	s_mov_b32 m0, s42
	v_lshl_add_u64 v[240:241], s[36:37], 0, v[132:133]
	global_load_lds_dwordx4 v[240:241], off
	v_lshl_add_u64 v[240:241], s[36:37], 0, v[130:131]
	v_readfirstlane_b32 s36, v138
	s_mov_b32 m0, s36
	s_nop 0
	global_load_lds_dwordx4 v[240:241], off
	s_barrier
	s_waitcnt lgkmcnt(0)
	s_setprio 1
	s_waitcnt lgkmcnt(0)
	v_mfma_f32_16x16x32_bf16 v[62:65], v[186:189], v[170:173], v[62:65]
	v_mfma_f32_16x16x32_bf16 v[58:61], v[186:189], v[178:181], v[58:61]
	v_mfma_f32_16x16x32_bf16 v[54:57], v[194:197], v[170:173], v[54:57]
	v_mfma_f32_16x16x32_bf16 v[50:53], v[194:197], v[178:181], v[50:53]
	v_mfma_f32_16x16x32_bf16 v[46:49], v[202:205], v[170:173], v[46:49]
	v_mfma_f32_16x16x32_bf16 v[42:45], v[202:205], v[178:181], v[42:45]
	v_mfma_f32_16x16x32_bf16 v[38:41], v[212:215], v[170:173], v[38:41]
	v_mfma_f32_16x16x32_bf16 v[34:37], v[212:215], v[178:181], v[34:37]
	v_mfma_f32_16x16x32_bf16 v[62:65], v[190:193], v[174:177], v[62:65]
	v_mfma_f32_16x16x32_bf16 v[58:61], v[190:193], v[182:185], v[58:61]
	v_mfma_f32_16x16x32_bf16 v[54:57], v[198:201], v[174:177], v[54:57]
	v_mfma_f32_16x16x32_bf16 v[50:53], v[198:201], v[182:185], v[50:53]
	v_mfma_f32_16x16x32_bf16 v[46:49], v[206:209], v[174:177], v[46:49]
	v_mfma_f32_16x16x32_bf16 v[42:45], v[206:209], v[182:185], v[42:45]
	v_mfma_f32_16x16x32_bf16 v[38:41], v[216:219], v[174:177], v[38:41]
	v_mfma_f32_16x16x32_bf16 v[34:37], v[216:219], v[182:185], v[34:37]
	s_setprio 0
	s_barrier
	s_add_u32 s42, s12, s16
	s_addc_u32 s43, s13, s17
	s_add_u32 s36, s42, 0x100
	s_addc_u32 s37, s43, 0
	v_readfirstlane_b32 s44, v146
	s_mov_b32 m0, s44
	v_lshl_add_u64 v[170:171], s[36:37], 0, v[132:133]
	global_load_lds_dwordx4 v[170:171], off
	v_lshl_add_u64 v[170:171], s[36:37], 0, v[130:131]
	v_readfirstlane_b32 s36, v147
	s_mov_b32 m0, s36
	s_nop 0
	global_load_lds_dwordx4 v[170:171], off
	s_waitcnt vmcnt(6)
	s_barrier
	s_setprio 1
	v_mfma_f32_16x16x32_bf16 v[30:33], v[186:189], v[224:227], v[30:33]
	v_mfma_f32_16x16x32_bf16 v[26:29], v[186:189], v[232:235], v[26:29]
	v_mfma_f32_16x16x32_bf16 v[22:25], v[194:197], v[224:227], v[22:25]
	v_mfma_f32_16x16x32_bf16 v[18:21], v[194:197], v[232:235], v[18:21]
	v_mfma_f32_16x16x32_bf16 v[14:17], v[202:205], v[224:227], v[14:17]
	v_mfma_f32_16x16x32_bf16 v[10:13], v[202:205], v[232:235], v[10:13]
	v_mfma_f32_16x16x32_bf16 v[6:9], v[212:215], v[224:227], v[6:9]
	v_mfma_f32_16x16x32_bf16 v[2:5], v[212:215], v[232:235], v[2:5]
	v_mfma_f32_16x16x32_bf16 v[30:33], v[190:193], v[228:231], v[30:33]
	v_mfma_f32_16x16x32_bf16 v[26:29], v[190:193], v[236:239], v[26:29]
	v_mfma_f32_16x16x32_bf16 v[22:25], v[198:201], v[228:231], v[22:25]
	v_mfma_f32_16x16x32_bf16 v[18:21], v[198:201], v[236:239], v[18:21]
	v_mfma_f32_16x16x32_bf16 v[14:17], v[206:209], v[228:231], v[14:17]
	v_mfma_f32_16x16x32_bf16 v[10:13], v[206:209], v[236:239], v[10:13]
	v_mfma_f32_16x16x32_bf16 v[6:9], v[216:219], v[228:231], v[6:9]
	v_mfma_f32_16x16x32_bf16 v[2:5], v[216:219], v[236:239], v[2:5]
	s_setprio 0
	v_or_b32_e32 v170, 0x18000, v156
	v_or_b32_e32 v172, 0x18000, v158
	s_barrier
	v_or_b32_e32 v171, 0x18000, v157
	ds_read_b128 v[178:181], v170
	ds_read_b128 v[182:185], v171
	v_or_b32_e32 v173, 0x18000, v159
	ds_read_b128 v[186:189], v172
	ds_read_b128 v[190:193], v173
	s_add_u32 s36, s7, s16
	s_addc_u32 s37, s18, s17
	v_readfirstlane_b32 s44, v148
	ds_read_b128 v[194:197], v139 offset:32768
	ds_read_b128 v[198:201], v139 offset:33792
	ds_read_b128 v[202:205], v142 offset:32768
	ds_read_b128 v[206:209], v142 offset:33792
	ds_read_b128 v[212:215], v141 offset:32768
	ds_read_b128 v[216:219], v141 offset:33792
	ds_read_b128 v[224:227], v140 offset:32768
	ds_read_b128 v[228:231], v140 offset:33792
	s_mov_b32 m0, s44
	v_lshl_add_u64 v[174:175], s[36:37], 0, v[132:133]
	global_load_lds_dwordx4 v[174:175], off
	v_lshl_add_u64 v[174:175], s[36:37], 0, v[130:131]
	v_readfirstlane_b32 s36, v149
	s_mov_b32 m0, s36
	s_nop 0
	global_load_lds_dwordx4 v[174:175], off
	s_waitcnt lgkmcnt(8)
	s_barrier
	s_waitcnt lgkmcnt(0)
	s_setprio 1
	s_waitcnt lgkmcnt(0)
	v_mfma_f32_16x16x32_bf16 v[126:129], v[194:197], v[178:181], v[126:129]
	v_mfma_f32_16x16x32_bf16 v[122:125], v[194:197], v[186:189], v[122:125]
	v_mfma_f32_16x16x32_bf16 v[118:121], v[202:205], v[178:181], v[118:121]
	v_mfma_f32_16x16x32_bf16 v[114:117], v[202:205], v[186:189], v[114:117]
	v_mfma_f32_16x16x32_bf16 v[110:113], v[212:215], v[178:181], v[110:113]
	v_mfma_f32_16x16x32_bf16 v[106:109], v[212:215], v[186:189], v[106:109]
	v_mfma_f32_16x16x32_bf16 v[102:105], v[224:227], v[178:181], v[102:105]
	v_mfma_f32_16x16x32_bf16 v[98:101], v[224:227], v[186:189], v[98:101]
	v_mfma_f32_16x16x32_bf16 v[126:129], v[198:201], v[182:185], v[126:129]
	v_mfma_f32_16x16x32_bf16 v[122:125], v[198:201], v[190:193], v[122:125]
	v_mfma_f32_16x16x32_bf16 v[118:121], v[206:209], v[182:185], v[118:121]
	v_mfma_f32_16x16x32_bf16 v[114:117], v[206:209], v[190:193], v[114:117]
	v_mfma_f32_16x16x32_bf16 v[110:113], v[216:219], v[182:185], v[110:113]
	v_mfma_f32_16x16x32_bf16 v[106:109], v[216:219], v[190:193], v[106:109]
	v_mfma_f32_16x16x32_bf16 v[102:105], v[228:231], v[182:185], v[102:105]
	v_mfma_f32_16x16x32_bf16 v[98:101], v[228:231], v[190:193], v[98:101]
	s_setprio 0
	s_barrier
	s_add_u32 s36, s38, 0x180
	v_or_b32_e32 v174, 0x1c000, v156
	v_or_b32_e32 v176, 0x1c000, v158
	s_addc_u32 s37, s39, 0
	v_readfirstlane_b32 s38, v150
	v_or_b32_e32 v175, 0x1c000, v157
	ds_read_b128 v[232:235], v174
	ds_read_b128 v[236:239], v175
	v_or_b32_e32 v177, 0x1c000, v159
	ds_read_b128 v[240:243], v176
	ds_read_b128 v[244:247], v177
	s_mov_b32 m0, s38
	v_lshl_add_u64 v[248:249], s[36:37], 0, v[132:133]
	global_load_lds_dwordx4 v[248:249], off
	v_lshl_add_u64 v[248:249], s[36:37], 0, v[130:131]
	v_readfirstlane_b32 s36, v151
	s_mov_b32 m0, s36
	s_nop 0
	global_load_lds_dwordx4 v[248:249], off
	s_barrier
	s_waitcnt lgkmcnt(0)
	s_setprio 1
	s_waitcnt lgkmcnt(0)
	v_mfma_f32_16x16x32_bf16 v[94:97], v[194:197], v[232:235], v[94:97]
	v_mfma_f32_16x16x32_bf16 v[90:93], v[194:197], v[240:243], v[90:93]
	v_mfma_f32_16x16x32_bf16 v[86:89], v[202:205], v[232:235], v[86:89]
	v_mfma_f32_16x16x32_bf16 v[82:85], v[202:205], v[240:243], v[82:85]
	v_mfma_f32_16x16x32_bf16 v[78:81], v[212:215], v[232:235], v[78:81]
	v_mfma_f32_16x16x32_bf16 v[74:77], v[212:215], v[240:243], v[74:77]
	v_mfma_f32_16x16x32_bf16 v[70:73], v[224:227], v[232:235], v[70:73]
	v_mfma_f32_16x16x32_bf16 v[66:69], v[224:227], v[240:243], v[66:69]
	v_mfma_f32_16x16x32_bf16 v[94:97], v[198:201], v[236:239], v[94:97]
	v_mfma_f32_16x16x32_bf16 v[90:93], v[198:201], v[244:247], v[90:93]
	v_mfma_f32_16x16x32_bf16 v[86:89], v[206:209], v[236:239], v[86:89]
	v_mfma_f32_16x16x32_bf16 v[82:85], v[206:209], v[244:247], v[82:85]
	v_mfma_f32_16x16x32_bf16 v[78:81], v[216:219], v[236:239], v[78:81]
	v_mfma_f32_16x16x32_bf16 v[74:77], v[216:219], v[244:247], v[74:77]
	v_mfma_f32_16x16x32_bf16 v[70:73], v[228:231], v[236:239], v[70:73]
	v_mfma_f32_16x16x32_bf16 v[66:69], v[228:231], v[244:247], v[66:69]
	s_setprio 0
	s_add_u32 s36, s40, 0x180
	s_addc_u32 s37, s41, 0
	v_readfirstlane_b32 s38, v152
	s_barrier
	ds_read_b128 v[194:197], v139 offset:49152
	ds_read_b128 v[198:201], v139 offset:50176
	ds_read_b128 v[202:205], v142 offset:49152
	ds_read_b128 v[206:209], v142 offset:50176
	ds_read_b128 v[212:215], v141 offset:49152
	ds_read_b128 v[216:219], v141 offset:50176
	ds_read_b128 v[224:227], v140 offset:49152
	ds_read_b128 v[228:231], v140 offset:50176
	s_mov_b32 m0, s38
	v_lshl_add_u64 v[248:249], s[36:37], 0, v[132:133]
	global_load_lds_dwordx4 v[248:249], off
	v_lshl_add_u64 v[248:249], s[36:37], 0, v[130:131]
	v_readfirstlane_b32 s36, v153
	s_mov_b32 m0, s36
	s_nop 0
	global_load_lds_dwordx4 v[248:249], off
	s_barrier
	s_waitcnt lgkmcnt(0)
	s_setprio 1
	s_waitcnt lgkmcnt(0)
	v_mfma_f32_16x16x32_bf16 v[62:65], v[194:197], v[178:181], v[62:65]
	v_mfma_f32_16x16x32_bf16 v[58:61], v[194:197], v[186:189], v[58:61]
	v_mfma_f32_16x16x32_bf16 v[54:57], v[202:205], v[178:181], v[54:57]
	v_mfma_f32_16x16x32_bf16 v[50:53], v[202:205], v[186:189], v[50:53]
	v_mfma_f32_16x16x32_bf16 v[46:49], v[212:215], v[178:181], v[46:49]
	v_mfma_f32_16x16x32_bf16 v[42:45], v[212:215], v[186:189], v[42:45]
	v_mfma_f32_16x16x32_bf16 v[38:41], v[224:227], v[178:181], v[38:41]
	v_mfma_f32_16x16x32_bf16 v[34:37], v[224:227], v[186:189], v[34:37]
	v_mfma_f32_16x16x32_bf16 v[62:65], v[198:201], v[182:185], v[62:65]
	v_mfma_f32_16x16x32_bf16 v[58:61], v[198:201], v[190:193], v[58:61]
	v_mfma_f32_16x16x32_bf16 v[54:57], v[206:209], v[182:185], v[54:57]
	v_mfma_f32_16x16x32_bf16 v[50:53], v[206:209], v[190:193], v[50:53]
	v_mfma_f32_16x16x32_bf16 v[46:49], v[216:219], v[182:185], v[46:49]
	v_mfma_f32_16x16x32_bf16 v[42:45], v[216:219], v[190:193], v[42:45]
	v_mfma_f32_16x16x32_bf16 v[38:41], v[228:231], v[182:185], v[38:41]
	v_mfma_f32_16x16x32_bf16 v[34:37], v[228:231], v[190:193], v[34:37]
	s_setprio 0
	s_barrier
	s_add_u32 s36, s42, 0x180
	s_addc_u32 s37, s43, 0
	v_readfirstlane_b32 s38, v154
	s_mov_b32 m0, s38
	v_lshl_add_u64 v[178:179], s[36:37], 0, v[132:133]
	global_load_lds_dwordx4 v[178:179], off
	v_lshl_add_u64 v[178:179], s[36:37], 0, v[130:131]
	v_readfirstlane_b32 s36, v155
	s_mov_b32 m0, s36
	s_nop 0
	global_load_lds_dwordx4 v[178:179], off
	s_waitcnt vmcnt(6)
	s_barrier
	s_setprio 1
	v_mfma_f32_16x16x32_bf16 v[30:33], v[194:197], v[232:235], v[30:33]
	v_mfma_f32_16x16x32_bf16 v[26:29], v[194:197], v[240:243], v[26:29]
	v_mfma_f32_16x16x32_bf16 v[22:25], v[202:205], v[232:235], v[22:25]
	v_mfma_f32_16x16x32_bf16 v[18:21], v[202:205], v[240:243], v[18:21]
	v_mfma_f32_16x16x32_bf16 v[14:17], v[212:215], v[232:235], v[14:17]
	v_mfma_f32_16x16x32_bf16 v[10:13], v[212:215], v[240:243], v[10:13]
	v_mfma_f32_16x16x32_bf16 v[6:9], v[224:227], v[232:235], v[6:9]
	v_mfma_f32_16x16x32_bf16 v[2:5], v[224:227], v[240:243], v[2:5]
	v_mfma_f32_16x16x32_bf16 v[30:33], v[198:201], v[236:239], v[30:33]
	v_mfma_f32_16x16x32_bf16 v[26:29], v[198:201], v[244:247], v[26:29]
	v_mfma_f32_16x16x32_bf16 v[22:25], v[206:209], v[236:239], v[22:25]
	v_mfma_f32_16x16x32_bf16 v[18:21], v[206:209], v[244:247], v[18:21]
	v_mfma_f32_16x16x32_bf16 v[14:17], v[216:219], v[236:239], v[14:17]
	v_mfma_f32_16x16x32_bf16 v[10:13], v[216:219], v[244:247], v[10:13]
	v_mfma_f32_16x16x32_bf16 v[6:9], v[228:231], v[236:239], v[6:9]
	v_mfma_f32_16x16x32_bf16 v[2:5], v[228:231], v[244:247], v[2:5]
	s_setprio 0
	s_add_i32 s35, s35, 2
	s_add_u32 s16, s16, 0x100
	s_addc_u32 s17, s17, 0
	s_cmp_lt_u32 s35, 12
	s_barrier
	s_cbranch_scc1 .LBB0_1871
	s_add_u32 s0, s14, 0x780
	s_addc_u32 s1, s15, 0
	ds_read_b128 v[146:149], v160
	ds_read_b128 v[150:153], v161
	ds_read_b128 v[154:157], v162
	ds_read_b128 v[158:161], v163
	ds_read_b128 v[178:181], v139
	ds_read_b128 v[182:185], v139 offset:1024
	ds_read_b128 v[186:189], v142
	ds_read_b128 v[190:193], v142 offset:1024
	ds_read_b128 v[194:197], v141
	ds_read_b128 v[198:201], v141 offset:1024
	ds_read_b128 v[202:205], v140
	ds_read_b128 v[206:209], v140 offset:1024
	v_readfirstlane_b32 s7, v164
	v_lshl_add_u64 v[132:133], s[0:1], 0, v[132:133]
	s_mov_b32 m0, s7
	v_lshl_add_u64 v[130:131], s[0:1], 0, v[130:131]
	v_readfirstlane_b32 s0, v165
	global_load_lds_dwordx4 v[132:133], off
	s_mov_b32 m0, s0
	s_nop 0
	global_load_lds_dwordx4 v[130:131], off
	s_barrier
	s_waitcnt lgkmcnt(0)
	s_setprio 1
	s_waitcnt lgkmcnt(0)
	v_mfma_f32_16x16x32_bf16 v[126:129], v[178:181], v[146:149], v[126:129]
	v_mfma_f32_16x16x32_bf16 v[122:125], v[178:181], v[154:157], v[122:125]
	v_mfma_f32_16x16x32_bf16 v[110:113], v[194:197], v[146:149], v[110:113]
	v_mfma_f32_16x16x32_bf16 v[106:109], v[194:197], v[154:157], v[106:109]
	v_mfma_f32_16x16x32_bf16 v[126:129], v[182:185], v[150:153], v[126:129]
	v_mfma_f32_16x16x32_bf16 v[122:125], v[182:185], v[158:161], v[122:125]
	v_mfma_f32_16x16x32_bf16 v[118:121], v[186:189], v[146:149], v[118:121]
	v_mfma_f32_16x16x32_bf16 v[114:117], v[186:189], v[154:157], v[114:117]
	v_mfma_f32_16x16x32_bf16 v[110:113], v[198:201], v[150:153], v[110:113]
	v_mfma_f32_16x16x32_bf16 v[106:109], v[198:201], v[158:161], v[106:109]
	v_mfma_f32_16x16x32_bf16 v[102:105], v[202:205], v[146:149], v[102:105]
	v_mfma_f32_16x16x32_bf16 v[98:101], v[202:205], v[154:157], v[98:101]
	v_mfma_f32_16x16x32_bf16 v[130:133], v[190:193], v[150:153], v[118:121]
	v_mfma_f32_16x16x32_bf16 v[162:165], v[190:193], v[158:161], v[114:117]
	v_mfma_f32_16x16x32_bf16 v[212:215], v[206:209], v[150:153], v[102:105]
	v_mfma_f32_16x16x32_bf16 v[216:219], v[206:209], v[158:161], v[98:101]
	s_setprio 0
	s_barrier
	s_nop 0
	ds_read_b128 v[98:101], v166
	ds_read_b128 v[102:105], v167
	ds_read_b128 v[114:117], v168
	ds_read_b128 v[118:121], v169
	s_barrier
	s_waitcnt lgkmcnt(0)
	s_setprio 1
	s_waitcnt lgkmcnt(3)
	v_mfma_f32_16x16x32_bf16 v[94:97], v[178:181], v[98:101], v[94:97]
	s_waitcnt lgkmcnt(1)
	v_mfma_f32_16x16x32_bf16 v[90:93], v[178:181], v[114:117], v[90:93]
	v_mfma_f32_16x16x32_bf16 v[78:81], v[194:197], v[98:101], v[78:81]
	v_mfma_f32_16x16x32_bf16 v[74:77], v[194:197], v[114:117], v[74:77]
	v_mfma_f32_16x16x32_bf16 v[94:97], v[182:185], v[102:105], v[94:97]
	s_waitcnt lgkmcnt(0)
	v_mfma_f32_16x16x32_bf16 v[90:93], v[182:185], v[118:121], v[90:93]
	v_mfma_f32_16x16x32_bf16 v[86:89], v[186:189], v[98:101], v[86:89]
	v_mfma_f32_16x16x32_bf16 v[82:85], v[186:189], v[114:117], v[82:85]
	v_mfma_f32_16x16x32_bf16 v[78:81], v[198:201], v[102:105], v[78:81]
	v_mfma_f32_16x16x32_bf16 v[74:77], v[198:201], v[118:121], v[74:77]
	v_mfma_f32_16x16x32_bf16 v[70:73], v[202:205], v[98:101], v[70:73]
	v_mfma_f32_16x16x32_bf16 v[66:69], v[202:205], v[114:117], v[66:69]
	v_mfma_f32_16x16x32_bf16 v[166:169], v[190:193], v[102:105], v[86:89]
	v_mfma_f32_16x16x32_bf16 v[178:181], v[190:193], v[118:121], v[82:85]
	v_mfma_f32_16x16x32_bf16 v[182:185], v[206:209], v[102:105], v[70:73]
	v_mfma_f32_16x16x32_bf16 v[186:189], v[206:209], v[118:121], v[66:69]
	s_setprio 0
	s_barrier
	s_nop 1
	ds_read_b128 v[66:69], v139 offset:16384
	ds_read_b128 v[70:73], v139 offset:17408
	ds_read_b128 v[82:85], v142 offset:16384
	ds_read_b128 v[86:89], v142 offset:17408
	ds_read_b128 v[190:193], v141 offset:16384
	ds_read_b128 v[194:197], v141 offset:17408
	ds_read_b128 v[198:201], v140 offset:16384
	ds_read_b128 v[202:205], v140 offset:17408
	s_waitcnt vmcnt(4)
	s_barrier
	s_waitcnt lgkmcnt(0)
	s_setprio 1
	s_waitcnt lgkmcnt(7)
	v_mfma_f32_16x16x32_bf16 v[62:65], v[66:69], v[146:149], v[62:65]
	v_mfma_f32_16x16x32_bf16 v[58:61], v[66:69], v[154:157], v[58:61]
	s_waitcnt lgkmcnt(3)
	v_mfma_f32_16x16x32_bf16 v[46:49], v[190:193], v[146:149], v[46:49]
	v_mfma_f32_16x16x32_bf16 v[42:45], v[190:193], v[154:157], v[42:45]
	v_mfma_f32_16x16x32_bf16 v[62:65], v[70:73], v[150:153], v[62:65]
	v_mfma_f32_16x16x32_bf16 v[58:61], v[70:73], v[158:161], v[58:61]
	v_mfma_f32_16x16x32_bf16 v[54:57], v[82:85], v[146:149], v[54:57]
	v_mfma_f32_16x16x32_bf16 v[50:53], v[82:85], v[154:157], v[50:53]
	s_waitcnt lgkmcnt(2)
	v_mfma_f32_16x16x32_bf16 v[46:49], v[194:197], v[150:153], v[46:49]
	v_mfma_f32_16x16x32_bf16 v[42:45], v[194:197], v[158:161], v[42:45]
	s_waitcnt lgkmcnt(1)
	v_mfma_f32_16x16x32_bf16 v[38:41], v[198:201], v[146:149], v[38:41]
	v_mfma_f32_16x16x32_bf16 v[34:37], v[198:201], v[154:157], v[34:37]
	v_mfma_f32_16x16x32_bf16 v[206:209], v[86:89], v[150:153], v[54:57]
	v_mfma_f32_16x16x32_bf16 v[224:227], v[86:89], v[158:161], v[50:53]
	s_waitcnt lgkmcnt(0)
	v_mfma_f32_16x16x32_bf16 v[146:149], v[202:205], v[150:153], v[38:41]
	v_mfma_f32_16x16x32_bf16 v[150:153], v[202:205], v[158:161], v[34:37]
	s_setprio 0
	s_setprio 1
	v_mfma_f32_16x16x32_bf16 v[30:33], v[66:69], v[98:101], v[30:33]
	v_mfma_f32_16x16x32_bf16 v[26:29], v[66:69], v[114:117], v[26:29]
	v_mfma_f32_16x16x32_bf16 v[14:17], v[190:193], v[98:101], v[14:17]
	v_mfma_f32_16x16x32_bf16 v[10:13], v[190:193], v[114:117], v[10:13]
	v_mfma_f32_16x16x32_bf16 v[30:33], v[70:73], v[102:105], v[30:33]
	v_mfma_f32_16x16x32_bf16 v[26:29], v[70:73], v[118:121], v[26:29]
	v_mfma_f32_16x16x32_bf16 v[22:25], v[82:85], v[98:101], v[22:25]
	v_mfma_f32_16x16x32_bf16 v[18:21], v[82:85], v[114:117], v[18:21]
	v_mfma_f32_16x16x32_bf16 v[14:17], v[194:197], v[102:105], v[14:17]
	v_mfma_f32_16x16x32_bf16 v[10:13], v[194:197], v[118:121], v[10:13]
	v_mfma_f32_16x16x32_bf16 v[6:9], v[198:201], v[98:101], v[6:9]
	v_mfma_f32_16x16x32_bf16 v[2:5], v[198:201], v[114:117], v[2:5]
	v_mfma_f32_16x16x32_bf16 v[154:157], v[86:89], v[102:105], v[22:25]
	v_mfma_f32_16x16x32_bf16 v[158:161], v[86:89], v[118:121], v[18:21]
	v_mfma_f32_16x16x32_bf16 v[190:193], v[202:205], v[102:105], v[6:9]
	v_mfma_f32_16x16x32_bf16 v[194:197], v[202:205], v[118:121], v[2:5]
	s_setprio 0
	s_barrier
	s_nop 1
	ds_read_b128 v[2:5], v170
	ds_read_b128 v[6:9], v171
	ds_read_b128 v[198:201], v172
	ds_read_b128 v[170:173], v173
	ds_read_b128 v[18:21], v139 offset:32768
	ds_read_b128 v[22:25], v139 offset:33792
	ds_read_b128 v[34:37], v142 offset:32768
	ds_read_b128 v[38:41], v142 offset:33792
	ds_read_b128 v[50:53], v141 offset:32768
	ds_read_b128 v[54:57], v141 offset:33792
	ds_read_b128 v[202:205], v140 offset:32768
	ds_read_b128 v[228:231], v140 offset:33792
	s_waitcnt vmcnt(2)
	s_barrier
	s_waitcnt lgkmcnt(0)
	s_setprio 1
	s_waitcnt lgkmcnt(7)
	v_mfma_f32_16x16x32_bf16 v[66:69], v[18:21], v[2:5], v[126:129]
	s_waitcnt lgkmcnt(6)
	v_mfma_f32_16x16x32_bf16 v[114:117], v[22:25], v[6:9], v[66:69]
	v_mfma_f32_16x16x32_bf16 v[66:69], v[18:21], v[198:201], v[122:125]
	v_mfma_f32_16x16x32_bf16 v[118:121], v[22:25], v[170:173], v[66:69]
	s_waitcnt lgkmcnt(5)
	v_mfma_f32_16x16x32_bf16 v[66:69], v[34:37], v[2:5], v[130:133]
	s_waitcnt lgkmcnt(4)
	v_mfma_f32_16x16x32_bf16 v[98:101], v[38:41], v[6:9], v[66:69]
	v_mfma_f32_16x16x32_bf16 v[66:69], v[34:37], v[198:201], v[162:165]
	v_mfma_f32_16x16x32_bf16 v[102:105], v[38:41], v[170:173], v[66:69]
	s_waitcnt lgkmcnt(3)
	v_mfma_f32_16x16x32_bf16 v[66:69], v[50:53], v[2:5], v[110:113]
	s_waitcnt lgkmcnt(2)
	v_mfma_f32_16x16x32_bf16 v[82:85], v[54:57], v[6:9], v[66:69]
	v_mfma_f32_16x16x32_bf16 v[66:69], v[50:53], v[198:201], v[106:109]
	v_mfma_f32_16x16x32_bf16 v[86:89], v[54:57], v[170:173], v[66:69]
	s_waitcnt lgkmcnt(1)
	v_mfma_f32_16x16x32_bf16 v[66:69], v[202:205], v[2:5], v[212:215]
	v_mfma_f32_16x16x32_bf16 v[70:73], v[202:205], v[198:201], v[216:219]
	s_waitcnt lgkmcnt(0)
	v_mfma_f32_16x16x32_bf16 v[66:69], v[228:231], v[6:9], v[66:69]
	v_mfma_f32_16x16x32_bf16 v[70:73], v[228:231], v[170:173], v[70:73]
	s_setprio 0
	s_barrier
	ds_read_b128 v[130:133], v174
	ds_read_b128 v[162:165], v175
	ds_read_b128 v[212:215], v176
	ds_read_b128 v[174:177], v177
	s_waitcnt vmcnt(0)
	s_barrier
	s_waitcnt lgkmcnt(0)
	s_setprio 1
	s_waitcnt lgkmcnt(3)
	v_mfma_f32_16x16x32_bf16 v[94:97], v[18:21], v[130:133], v[94:97]
	s_waitcnt lgkmcnt(1)
	v_mfma_f32_16x16x32_bf16 v[18:21], v[18:21], v[212:215], v[90:93]
	s_waitcnt lgkmcnt(0)
	v_mfma_f32_16x16x32_bf16 v[122:125], v[22:25], v[174:177], v[18:21]
	v_mfma_f32_16x16x32_bf16 v[18:21], v[34:37], v[130:133], v[166:169]
	v_mfma_f32_16x16x32_bf16 v[110:113], v[38:41], v[162:165], v[18:21]
	v_mfma_f32_16x16x32_bf16 v[18:21], v[34:37], v[212:215], v[178:181]
	v_mfma_f32_16x16x32_bf16 v[106:109], v[38:41], v[174:177], v[18:21]
	v_mfma_f32_16x16x32_bf16 v[18:21], v[50:53], v[130:133], v[78:81]
	v_mfma_f32_16x16x32_bf16 v[126:129], v[22:25], v[162:165], v[94:97]
	v_mfma_f32_16x16x32_bf16 v[94:97], v[54:57], v[162:165], v[18:21]
	v_mfma_f32_16x16x32_bf16 v[18:21], v[50:53], v[212:215], v[74:77]
	v_mfma_f32_16x16x32_bf16 v[90:93], v[54:57], v[174:177], v[18:21]
	v_mfma_f32_16x16x32_bf16 v[18:21], v[202:205], v[130:133], v[182:185]
	v_mfma_f32_16x16x32_bf16 v[78:81], v[228:231], v[162:165], v[18:21]
	v_mfma_f32_16x16x32_bf16 v[18:21], v[202:205], v[212:215], v[186:189]
	v_mfma_f32_16x16x32_bf16 v[74:77], v[228:231], v[174:177], v[18:21]
	s_setprio 0
	s_barrier
	ds_read_b128 v[166:169], v139 offset:49152
	ds_read_b128 v[178:181], v139 offset:50176
	ds_read_b128 v[182:185], v142 offset:49152
	ds_read_b128 v[186:189], v142 offset:50176
	ds_read_b128 v[202:205], v141 offset:49152
	ds_read_b128 v[216:219], v141 offset:50176
	ds_read_b128 v[228:231], v140 offset:49152
	ds_read_b128 v[138:141], v140 offset:50176
	s_barrier
	s_waitcnt lgkmcnt(0)
	s_setprio 1
	s_waitcnt lgkmcnt(7)
	v_mfma_f32_16x16x32_bf16 v[18:21], v[166:169], v[2:5], v[62:65]
	s_waitcnt lgkmcnt(6)
	v_mfma_f32_16x16x32_bf16 v[50:53], v[178:181], v[6:9], v[18:21]
	v_mfma_f32_16x16x32_bf16 v[18:21], v[166:169], v[198:201], v[58:61]
	v_mfma_f32_16x16x32_bf16 v[54:57], v[178:181], v[170:173], v[18:21]
	s_waitcnt lgkmcnt(5)
	v_mfma_f32_16x16x32_bf16 v[18:21], v[182:185], v[2:5], v[206:209]
	s_waitcnt lgkmcnt(4)
	v_mfma_f32_16x16x32_bf16 v[34:37], v[186:189], v[6:9], v[18:21]
	v_mfma_f32_16x16x32_bf16 v[18:21], v[182:185], v[198:201], v[224:227]
	v_mfma_f32_16x16x32_bf16 v[38:41], v[186:189], v[170:173], v[18:21]
	s_waitcnt lgkmcnt(3)
	v_mfma_f32_16x16x32_bf16 v[18:21], v[202:205], v[2:5], v[46:49]
	s_waitcnt lgkmcnt(1)
	v_mfma_f32_16x16x32_bf16 v[2:5], v[228:231], v[2:5], v[146:149]
	v_mfma_f32_16x16x32_bf16 v[18:21], v[216:219], v[6:9], v[18:21]
	v_mfma_f32_16x16x32_bf16 v[22:25], v[202:205], v[198:201], v[42:45]
	s_waitcnt lgkmcnt(0)
	v_mfma_f32_16x16x32_bf16 v[2:5], v[138:141], v[6:9], v[2:5]
	v_mfma_f32_16x16x32_bf16 v[6:9], v[228:231], v[198:201], v[150:153]
	v_mfma_f32_16x16x32_bf16 v[22:25], v[216:219], v[170:173], v[22:25]
	v_mfma_f32_16x16x32_bf16 v[6:9], v[138:141], v[170:173], v[6:9]
	s_setprio 0
	s_setprio 1
	v_mfma_f32_16x16x32_bf16 v[26:29], v[166:169], v[212:215], v[26:29]
	v_mfma_f32_16x16x32_bf16 v[58:61], v[178:181], v[174:177], v[26:29]
	v_mfma_f32_16x16x32_bf16 v[26:29], v[182:185], v[130:133], v[154:157]
	v_mfma_f32_16x16x32_bf16 v[46:49], v[186:189], v[162:165], v[26:29]
	v_mfma_f32_16x16x32_bf16 v[26:29], v[182:185], v[212:215], v[158:161]
	v_mfma_f32_16x16x32_bf16 v[10:13], v[202:205], v[212:215], v[10:13]
	v_mfma_f32_16x16x32_bf16 v[30:33], v[166:169], v[130:133], v[30:33]
	v_mfma_f32_16x16x32_bf16 v[42:45], v[186:189], v[174:177], v[26:29]
	v_mfma_f32_16x16x32_bf16 v[14:17], v[202:205], v[130:133], v[14:17]
	v_mfma_f32_16x16x32_bf16 v[26:29], v[216:219], v[174:177], v[10:13]
	v_mfma_f32_16x16x32_bf16 v[10:13], v[228:231], v[130:133], v[190:193]
	v_mfma_f32_16x16x32_bf16 v[62:65], v[178:181], v[162:165], v[30:33]
	v_mfma_f32_16x16x32_bf16 v[30:33], v[216:219], v[162:165], v[14:17]
	v_mfma_f32_16x16x32_bf16 v[14:17], v[138:141], v[162:165], v[10:13]
	v_mfma_f32_16x16x32_bf16 v[10:13], v[228:231], v[212:215], v[194:197]
	v_mfma_f32_16x16x32_bf16 v[10:13], v[138:141], v[174:177], v[10:13]
	s_setprio 0
	s_movk_i32 s0, 0x100
	v_cmp_gt_u32_e32 vcc, s0, v134
	s_barrier
	s_and_saveexec_b64 s[0:1], vcc
	s_cbranch_execz .LBB0_1874
	s_barrier
